# norm phases: LDS-staged params + LDS-DMA row prefetch + DPP reduce; de-serialized load ladders in mlstm_out/gla_out; gla gate loop 4-way interleave
# speedup vs baseline: 1.0177x; 1.0177x over previous
; DI int otid(int wv) { int l; asm volatile("v_mbcnt_lo_u32_b32 %0, -1, 0\n\tv_mbcnt_hi_u32_b32 %0, -1, %0" : "=v"(l)); return wv * 64 + l; }
; DI void norm_phase(const KP& P, int layer, int which  , int skip_ctx) {
;     const int tid = otid(P.wv), lane = tid & 63, wave = tid >> 6;
;     const int gw = blockIdx.x * 8 + wave, NGW = gridDim.x * 8;
;     const float* MOD = (const float*)(P.ws + WS_MOD);
;     bf16_t* H = (bf16_t*)(P.ws + WS_H);
;     const float* g = (which == 1 ? P.g_norm1 : P.g_norm2) + layer * D;
;     const int nslab = (layer == 0 && which == 2) ? 4 : (layer == 1 && which == 1) ? 8 : 0;
;     for (int R = gw; R < MROWS; R += NGW) {
;         const int b = R / TT, t = R % TT;
;         if (skip_ctx && t < CTX) continue;
;         const int tl = t < CTX ? 0 : 1 + ((t - CTX) >> 8), rin = t < CTX ? t : ((t - CTX) & 255);
;         const float* src = ((which == 1 && layer == 0) ? xin_tile(P, b, tl) : xst_tile(P, b, tl)) + (size_t)rin * D;
;         const float* mrow = MOD + ((size_t)layer * 9 + (t < CTX ? 8 : b)) * 6144 + (which == 1 ? 0 : 3072);
;     ...
;                 const f32x4 gg = *(const f32x4*)(g + col), sh = *(const f32x4*)(mrow + col), sc = *(const f32x4*)(mrow + 1024 + col);
;                 f32x4 y;
; #pragma unroll
;                 for (int e = 0; e < 4; ++e) y[e] = v[j][e] * rstd * gg[e] * (1.f + sc[e]) + sh[e];
.LBB0_85:
	v_readlane_b32 s78, v251, 61
	v_readlane_b32 s86, v251, 4
	v_readlane_b32 s76, v254, 14
	v_readlane_b32 s77, v254, 15
	v_readlane_b32 s90, v251, 21
	v_readlane_b32 s91, v251, 22
	v_readlane_b32 s74, v251, 5
	v_readlane_b32 s75, v251, 6
	v_readlane_b32 s92, v251, 56
	v_readlane_b32 s93, v251, 57
	v_readlane_b32 s94, v251, 17
	v_readlane_b32 s95, v251, 18
	v_mbcnt_lo_u32_b32 v114, -1, 0
	v_mbcnt_hi_u32_b32 v114, -1, v114
	s_nop 3
	s_lshr_b32 s87, s86, 6
	s_add_i32 s78, s78, s87
	s_lshr_b32 s81, s78, 8
	s_lshl_b32 s81, s81, 1
	s_lshl_b32 s80, s87, 13
	s_add_i32 s80, s80, 0x12000
	s_cmp_eq_u32 s4, 0
	s_cselect_b32 s74, s74, s92
	s_cselect_b32 s75, s75, s93
	s_lshl_b32 s87, s4, 12
	s_add_u32 s94, s94, s87
	s_addc_u32 s95, s95, 0
	s_mul_i32 s87, s4, 0x36000
	s_add_u32 s90, s90, s87
	s_addc_u32 s91, s91, 0
	v_lshlrev_b32_e32 v115, 5, v114
	v_add_u32_e32 v116, 16, v115
	v_add_u32_e32 v117, 0x800, v115
	v_add_u32_e32 v118, 0x810, v115
	v_lshlrev_b32_e32 v121, 4, v114
	v_add_u32_e32 v119, s80, v121
	v_mov_b32_e32 v120, v115
	v_add_u32_e32 v122, s86, v114
	v_and_b32_e32 v122, 0xff, v122
	v_lshlrev_b32_e32 v122, 4, v122
	s_cmpk_ge_u32 s86, 0x100
	s_cbranch_scc1 .Lstage_hi_n1
	global_load_dwordx4 v[152:155], v122, s[94:95]
	s_add_u32 s82, s90, 0x0
	s_addc_u32 s83, s91, 0
	global_load_dwordx4 v[156:159], v122, s[82:83]
	s_add_u32 s82, s90, 0x6000
	s_addc_u32 s83, s91, 0
	global_load_dwordx4 v[160:163], v122, s[82:83]
	s_add_u32 s82, s90, 0xc000
	s_addc_u32 s83, s91, 0
	global_load_dwordx4 v[164:167], v122, s[82:83]
	s_add_u32 s82, s90, 0x12000
	s_addc_u32 s83, s91, 0
	global_load_dwordx4 v[168:171], v122, s[82:83]
	s_add_u32 s82, s90, 0x18000
	s_addc_u32 s83, s91, 0
	global_load_dwordx4 v[172:175], v122, s[82:83]
	s_add_u32 s82, s90, 0x1e000
	s_addc_u32 s83, s91, 0
	global_load_dwordx4 v[176:179], v122, s[82:83]
	s_add_u32 s82, s90, 0x24000
	s_addc_u32 s83, s91, 0
	global_load_dwordx4 v[180:183], v122, s[82:83]
	s_add_u32 s82, s90, 0x2a000
	s_addc_u32 s83, s91, 0
	global_load_dwordx4 v[184:187], v122, s[82:83]
	v_add_u32_e32 v123, 0x8000, v122
	s_waitcnt vmcnt(8)
	ds_write_b128 v122, v[152:155]
	s_waitcnt vmcnt(7)
	ds_write_b128 v122, v[156:159] offset:8192
	s_waitcnt vmcnt(6)
	ds_write_b128 v122, v[160:163] offset:16384
	s_waitcnt vmcnt(5)
	ds_write_b128 v122, v[164:167] offset:24576
	s_waitcnt vmcnt(4)
	ds_write_b128 v123, v[168:171]
	s_waitcnt vmcnt(3)
	ds_write_b128 v123, v[172:175] offset:8192
	s_waitcnt vmcnt(2)
	ds_write_b128 v123, v[176:179] offset:16384
	s_waitcnt vmcnt(1)
	ds_write_b128 v123, v[180:183] offset:24576
	s_waitcnt vmcnt(0)
	ds_write_b128 v123, v[184:187] offset:32768
	s_branch .Lstage_done_n1
.Lstage_hi_n1:
	s_add_u32 s82, s90, 0x1000
	s_addc_u32 s83, s91, 0
	global_load_dwordx4 v[152:155], v122, s[82:83]
	s_add_u32 s82, s90, 0x7000
	s_addc_u32 s83, s91, 0
	global_load_dwordx4 v[156:159], v122, s[82:83]
	s_add_u32 s82, s90, 0xd000
	s_addc_u32 s83, s91, 0
	global_load_dwordx4 v[160:163], v122, s[82:83]
	s_add_u32 s82, s90, 0x13000
	s_addc_u32 s83, s91, 0
	global_load_dwordx4 v[164:167], v122, s[82:83]
	s_add_u32 s82, s90, 0x19000
	s_addc_u32 s83, s91, 0
	global_load_dwordx4 v[168:171], v122, s[82:83]
	s_add_u32 s82, s90, 0x1f000
	s_addc_u32 s83, s91, 0
	global_load_dwordx4 v[172:175], v122, s[82:83]
	s_add_u32 s82, s90, 0x25000
	s_addc_u32 s83, s91, 0
	global_load_dwordx4 v[176:179], v122, s[82:83]
	s_add_u32 s82, s90, 0x2b000
	s_addc_u32 s83, s91, 0
	global_load_dwordx4 v[180:183], v122, s[82:83]
	v_add_u32_e32 v123, 0x8000, v122
	s_waitcnt vmcnt(7)
	v_pk_add_f32 v[152:153], v[152:153], 1.0 op_sel_hi:[1,0]
	v_pk_add_f32 v[154:155], v[154:155], 1.0 op_sel_hi:[1,0]
	ds_write_b128 v122, v[152:155] offset:4096
	s_waitcnt vmcnt(6)
	v_pk_add_f32 v[156:157], v[156:157], 1.0 op_sel_hi:[1,0]
	v_pk_add_f32 v[158:159], v[158:159], 1.0 op_sel_hi:[1,0]
	ds_write_b128 v122, v[156:159] offset:12288
	s_waitcnt vmcnt(5)
	v_pk_add_f32 v[160:161], v[160:161], 1.0 op_sel_hi:[1,0]
	v_pk_add_f32 v[162:163], v[162:163], 1.0 op_sel_hi:[1,0]
	ds_write_b128 v122, v[160:163] offset:20480
	s_waitcnt vmcnt(4)
	v_pk_add_f32 v[164:165], v[164:165], 1.0 op_sel_hi:[1,0]
	v_pk_add_f32 v[166:167], v[166:167], 1.0 op_sel_hi:[1,0]
	ds_write_b128 v122, v[164:167] offset:28672
	s_waitcnt vmcnt(3)
	v_pk_add_f32 v[168:169], v[168:169], 1.0 op_sel_hi:[1,0]
	v_pk_add_f32 v[170:171], v[170:171], 1.0 op_sel_hi:[1,0]
	ds_write_b128 v123, v[168:171] offset:4096
	s_waitcnt vmcnt(2)
	v_pk_add_f32 v[172:173], v[172:173], 1.0 op_sel_hi:[1,0]
	v_pk_add_f32 v[174:175], v[174:175], 1.0 op_sel_hi:[1,0]
	ds_write_b128 v123, v[172:175] offset:12288
	s_waitcnt vmcnt(1)
	v_pk_add_f32 v[176:177], v[176:177], 1.0 op_sel_hi:[1,0]
	v_pk_add_f32 v[178:179], v[178:179], 1.0 op_sel_hi:[1,0]
	ds_write_b128 v123, v[176:179] offset:20480
	s_waitcnt vmcnt(0)
	v_pk_add_f32 v[180:181], v[180:181], 1.0 op_sel_hi:[1,0]
	v_pk_add_f32 v[182:183], v[182:183], 1.0 op_sel_hi:[1,0]
	ds_write_b128 v123, v[180:183] offset:28672
; DI void norm_phase(const KP& P, int layer, int which  , int skip_ctx) {
;     ...
;     for (int R = gw; R < MROWS; R += NGW) {
;         const int b = R / TT, t = R % TT;
;         if (skip_ctx && t < CTX) continue;
;         const int tl = t < CTX ? 0 : 1 + ((t - CTX) >> 8), rin = t < CTX ? t : ((t - CTX) & 255);
;         const float* src = ((which == 1 && layer == 0) ? xin_tile(P, b, tl) : xst_tile(P, b, tl)) + (size_t)rin * D;
;         const float* mrow = MOD + ((size_t)layer * 9 + (t < CTX ? 8 : b)) * 6144 + (which == 1 ? 0 : 3072);
;         f32x4 v[4]; float ss = 0.f;
; #pragma unroll
;         for (int j = 0; j < 4; ++j) v[j] = *(const f32x4*)(src + 8 * lane + 512 * (j >> 1) + 4 * (j & 1));
.Lstage_done_n1:
	s_movk_i32 s79, 0
	s_cmp_ge_u32 s79, s81
	s_cselect_b32 s86, 1, 0
	s_add_i32 s86, s86, s79
	s_lshl_b32 s86, s86, 11
	s_add_i32 s89, s78, s86
	s_lshr_b32 s88, s89, 8
	s_mul_i32 s88, s88, 0xf10
	s_lshr_b32 s88, s88, 16
	s_mul_i32 s87, s88, 0x1100
	s_sub_i32 s87, s89, s87
	s_lshl_b32 s86, s88, 12
	s_add_i32 s87, s87, s86
	s_add_i32 s87, s87, 0xffffff00
	s_lshl_b32 s87, s87, 12
	s_add_u32 s82, s74, s87
	s_addc_u32 s83, s75, 0
	s_mov_b32 m0, s80
	s_nop 0
	global_load_lds_dwordx4 v115, s[82:83]
	s_add_i32 m0, s80, 0x400
	s_nop 0
	global_load_lds_dwordx4 v116, s[82:83]
	s_add_i32 m0, s80, 0x800
	s_nop 0
	global_load_lds_dwordx4 v117, s[82:83]
	s_add_i32 m0, s80, 0xc00
	s_nop 0
	global_load_lds_dwordx4 v118, s[82:83]
	s_movk_i32 s79, 1
	s_cmp_ge_u32 s79, s81
	s_cselect_b32 s86, 1, 0
	s_add_i32 s86, s86, s79
	s_lshl_b32 s86, s86, 11
	s_add_i32 s89, s78, s86
	s_lshr_b32 s88, s89, 8
	s_mul_i32 s88, s88, 0xf10
	s_lshr_b32 s88, s88, 16
	s_mul_i32 s87, s88, 0x1100
	s_sub_i32 s87, s89, s87
	s_lshl_b32 s86, s88, 12
	s_add_i32 s87, s87, s86
	s_add_i32 s87, s87, 0xffffff00
	s_lshl_b32 s87, s87, 12
	s_add_u32 s82, s74, s87
	s_addc_u32 s83, s75, 0
	s_add_i32 m0, s80, 0x1000
	s_nop 0
	global_load_lds_dwordx4 v115, s[82:83]
	s_add_i32 m0, s80, 0x1400
	s_nop 0
	global_load_lds_dwordx4 v116, s[82:83]
	s_add_i32 m0, s80, 0x1800
	s_nop 0
	global_load_lds_dwordx4 v117, s[82:83]
	s_add_i32 m0, s80, 0x1c00
	s_nop 0
	global_load_lds_dwordx4 v118, s[82:83]
	v_writelane_b32 v254, s2, 49
	s_xor_b64 s[0:1], s[2:3], -1
	v_mbcnt_lo_u32_b32 v0, -1, 0
	v_mbcnt_hi_u32_b32 v0, -1, v0
	s_nop 0
	v_writelane_b32 v254, s3, 50
	v_writelane_b32 v254, s0, 51
	s_nop 1
	v_writelane_b32 v254, s1, 52
	v_readlane_b32 s0, v251, 4
	s_nop 1
	v_add_u32_e32 v1, s0, v0
	v_ashrrev_i32_e32 v1, 6, v1
	v_readlane_b32 s0, v251, 61
	s_nop 1
	v_add_u32_e32 v16, s0, v1
	v_lshrrev_b32_e32 v1, 8, v16
	v_lshl_add_u32 v16, v1, 12, v16
	s_mov_b32 s0, 0x8800
	v_cmp_gt_i32_e32 vcc, s0, v16
	s_mov_b32 s0, s4
	v_writelane_b32 v254, s0, 53
	s_nop 1
	v_writelane_b32 v254, s1, 54
	s_mul_i32 s0, s4, 9
	v_writelane_b32 v254, s0, 55
	s_and_saveexec_b64 s[2:3], vcc
	s_cbranch_execz .LBB0_94
	v_xor_b32_e32 v1, 1, v190
	v_cmp_lt_i32_e32 vcc, v1, v191
	v_readlane_b32 s0, v251, 59
	v_readlane_b32 s1, v251, 60
	v_cndmask_b32_e32 v1, v190, v1, vcc
	v_lshlrev_b32_e32 v28, 2, v1
	v_xor_b32_e32 v1, 2, v190
	v_cmp_lt_i32_e32 vcc, v1, v191
	s_mov_b32 s5, s1
	v_readlane_b32 s0, v254, 53
	v_cndmask_b32_e32 v1, v190, v1, vcc
	v_lshlrev_b32_e32 v29, 2, v1
	v_xor_b32_e32 v1, 4, v190
	v_readlane_b32 s1, v254, 54
	v_cmp_lt_i32_e32 vcc, v1, v191
	s_mov_b32 s1, s5
	s_lshl_b32 s4, s0, 10
	v_cndmask_b32_e32 v1, v190, v1, vcc
	v_writelane_b32 v251, s0, 59
	v_lshlrev_b32_e32 v30, 2, v1
	v_xor_b32_e32 v1, 8, v190
	v_writelane_b32 v251, s1, 60
	v_cmp_lt_i32_e32 vcc, v1, v191
	s_lshl_b64 s[0:1], s[4:5], 2
	v_readlane_b32 s4, v251, 5
	v_cndmask_b32_e32 v1, v190, v1, vcc
	v_cmp_lt_i32_e32 vcc, v201, v191
	v_readlane_b32 s5, v251, 6
	v_lshlrev_b32_e32 v0, 3, v0
	v_lshlrev_b32_e32 v31, 2, v1
	v_cndmask_b32_e32 v1, v190, v201, vcc
	v_readlane_b32 s16, v251, 17
	v_and_b32_e32 v0, 0x1f8, v0
	v_readlane_b32 s4, v254, 14
	v_lshlrev_b32_e32 v32, 2, v1
	v_xor_b32_e32 v1, 32, v190
	v_readlane_b32 s17, v251, 18
	s_add_u32 s0, s16, s0
	v_lshlrev_b32_e32 v112, 1, v0
	v_readlane_b32 s5, v254, 15
	v_cmp_lt_i32_e32 vcc, v1, v191
	v_readlane_b32 s6, v251, 7
	v_readlane_b32 s7, v251, 8
	s_addc_u32 s1, s17, s1
	v_lshl_add_u64 v[18:19], s[4:5], 0, v[112:113]
	v_lshlrev_b32_e32 v112, 2, v0
	v_or_b32_e32 v2, 0x200, v0
	v_cndmask_b32_e32 v1, v190, v1, vcc
	v_lshl_add_u64 v[20:21], s[0:1], 0, v[112:113]
	v_lshlrev_b32_e32 v33, 2, v1
	s_mov_b64 s[6:7], 0
	v_lshlrev_b32_e32 v112, 2, v0
	v_lshlrev_b32_e32 v22, 2, v2
	v_readlane_b32 s8, v251, 9
	v_readlane_b32 s9, v251, 10
	v_readlane_b32 s10, v251, 11
	v_readlane_b32 s11, v251, 12
	v_readlane_b32 s12, v251, 13
	v_readlane_b32 s13, v251, 14
	v_readlane_b32 s14, v251, 15
	v_readlane_b32 s15, v251, 16
	v_readlane_b32 s18, v251, 19
	v_readlane_b32 s19, v251, 20
	s_branch .LBB0_88
; DI unsigned pk2(float lo, float hi) { f32x2 v = {lo, hi}; bf2_t r = __builtin_convertvector(v, bf2_t); return __builtin_bit_cast(unsigned, r); }
; DI void norm_phase(const KP& P, int layer, int which  , int skip_ctx) {
;     ...
;     for (int R = gw; R < MROWS; R += NGW) {
;         const int b = R / TT, t = R % TT;
;         if (skip_ctx && t < CTX) continue;
;         const int tl = t < CTX ? 0 : 1 + ((t - CTX) >> 8), rin = t < CTX ? t : ((t - CTX) & 255);
;         const float* src = ((which == 1 && layer == 0) ? xin_tile(P, b, tl) : xst_tile(P, b, tl)) + (size_t)rin * D;
;         const float* mrow = MOD + ((size_t)layer * 9 + (t < CTX ? 8 : b)) * 6144 + (which == 1 ? 0 : 3072);
;         f32x4 v[4]; float ss = 0.f;
; #pragma unroll
;         for (int j = 0; j < 4; ++j) v[j] = *(const f32x4*)(src + 8 * lane + 512 * (j >> 1) + 4 * (j & 1));
;         if (nslab && t < CTX) { const float* sl = (const float*)(P.ws + WS_SLAB) + ((size_t)b * CTX + t) * D + 8 * lane;
;             for (int s = 0; s < nslab; ++s)
; #pragma unroll
;                 for (int j = 0; j < 4; ++j) v[j] = v[j] + *(const f32x4*)(sl + (size_t)s * (NB * CTX) * D + 512 * (j >> 1) + 4 * (j & 1));
;             if (which == 2) { float* dst = xst_tile(P, b, 0) + (size_t)rin * D + 8 * lane;
; #pragma unroll
;                 for (int j = 0; j < 4; ++j) *(f32x4*)(dst + 512 * (j >> 1) + 4 * (j & 1)) = v[j]; } }
; #pragma unroll
;         for (int j = 0; j < 4; ++j) { ss += v[j][0] * v[j][0] + v[j][1] * v[j][1] + v[j][2] * v[j][2] + v[j][3] * v[j][3]; }
; #pragma unroll
;         for (int o = 1; o < 64; o <<= 1) ss += __shfl_xor(ss, o);
;         const float rstd = rsqrtf(ss * (1.f / D) + EPS);
; #pragma unroll
;         for (int jj = 0; jj < 2; ++jj) { u32x4 o;
; #pragma unroll
;             for (int hh = 0; hh < 2; ++hh) { const int j = 2 * jj + hh, col = 8 * lane + 512 * jj + 4 * hh;
;                 const f32x4 gg = *(const f32x4*)(g + col), sh = *(const f32x4*)(mrow + col), sc = *(const f32x4*)(mrow + 1024 + col);
;                 f32x4 y;
; #pragma unroll
;                 for (int e = 0; e < 4; ++e) y[e] = v[j][e] * rstd * gg[e] * (1.f + sc[e]) + sh[e];
;                 if (hh == 0) { o.x = pk2(y[0], y[1]); o.y = pk2(y[2], y[3]); } else { o.z = pk2(y[0], y[1]); o.w = pk2(y[2], y[3]); } }
;             *(u32x4*)(H + (size_t)R * D + 8 * lane + 512 * jj) = o; }
;     }
.LBB0_87:
	s_or_b64 exec, exec, s[4:5]
	v_cndmask_b32_e64 v17, v24, 8, s[0:1]
	v_readlane_b32 s0, v254, 55
	s_waitcnt vmcnt(0)
	v_pk_mul_f32 v[66:67], v[12:13], v[12:13]
	v_pk_mul_f32 v[70:71], v[8:9], v[8:9]
	v_add_u32_e32 v17, s0, v17
	v_readlane_b32 s0, v251, 21
	v_mul_hi_i32_i24_e32 v25, 0x6000, v17
	v_mul_i32_i24_e32 v24, 0x6000, v17
	v_readlane_b32 s1, v251, 22
	v_pk_mul_f32 v[62:63], v[14:15], v[14:15]
	v_pk_mul_f32 v[64:65], v[10:11], v[10:11]
	v_lshl_add_u64 v[46:47], s[0:1], 0, v[24:25]
	s_mov_b64 s[0:1], 0x1000
	v_lshl_add_u64 v[68:69], v[46:47], 0, s[0:1]
	v_lshl_add_u64 v[42:43], v[68:69], 0, v[112:113]
	global_load_dwordx4 v[24:27], v[20:21], off offset:16
	global_load_dwordx4 v[34:37], v[20:21], off
	global_load_dwordx4 v[38:41], v[42:43], off offset:16
	s_nop 0
	global_load_dwordx4 v[42:45], v[42:43], off
	v_lshl_add_u64 v[72:73], v[46:47], 0, v[112:113]
	global_load_dwordx4 v[46:49], v[72:73], off offset:16
	global_load_dwordx4 v[50:53], v[72:73], off
	v_mov_b32_e32 v74, v66
	v_mov_b32_e32 v75, v70
	v_mov_b32_e32 v70, v67
	v_pk_add_f32 v[66:67], v[74:75], v[70:71]
	v_mov_b32_e32 v70, v62
	v_mov_b32_e32 v71, v64
	s_waitcnt vmcnt(7)
	v_pk_mul_f32 v[58:59], v[0:1], v[0:1]
	s_waitcnt vmcnt(6)
	v_pk_mul_f32 v[60:61], v[4:5], v[4:5]
	v_pk_add_f32 v[66:67], v[70:71], v[66:67]
	v_mov_b32_e32 v64, v63
	v_pk_mul_f32 v[54:55], v[2:3], v[2:3]
	v_pk_mul_f32 v[56:57], v[6:7], v[6:7]
	v_pk_add_f32 v[62:63], v[64:65], v[66:67]
	v_mov_b32_e32 v64, v58
	v_mov_b32_e32 v65, v60
	v_mov_b32_e32 v60, v59
	v_pk_add_f32 v[58:59], v[64:65], v[60:61]
	v_mov_b32_e32 v60, v54
	v_mov_b32_e32 v61, v56
	v_pk_add_f32 v[58:59], v[60:61], v[58:59]
	v_mov_b32_e32 v56, v55
	v_pk_add_f32 v[54:55], v[56:57], v[58:59]
	v_add_f32_e32 v17, v62, v63
	v_add_f32_e32 v17, v55, v17
	v_add_f32_e32 v17, v54, v17
	ds_bpermute_b32 v23, v28, v17
	s_mov_b32 s0, 0x800000
	s_waitcnt lgkmcnt(0)
	v_add_f32_e32 v17, v17, v23
	ds_bpermute_b32 v23, v29, v17
	s_waitcnt lgkmcnt(0)
	v_add_f32_e32 v17, v17, v23
	ds_bpermute_b32 v23, v30, v17
	s_waitcnt lgkmcnt(0)
	v_add_f32_e32 v17, v17, v23
	ds_bpermute_b32 v23, v31, v17
	s_waitcnt lgkmcnt(0)
	v_add_f32_e32 v17, v17, v23
	ds_bpermute_b32 v23, v32, v17
	s_waitcnt lgkmcnt(0)
	v_add_f32_e32 v54, v17, v23
	ds_bpermute_b32 v55, v33, v54
	v_ashrrev_i32_e32 v17, 31, v16
	v_mov_b32_e32 v23, v113
	v_lshl_add_u64 v[56:57], v[68:69], 0, v[22:23]
	s_waitcnt lgkmcnt(0)
	v_add_f32_e32 v54, v54, v55
	v_fmamk_f32 v54, v54, 0x3a800000, v144
	v_mul_f32_e32 v55, 0x4b800000, v54
	v_cmp_gt_f32_e32 vcc, s0, v54
	s_mov_b32 s0, 0x8800
	s_nop 0
	v_cndmask_b32_e32 v54, v54, v55, vcc
	v_rsq_f32_e32 v58, v54
	v_lshlrev_b64 v[54:55], 11, v[16:17]
	v_lshl_add_u64 v[54:55], v[18:19], 0, v[54:55]
	v_add_u32_e32 v16, s0, v16
	v_mul_f32_e32 v17, 0x45800000, v58
	v_cndmask_b32_e32 v58, v58, v17, vcc
	v_pk_mul_f32 v[12:13], v[12:13], v[58:59] op_sel_hi:[1,0]
	v_pk_mul_f32 v[14:15], v[14:15], v[58:59] op_sel_hi:[1,0]
	v_pk_mul_f32 v[8:9], v[8:9], v[58:59] op_sel_hi:[1,0]
	v_pk_mul_f32 v[10:11], v[10:11], v[58:59] op_sel_hi:[1,0]
	s_waitcnt vmcnt(4)
	v_pk_mul_f32 v[12:13], v[34:35], v[12:13]
	v_pk_mul_f32 v[14:15], v[36:37], v[14:15]
	v_pk_mul_f32 v[8:9], v[24:25], v[8:9]
	v_pk_mul_f32 v[10:11], v[26:27], v[10:11]
	s_waitcnt vmcnt(2)
	v_pk_add_f32 v[24:25], v[42:43], 1.0 op_sel_hi:[1,0]
	v_pk_add_f32 v[26:27], v[44:45], 1.0 op_sel_hi:[1,0]
	v_pk_add_f32 v[34:35], v[38:39], 1.0 op_sel_hi:[1,0]
	v_pk_add_f32 v[36:37], v[40:41], 1.0 op_sel_hi:[1,0]
	s_waitcnt vmcnt(0)
	v_pk_fma_f32 v[12:13], v[24:25], v[12:13], v[50:51]
	v_pk_fma_f32 v[14:15], v[26:27], v[14:15], v[52:53]
	v_pk_fma_f32 v[24:25], v[34:35], v[8:9], v[46:47]
	v_pk_fma_f32 v[26:27], v[36:37], v[10:11], v[48:49]
	v_cvt_pk_bf16_f32 v8, v12, v13
	v_cvt_pk_bf16_f32 v9, v14, v15
	v_cvt_pk_bf16_f32 v10, v24, v25
	v_cvt_pk_bf16_f32 v11, v26, v27
	global_store_dwordx4 v[54:55], v[8:11], off
	global_load_dwordx4 v[8:11], v[56:57], off
	s_nop 0
	global_load_dwordx4 v[12:15], v[20:21], off offset:2048
	global_load_dwordx4 v[24:27], v[56:57], off offset:16
	global_load_dwordx4 v[34:37], v[20:21], off offset:2064
	global_load_dwordx4 v[38:41], v[72:73], off offset:2048
	global_load_dwordx4 v[42:45], v[72:73], off offset:2064
	v_pk_mul_f32 v[4:5], v[4:5], v[58:59] op_sel_hi:[1,0]
	v_pk_mul_f32 v[6:7], v[6:7], v[58:59] op_sel_hi:[1,0]
	v_pk_mul_f32 v[0:1], v[0:1], v[58:59] op_sel_hi:[1,0]
	v_pk_mul_f32 v[2:3], v[2:3], v[58:59] op_sel_hi:[1,0]
	s_mov_b32 s0, 0x87ff
	v_cmp_lt_i32_e32 vcc, s0, v16
	s_or_b64 s[6:7], vcc, s[6:7]
	s_waitcnt vmcnt(5)
	v_pk_add_f32 v[8:9], v[8:9], 1.0 op_sel_hi:[1,0]
	s_waitcnt vmcnt(4)
	v_pk_mul_f32 v[4:5], v[12:13], v[4:5]
	v_pk_add_f32 v[10:11], v[10:11], 1.0 op_sel_hi:[1,0]
	v_pk_mul_f32 v[6:7], v[14:15], v[6:7]
	s_waitcnt vmcnt(3)
	v_pk_add_f32 v[12:13], v[24:25], 1.0 op_sel_hi:[1,0]
	s_waitcnt vmcnt(2)
	v_pk_mul_f32 v[0:1], v[34:35], v[0:1]
	v_pk_add_f32 v[14:15], v[26:27], 1.0 op_sel_hi:[1,0]
	v_pk_mul_f32 v[2:3], v[36:37], v[2:3]
	s_waitcnt vmcnt(1)
	v_pk_fma_f32 v[4:5], v[8:9], v[4:5], v[38:39]
	v_pk_fma_f32 v[6:7], v[10:11], v[6:7], v[40:41]
	s_waitcnt vmcnt(0)
	v_pk_fma_f32 v[8:9], v[12:13], v[0:1], v[42:43]
	v_pk_fma_f32 v[10:11], v[14:15], v[2:3], v[44:45]
	v_cvt_pk_bf16_f32 v0, v4, v5
	v_cvt_pk_bf16_f32 v1, v6, v7
	v_cvt_pk_bf16_f32 v2, v8, v9
	v_cvt_pk_bf16_f32 v3, v10, v11
	global_store_dwordx4 v[54:55], v[0:3], off offset:1024
	s_andn2_b64 exec, exec, s[6:7]
	s_cbranch_execz .LBB0_94

; DI void norm_phase(const KP& P, int layer, int which  , int skip_ctx) {
;     ...
;     for (int R = gw; R < MROWS; R += NGW) {
;         const int b = R / TT, t = R % TT;
;         if (skip_ctx && t < CTX) continue;
;         const int tl = t < CTX ? 0 : 1 + ((t - CTX) >> 8), rin = t < CTX ? t : ((t - CTX) & 255);
;         const float* src = ((which == 1 && layer == 0) ? xin_tile(P, b, tl) : xst_tile(P, b, tl)) + (size_t)rin * D;
;         const float* mrow = MOD + ((size_t)layer * 9 + (t < CTX ? 8 : b)) * 6144 + (which == 1 ? 0 : 3072);
;         f32x4 v[4]; float ss = 0.f;
; #pragma unroll
;         for (int j = 0; j < 4; ++j) v[j] = *(const f32x4*)(src + 8 * lane + 512 * (j >> 1) + 4 * (j & 1));
.LBB0_94:
	s_or_b64 exec, exec, s[2:3]
	s_waitcnt vmcnt(0) lgkmcnt(0)
	s_barrier
	v_mov_b32_e32 v143, 0x358637bd
	s_movk_i32 s79, 0
.Lrow_n1:
	s_cmp_eq_u32 s79, 15
	s_cbranch_scc1 .Lw0_n1
	s_waitcnt vmcnt(8)
	s_branch .Lgo_n1

; DI unsigned pk2(float lo, float hi) { f32x2 v = {lo, hi}; bf2_t r = __builtin_convertvector(v, bf2_t); return __builtin_bit_cast(unsigned, r); }
; DI void norm_phase(const KP& P, int layer, int which  , int skip_ctx) {
;     ...
;         f32x4 v[4]; float ss = 0.f;
; #pragma unroll
;         for (int j = 0; j < 4; ++j) v[j] = *(const f32x4*)(src + 8 * lane + 512 * (j >> 1) + 4 * (j & 1));
;         if (nslab && t < CTX) { const float* sl = (const float*)(P.ws + WS_SLAB) + ((size_t)b * CTX + t) * D + 8 * lane;
;             for (int s = 0; s < nslab; ++s)
; #pragma unroll
;                 for (int j = 0; j < 4; ++j) v[j] = v[j] + *(const f32x4*)(sl + (size_t)s * (NB * CTX) * D + 512 * (j >> 1) + 4 * (j & 1));
;             if (which == 2) { float* dst = xst_tile(P, b, 0) + (size_t)rin * D + 8 * lane;
; #pragma unroll
;                 for (int j = 0; j < 4; ++j) *(f32x4*)(dst + 512 * (j >> 1) + 4 * (j & 1)) = v[j]; } }
; #pragma unroll
;         for (int j = 0; j < 4; ++j) { ss += v[j][0] * v[j][0] + v[j][1] * v[j][1] + v[j][2] * v[j][2] + v[j][3] * v[j][3]; }
; #pragma unroll
;         for (int o = 1; o < 64; o <<= 1) ss += __shfl_xor(ss, o);
;         const float rstd = rsqrtf(ss * (1.f / D) + EPS);
; #pragma unroll
;         for (int jj = 0; jj < 2; ++jj) { u32x4 o;
; #pragma unroll
;             for (int hh = 0; hh < 2; ++hh) { const int j = 2 * jj + hh, col = 8 * lane + 512 * jj + 4 * hh;
;                 const f32x4 gg = *(const f32x4*)(g + col), sh = *(const f32x4*)(mrow + col), sc = *(const f32x4*)(mrow + 1024 + col);
;                 f32x4 y;
; #pragma unroll
;                 for (int e = 0; e < 4; ++e) y[e] = v[j][e] * rstd * gg[e] * (1.f + sc[e]) + sh[e];
;                 if (hh == 0) { o.x = pk2(y[0], y[1]); o.y = pk2(y[2], y[3]); } else { o.z = pk2(y[0], y[1]); o.w = pk2(y[2], y[3]); } }
;             *(u32x4*)(H + (size_t)R * D + 8 * lane + 512 * jj) = o; }
;     }
; DI void xcd_barrier(const XcdBarrier& b, int wv) {
;     asm volatile("s_waitcnt vmcnt(0)" ::: "memory");
;     __syncthreads();
;     if (otid(wv) == 0) {
;         unsigned* bar = b.bar;
;         __builtin_amdgcn_s_waitcnt(0);
;         unsigned nloc = b.st[0], nx = b.st[1];
;         if (nloc == 0u) { xcd_barrier_complete(bar, b.x, nloc, nx); b.st[0] = nloc; b.st[1] = nx; }
.Lgo_n1:
	ds_read_b128 v[124:127], v119
	ds_read_b128 v[128:131], v119 offset:1024
	ds_read_b128 v[132:135], v119 offset:2048
	ds_read_b128 v[136:139], v119 offset:3072
	s_cmp_ge_u32 s79, s81
	s_cselect_b32 s86, 1, 0
	s_add_i32 s86, s86, s79
	s_lshl_b32 s86, s86, 11
	s_add_i32 s89, s78, s86
	s_lshr_b32 s88, s89, 8
	s_mul_i32 s88, s88, 0xf10
	s_lshr_b32 s88, s88, 16
	s_lshl_b32 s86, s88, 13
	s_add_i32 s86, s86, 0x1000
	v_add_u32_e32 v122, s86, v120
	ds_read_b128 v[152:155], v120
	ds_read_b128 v[156:159], v120 offset:16
	ds_read_b128 v[160:163], v120 offset:2048
	ds_read_b128 v[164:167], v120 offset:2064
	ds_read_b128 v[168:171], v122
	ds_read_b128 v[172:175], v122 offset:16
	ds_read_b128 v[176:179], v122 offset:2048
	ds_read_b128 v[180:183], v122 offset:2064
	s_lshl_b32 s86, s89, 11
	s_add_u32 s84, s76, s86
	s_addc_u32 s85, s77, 0
	s_waitcnt lgkmcnt(8)
	ds_read_b128 v[204:207], v122 offset:4096
	ds_read_b128 v[208:211], v122 offset:4112
	ds_read_b128 v[212:215], v122 offset:6144
	ds_read_b128 v[216:219], v122 offset:6160
	s_cmp_gt_u32 s79, 13
	s_cbranch_scc1 .Lnodma_n1
	s_add_i32 s79, s79, 2
	s_cmp_ge_u32 s79, s81
	s_cselect_b32 s86, 1, 0
	s_add_i32 s86, s86, s79
	s_lshl_b32 s86, s86, 11
	s_add_i32 s89, s78, s86
	s_lshr_b32 s88, s89, 8
	s_mul_i32 s88, s88, 0xf10
	s_lshr_b32 s88, s88, 16
	s_mul_i32 s87, s88, 0x1100
	s_sub_i32 s87, s89, s87
	s_lshl_b32 s86, s88, 12
	s_add_i32 s87, s87, s86
	s_add_i32 s87, s87, 0xffffff00
	s_lshl_b32 s87, s87, 12
	s_add_u32 s82, s74, s87
	s_addc_u32 s83, s75, 0
	s_sub_i32 s79, s79, 2
	s_mov_b32 m0, s80
	s_nop 0
	global_load_lds_dwordx4 v115, s[82:83]
	s_add_i32 m0, s80, 0x400
	s_nop 0
	global_load_lds_dwordx4 v116, s[82:83]
	s_add_i32 m0, s80, 0x800
	s_nop 0
	global_load_lds_dwordx4 v117, s[82:83]
	s_add_i32 m0, s80, 0xc00
	s_nop 0
	global_load_lds_dwordx4 v118, s[82:83]
.Lnodma_n1:
	v_mul_f32_e32 v140, v124, v124
	v_mul_f32_e32 v141, v125, v125
	v_add_f32_e32 v140, v140, v141
	v_mul_f32_e32 v141, v126, v126
	v_add_f32_e32 v140, v141, v140
	v_mul_f32_e32 v141, v127, v127
	v_add_f32_e32 v140, v141, v140
	v_mul_f32_e32 v228, v128, v128
	v_mul_f32_e32 v141, v129, v129
	v_add_f32_e32 v228, v228, v141
	v_mul_f32_e32 v141, v130, v130
	v_add_f32_e32 v228, v141, v228
	v_mul_f32_e32 v141, v131, v131
	v_add_f32_e32 v228, v141, v228
	v_mul_f32_e32 v229, v132, v132
	v_mul_f32_e32 v141, v133, v133
	v_add_f32_e32 v229, v229, v141
	v_mul_f32_e32 v141, v134, v134
	v_add_f32_e32 v229, v141, v229
	v_mul_f32_e32 v141, v135, v135
	v_add_f32_e32 v229, v141, v229
	v_mul_f32_e32 v230, v136, v136
	v_mul_f32_e32 v141, v137, v137
	v_add_f32_e32 v230, v230, v141
	v_mul_f32_e32 v141, v138, v138
	v_add_f32_e32 v230, v141, v230
	v_mul_f32_e32 v141, v139, v139
	v_add_f32_e32 v230, v141, v230
	v_add_f32_e32 v140, v140, v228
	v_add_f32_e32 v140, v229, v140
	v_add_f32_e32 v140, v230, v140
	s_nop 1
	v_add_f32_dpp v141, v140, v140 quad_perm:[1,0,3,2] row_mask:0xf bank_mask:0xf
	s_nop 1
	v_add_f32_dpp v140, v141, v141 quad_perm:[2,3,0,1] row_mask:0xf bank_mask:0xf
	s_nop 1
	v_add_f32_dpp v141, v140, v140 row_half_mirror row_mask:0xf bank_mask:0xf
	s_nop 1
	v_add_f32_dpp v140, v141, v141 row_mirror row_mask:0xf bank_mask:0xf
	s_nop 1
	v_readlane_b32 s92, v140, 0
	v_readlane_b32 s93, v140, 16
	v_readlane_b32 s94, v140, 32
	v_readlane_b32 s95, v140, 48
	s_nop 1
	v_mov_b32_e32 v141, s93
	v_mov_b32_e32 v140, s95
	v_add_f32_e32 v141, s92, v141
	v_add_f32_e32 v140, s94, v140
	v_add_f32_e32 v140, v141, v140
	v_fmamk_f32 v140, v140, 0x3a800000, v143
	s_mov_b32 s86, 0x800000
	v_mul_f32_e32 v141, 0x4b800000, v140
	v_cmp_gt_f32_e32 vcc, s86, v140
	s_nop 1
	v_cndmask_b32_e32 v140, v140, v141, vcc
	v_rsq_f32_e32 v142, v140
	s_nop 0
	v_mul_f32_e32 v141, 0x45800000, v142
	v_cndmask_b32_e32 v142, v142, v141, vcc
	s_waitcnt lgkmcnt(0)
	v_pk_mul_f32 v[124:125], v[124:125], v[142:143] op_sel_hi:[1,0]
	v_pk_mul_f32 v[126:127], v[126:127], v[142:143] op_sel_hi:[1,0]
	v_pk_mul_f32 v[124:125], v[152:153], v[124:125]
	v_pk_mul_f32 v[126:127], v[154:155], v[126:127]
	v_pk_fma_f32 v[124:125], v[168:169], v[124:125], v[204:205]
	v_pk_fma_f32 v[126:127], v[170:171], v[126:127], v[206:207]
	v_pk_mul_f32 v[128:129], v[128:129], v[142:143] op_sel_hi:[1,0]
	v_pk_mul_f32 v[130:131], v[130:131], v[142:143] op_sel_hi:[1,0]
	v_pk_mul_f32 v[128:129], v[156:157], v[128:129]
	v_pk_mul_f32 v[130:131], v[158:159], v[130:131]
	v_pk_fma_f32 v[128:129], v[172:173], v[128:129], v[208:209]
	v_pk_fma_f32 v[130:131], v[174:175], v[130:131], v[210:211]
	v_pk_mul_f32 v[132:133], v[132:133], v[142:143] op_sel_hi:[1,0]
	v_pk_mul_f32 v[134:135], v[134:135], v[142:143] op_sel_hi:[1,0]
	v_pk_mul_f32 v[132:133], v[160:161], v[132:133]
	v_pk_mul_f32 v[134:135], v[162:163], v[134:135]
	v_pk_fma_f32 v[132:133], v[176:177], v[132:133], v[212:213]
	v_pk_fma_f32 v[134:135], v[178:179], v[134:135], v[214:215]
	v_pk_mul_f32 v[136:137], v[136:137], v[142:143] op_sel_hi:[1,0]
	v_pk_mul_f32 v[138:139], v[138:139], v[142:143] op_sel_hi:[1,0]
	v_pk_mul_f32 v[136:137], v[164:165], v[136:137]
	v_pk_mul_f32 v[138:139], v[166:167], v[138:139]
	v_pk_fma_f32 v[136:137], v[180:181], v[136:137], v[216:217]
	v_pk_fma_f32 v[138:139], v[182:183], v[138:139], v[218:219]
	v_cvt_pk_bf16_f32 v220, v124, v125
	v_cvt_pk_bf16_f32 v221, v126, v127
	v_cvt_pk_bf16_f32 v222, v128, v129
	v_cvt_pk_bf16_f32 v223, v130, v131
	v_cvt_pk_bf16_f32 v224, v132, v133
	v_cvt_pk_bf16_f32 v225, v134, v135
	v_cvt_pk_bf16_f32 v226, v136, v137
	v_cvt_pk_bf16_f32 v227, v138, v139
	global_store_dwordx4 v121, v[220:223], s[84:85]
	global_store_dwordx4 v121, v[224:227], s[84:85] offset:1024
	v_xor_b32_e32 v119, 0x1000, v119
	s_xor_b32 s80, s80, 0x1000
	s_add_i32 s79, s79, 1
	s_cmp_lt_u32 s79, 16
	s_cbranch_scc1 .Lrow_n1
	v_readlane_b32 s0, v254, 43
	v_readlane_b32 s1, v254, 44
	s_xor_b64 s[0:1], s[0:1], -1
	v_writelane_b32 v254, s0, 56
	s_waitcnt vmcnt(0)
	s_barrier
	s_nop 0
	v_writelane_b32 v254, s1, 57
	v_readlane_b32 s0, v252, 1
	v_mbcnt_lo_u32_b32 v0, -1, 0
	v_mbcnt_hi_u32_b32 v0, -1, v0
	s_nop 1
	v_cmp_eq_u32_e32 vcc, s0, v0
	s_and_saveexec_b64 s[0:1], vcc
	s_cbranch_execz .LBB0_146
	v_readlane_b32 s2, v254, 38
	s_waitcnt vmcnt(0) expcnt(0) lgkmcnt(0)
	s_nop 0
	v_mov_b32_e32 v0, s2
	ds_read_b32 v2, v0
	v_readlane_b32 s2, v254, 39
	s_waitcnt lgkmcnt(0)
	v_cmp_ne_u32_e32 vcc, 0, v2
	v_mov_b32_e32 v0, s2
	ds_read_b32 v0, v0
	s_cbranch_vccnz .LBB0_110
	s_mov_b32 s8, 1
	s_branch .LBB0_98

; #define LAS __attribute__((address_space(3)))
; DI void gla_prep_item(const KP& P, int layer, int b, int tb, LAS unsigned char* lds) {
;     ...
;     { u32x4 kv[2], vv[4];
; #pragma unroll
;       for (int i = 0; i < 2; ++i) { const int q = tid + 512 * i, row = q >> 4, ch = q & 15; kv[i] = ldg16(Z + (R0 + row) * ZW + C_KC + ch * 8); }
; #pragma unroll
;       for (int i = 0; i < 4; ++i) { const int q = tid + 512 * i, row = q >> 5, ch = q & 31; vv[i] = ldg16(Z + (R0 + row) * ZW + C_VC + ch * 8); }
;       const int tok = tid >> 3, c4 = (tid & 7) * 4; const f32x4 gv = *(const f32x4*)(GATE + (R0 + tok) * 48 + c4);
; #pragma unroll
;       for (int i = 0; i < 2; ++i) { const int q = tid + 512 * i, row = q >> 4, ch = q & 15; *(LAS u32x4*)(Kt + row * KP_ + ch * 8) = kv[i]; }
; #pragma unroll
;       for (int i = 0; i < 4; ++i) { const int q = tid + 512 * i, row = q >> 5, ch = q & 31; *(LAS u32x4*)(Vt + row * VP + ch * 8) = vv[i]; }
;       *(LAS f32x4*)(Gt + tok * 32 + c4) = gv; }
;     __syncthreads();
;     float* BG = (float*)(P.ws + WS_BG);
;     { const int dc = tid & 255, dir = dc >> 7, ch = dc & 127;
;       float w[16];
; #pragma unroll
;       for (int k = 0; k < 16; ++k) w[k] = P.w_gla_gate[(((size_t)layer * 2 + dir) * 16 + k) * 128 + ch];
;       const float bias = P.b_gla_gate[(layer * 2 + dir) * 128 + ch];
;       for (int i = 0; i < 32; ++i) { const int t = (tid >> 8) + 2 * i; float pre = bias;
.LBB0_282:
	s_mul_hi_i32 s0, s4, 0x78787879
	s_lshr_b32 s1, s0, 31
	s_ashr_i32 s8, s0, 5
	s_add_i32 s8, s8, s1
	s_mul_i32 s0, s8, 0x44
	s_sub_i32 s7, s4, s0
	v_readlane_b32 s0, v251, 4
	v_mbcnt_lo_u32_b32 v10, -1, 0
	v_mbcnt_hi_u32_b32 v10, -1, v10
	s_mul_i32 s2, s8, 0x1100
	s_mul_hi_i32 s1, s8, 0x1100
	v_add_u32_e32 v11, s0, v10
	s_lshl_b32 s0, s7, 6
	s_ashr_i32 s3, s0, 31
	s_add_u32 s0, s2, s0
	v_ashrrev_i32_e32 v8, 4, v11
	s_addc_u32 s1, s1, s3
	v_ashrrev_i32_e32 v9, 31, v8
	v_readlane_b32 s2, v253, 12
	v_lshl_add_u64 v[0:1], s[0:1], 0, v[8:9]
	v_readlane_b32 s3, v253, 13
	v_lshlrev_b32_e32 v9, 4, v10
	v_ashrrev_i32_e32 v34, 5, v11
	v_mov_b64_e32 v[20:21], s[2:3]
	s_movk_i32 s9, 0x1800
	v_and_b32_e32 v112, 0xf0, v9
	v_add_u32_e32 v16, 0x200, v11
	v_ashrrev_i32_e32 v35, 31, v34
	v_and_b32_e32 v36, 0x1f0, v9
	v_add_u32_e32 v9, 0x400, v11
	v_mad_u64_u32 v[2:3], s[2:3], v0, s9, v[20:21]
	v_ashrrev_i32_e32 v32, 4, v16
	v_lshl_add_u64 v[12:13], s[0:1], 0, v[34:35]
	v_ashrrev_i32_e32 v40, 5, v9
	v_mad_i32_i24 v3, v1, s9, v3
	v_ashrrev_i32_e32 v33, 31, v32
	v_mad_u64_u32 v[14:15], s[2:3], v12, s9, v[20:21]
	v_ashrrev_i32_e32 v38, 5, v16
	v_ashrrev_i32_e32 v41, 31, v40
	v_lshl_add_u64 v[0:1], v[2:3], 0, v[112:113]
	v_lshl_add_u64 v[2:3], s[0:1], 0, v[32:33]
	v_mad_i32_i24 v15, v13, s9, v15
	v_mov_b32_e32 v37, v113
	v_ashrrev_i32_e32 v39, 31, v38
	v_lshl_add_u64 v[22:23], s[0:1], 0, v[40:41]
	v_add_u32_e32 v9, 0x600, v11
	v_mad_u64_u32 v[4:5], s[2:3], v2, s9, v[20:21]
	v_lshl_add_u64 v[12:13], v[14:15], 0, v[36:37]
	v_lshl_add_u64 v[14:15], s[0:1], 0, v[38:39]
	v_mad_u64_u32 v[24:25], s[2:3], v22, s9, v[20:21]
	v_ashrrev_i32_e32 v42, 5, v9
	v_mad_i32_i24 v5, v3, s9, v5
	v_mad_u64_u32 v[16:17], s[2:3], v14, s9, v[20:21]
	v_mad_i32_i24 v25, v23, s9, v25
	v_ashrrev_i32_e32 v43, 31, v42
	v_lshl_add_u64 v[4:5], v[4:5], 0, v[112:113]
	v_mad_i32_i24 v17, v15, s9, v17
	v_lshl_add_u64 v[22:23], v[24:25], 0, v[36:37]
	v_lshl_add_u64 v[24:25], s[0:1], 0, v[42:43]
	v_ashrrev_i32_e32 v44, 3, v11
	global_load_dwordx4 v[0:3], v[0:1], off offset:2304
	s_nop 0
	global_load_dwordx4 v[4:7], v[4:5], off offset:2304
	v_lshl_add_u64 v[16:17], v[16:17], 0, v[36:37]
	v_mad_u64_u32 v[20:21], s[2:3], v24, s9, v[20:21]
	v_ashrrev_i32_e32 v45, 31, v44
	global_load_dwordx4 v[12:15], v[12:13], off offset:2560
	s_nop 0
	global_load_dwordx4 v[16:19], v[16:17], off offset:2560
	v_mad_i32_i24 v21, v25, s9, v21
	v_lshl_add_u64 v[28:29], s[0:1], 0, v[44:45]
	v_mov_b64_e32 v[30:31], s[28:29]
	s_movk_i32 s9, 0xc0
	v_lshl_add_u64 v[24:25], v[20:21], 0, v[36:37]
	v_mad_u64_u32 v[30:31], s[2:3], v28, s9, v[30:31]
	v_lshlrev_b32_e32 v9, 4, v11
	global_load_dwordx4 v[20:23], v[22:23], off offset:2560
	s_nop 0
	global_load_dwordx4 v[24:27], v[24:25], off offset:2560
	v_mad_i32_i24 v31, v29, s9, v31
	v_and_b32_e32 v46, 0x70, v9
	v_mov_b32_e32 v47, v113
	v_lshl_add_u64 v[28:29], v[30:31], 0, v[46:47]
	global_load_dwordx4 v[28:31], v[28:29], off
	v_add_u32_e32 v48, 0, v112
	s_movk_i32 s9, 0x120
	v_add_u32_e32 v36, 0, v36
	v_mad_u64_u32 v[8:9], s[2:3], v8, s9, v[48:49]
	v_mad_u64_u32 v[32:33], s[2:3], v32, s9, v[48:49]
	s_movk_i32 s9, 0x220
	v_mad_u64_u32 v[34:35], s[2:3], v34, s9, v[36:37]
	v_readlane_b32 s12, v251, 26
	v_readlane_b32 s13, v251, 27
	v_readlane_b32 s14, v251, 28
	s_waitcnt vmcnt(6)
	ds_write_b128 v8, v[0:3]
	s_waitcnt vmcnt(5)
	ds_write_b128 v32, v[4:7]
	s_waitcnt vmcnt(4)
	ds_write_b128 v34, v[12:15] offset:18432
	v_mad_u64_u32 v[0:1], s[2:3], v38, s9, v[36:37]
	s_waitcnt vmcnt(3)
	ds_write_b128 v0, v[16:19] offset:18432
	v_mad_u64_u32 v[0:1], s[2:3], v40, s9, v[36:37]
	v_readlane_b32 s15, v251, 29
	v_readlane_b32 s16, v251, 30
	v_readlane_b32 s17, v251, 31
	s_waitcnt vmcnt(2)
	ds_write_b128 v0, v[20:23] offset:18432
	v_mad_u64_u32 v[0:1], s[2:3], v42, s9, v[36:37]
	s_waitcnt vmcnt(1)
	ds_write_b128 v0, v[24:27] offset:18432
	v_lshlrev_b32_e32 v0, 7, v44
	v_readlane_b32 s2, v254, 40
	v_bfe_u32 v22, v11, 7, 1
	v_readlane_b32 s18, v251, 32
	v_add3_u32 v0, s2, v0, v46
	v_readlane_b32 s19, v251, 33
	v_readlane_b32 s20, v251, 34
	v_readlane_b32 s21, v251, 35
	v_readlane_b32 s22, v251, 36
	v_readlane_b32 s23, v251, 37
	s_waitcnt vmcnt(0)
	ds_write_b128 v0, v[28:31]
	v_and_b32_e32 v13, 0x7f, v11
	v_lshlrev_b32_e32 v0, 11, v22
	v_readlane_b32 s24, v251, 38
	v_readlane_b32 s25, v251, 39
	v_readlane_b32 s26, v251, 40
	v_readlane_b32 s27, v251, 41
	s_mov_b64 s[12:13], s[16:17]
	v_or3_b32 v112, v0, s5, v13
	s_mov_b64 s[14:15], s[18:19]
	s_mov_b64 s[16:17], s[20:21]
	s_mov_b64 s[18:19], s[22:23]
	s_mov_b64 s[20:21], s[24:25]
	v_lshl_add_u64 v[2:3], v[112:113], 2, s[20:21]
	s_movk_i32 s2, 0x1000
	v_add_co_u32_e32 v20, vcc, s2, v2
	s_waitcnt lgkmcnt(0)
	s_nop 0
	v_addc_co_u32_e32 v21, vcc, 0, v3, vcc
	s_barrier
	global_load_dword v14, v[2:3], off
	global_load_dword v15, v[2:3], off offset:512
	global_load_dword v16, v[2:3], off offset:1024
	global_load_dword v17, v[2:3], off offset:1536
	global_load_dword v18, v[2:3], off offset:2048
	global_load_dword v19, v[2:3], off offset:2560
	global_load_dword v0, v[2:3], off offset:3072
	global_load_dword v1, v[2:3], off offset:3584
	s_nop 0
	global_load_dword v2, v[20:21], off
	global_load_dword v3, v[20:21], off offset:512
	global_load_dword v4, v[20:21], off offset:1024
	global_load_dword v5, v[20:21], off offset:1536
	global_load_dword v6, v[20:21], off offset:2048
	global_load_dword v7, v[20:21], off offset:2560
	global_load_dword v8, v[20:21], off offset:3072
	global_load_dword v9, v[20:21], off offset:3584
	v_lshlrev_b32_e32 v12, 7, v22
	s_mov_b64 s[22:23], s[26:27]
	v_or3_b32 v112, v12, s6, v13
	v_lshl_add_u64 v[20:21], v[112:113], 2, s[22:23]
	global_load_dword v20, v[20:21], off
	v_ashrrev_i32_e32 v41, 8, v11
	v_lshlrev_b32_e32 v21, 9, v41
	v_lshl_add_u32 v21, v22, 15, v21
	v_lshlrev_b32_e32 v23, 6, v22
	v_lshl_or_b32 v21, v13, 2, v21
	s_movk_i32 s68, 0x1800
	s_movk_i32 s30, 0x120
	v_lshlrev_b32_e32 v12, 2, v11
	v_add_u32_e32 v21, 0xd000, v21
	v_lshl_or_b32 v22, v41, 7, v23
	s_mov_b32 s2, 32
	s_mov_b32 s3, 0x800000
	s_mov_b32 s9, 0xbfb8aa3b
	s_mov_b32 s10, 0x3f317217
	s_mov_b32 s11, 0x7f800000
	s_waitcnt vmcnt(0)
; DI float logsig(float x) { return fminf(x, 0.f) - __logf(1.f + __expf(-fabsf(x))); }
; DI void gla_prep_item(const KP& P, int layer, int b, int tb, LAS unsigned char* lds) {
;     ...
;       for (int i = 0; i < 32; ++i) { const int t = (tid >> 8) + 2 * i; float pre = bias;
; #pragma unroll
;           for (int k = 0; k < 16; ++k) pre += Gt[t * 32 + dir * 16 + k] * w[k];
;           Bc[(dir * 64 + t) * 128 + ch] = logsig(pre) * (1.f / 16.f); } }
.Lgate_loop:
	v_add_u32_e32 v136, 0x1d000, v22
	ds_read_b128 v[24:27], v136 offset:0
	ds_read_b128 v[28:31], v136 offset:16
	ds_read_b128 v[32:35], v136 offset:32
	ds_read_b128 v[36:39], v136 offset:48
	ds_read_b128 v[46:49], v136 offset:256
	ds_read_b128 v[50:53], v136 offset:272
	ds_read_b128 v[54:57], v136 offset:288
	ds_read_b128 v[58:61], v136 offset:304
	ds_read_b128 v[116:119], v136 offset:512
	ds_read_b128 v[120:123], v136 offset:528
	ds_read_b128 v[124:127], v136 offset:544
	ds_read_b128 v[128:131], v136 offset:560
	ds_read_b128 v[152:155], v136 offset:768
	ds_read_b128 v[156:159], v136 offset:784
	ds_read_b128 v[160:163], v136 offset:800
	ds_read_b128 v[164:167], v136 offset:816
	s_add_i32 s2, s2, -4
	v_add_u32_e32 v22, 0x400, v22
	s_waitcnt lgkmcnt(0)
	v_fma_f32 v42, v14, v24, v20
	v_fma_f32 v62, v14, v46, v20
	v_fma_f32 v132, v14, v116, v20
	v_fma_f32 v168, v14, v152, v20
	v_fmac_f32_e32 v42, v15, v25
	v_fmac_f32_e32 v62, v15, v47
	v_fmac_f32_e32 v132, v15, v117
	v_fmac_f32_e32 v168, v15, v153
	v_fmac_f32_e32 v42, v16, v26
	v_fmac_f32_e32 v62, v16, v48
	v_fmac_f32_e32 v132, v16, v118
	v_fmac_f32_e32 v168, v16, v154
	v_fmac_f32_e32 v42, v17, v27
	v_fmac_f32_e32 v62, v17, v49
	v_fmac_f32_e32 v132, v17, v119
	v_fmac_f32_e32 v168, v17, v155
	v_fmac_f32_e32 v42, v18, v28
	v_fmac_f32_e32 v62, v18, v50
	v_fmac_f32_e32 v132, v18, v120
	v_fmac_f32_e32 v168, v18, v156
	v_pk_mul_f32 v[30:31], v[0:1], v[30:31]
	v_pk_mul_f32 v[52:53], v[0:1], v[52:53]
	v_pk_mul_f32 v[122:123], v[0:1], v[122:123]
	v_pk_mul_f32 v[158:159], v[0:1], v[158:159]
	v_fmac_f32_e32 v42, v19, v29
	v_fmac_f32_e32 v62, v19, v51
	v_fmac_f32_e32 v132, v19, v121
	v_fmac_f32_e32 v168, v19, v157
	v_add_f32_e32 v42, v42, v30
	v_add_f32_e32 v62, v62, v52
	v_add_f32_e32 v132, v132, v122
	v_add_f32_e32 v168, v168, v158
	v_pk_mul_f32 v[32:33], v[2:3], v[32:33]
	v_pk_mul_f32 v[54:55], v[2:3], v[54:55]
	v_pk_mul_f32 v[124:125], v[2:3], v[124:125]
	v_pk_mul_f32 v[160:161], v[2:3], v[160:161]
	v_add_f32_e32 v42, v42, v31
	v_add_f32_e32 v62, v62, v53
	v_add_f32_e32 v132, v132, v123
	v_add_f32_e32 v168, v168, v159
	v_add_f32_e32 v42, v42, v32
	v_add_f32_e32 v62, v62, v54
	v_add_f32_e32 v132, v132, v124
	v_add_f32_e32 v168, v168, v160
	v_pk_mul_f32 v[34:35], v[4:5], v[34:35]
	v_pk_mul_f32 v[56:57], v[4:5], v[56:57]
	v_pk_mul_f32 v[126:127], v[4:5], v[126:127]
	v_pk_mul_f32 v[162:163], v[4:5], v[162:163]
	v_add_f32_e32 v42, v42, v33
	v_add_f32_e32 v62, v62, v55
	v_add_f32_e32 v132, v132, v125
	v_add_f32_e32 v168, v168, v161
	v_add_f32_e32 v42, v42, v34
	v_add_f32_e32 v62, v62, v56
	v_add_f32_e32 v132, v132, v126
	v_add_f32_e32 v168, v168, v162
	v_pk_mul_f32 v[36:37], v[6:7], v[36:37]
	v_pk_mul_f32 v[58:59], v[6:7], v[58:59]
	v_pk_mul_f32 v[128:129], v[6:7], v[128:129]
	v_pk_mul_f32 v[164:165], v[6:7], v[164:165]
	v_add_f32_e32 v42, v42, v35
	v_add_f32_e32 v62, v62, v57
	v_add_f32_e32 v132, v132, v127
	v_add_f32_e32 v168, v168, v163
	v_add_f32_e32 v42, v42, v36
	v_add_f32_e32 v62, v62, v58
	v_add_f32_e32 v132, v132, v128
	v_add_f32_e32 v168, v168, v164
	v_pk_mul_f32 v[38:39], v[8:9], v[38:39]
	v_pk_mul_f32 v[60:61], v[8:9], v[60:61]
	v_pk_mul_f32 v[130:131], v[8:9], v[130:131]
	v_pk_mul_f32 v[166:167], v[8:9], v[166:167]
	v_add_f32_e32 v42, v42, v37
	v_add_f32_e32 v62, v62, v59
	v_add_f32_e32 v132, v132, v129
	v_add_f32_e32 v168, v168, v165
	v_add_f32_e32 v42, v42, v38
	v_add_f32_e32 v62, v62, v60
	v_add_f32_e32 v132, v132, v130
	v_add_f32_e32 v168, v168, v166
	v_add_f32_e32 v42, v42, v39
	v_add_f32_e32 v62, v62, v61
	v_add_f32_e32 v132, v132, v131
	v_add_f32_e32 v168, v168, v167
	v_min_f32_e32 v43, 0, v42
	v_min_f32_e32 v63, 0, v62
	v_min_f32_e32 v133, 0, v132
	v_min_f32_e32 v169, 0, v168
	v_mul_f32_e64 v24, |v42|, s9
	v_mul_f32_e64 v46, |v62|, s9
	v_mul_f32_e64 v116, |v132|, s9
	v_mul_f32_e64 v152, |v168|, s9
	v_exp_f32_e32 v24, v24
	v_exp_f32_e32 v46, v46
	v_exp_f32_e32 v116, v116
	v_exp_f32_e32 v152, v152
	v_add_f32_e32 v24, 1.0, v24
	v_add_f32_e32 v46, 1.0, v46
	v_add_f32_e32 v116, 1.0, v116
	v_add_f32_e32 v152, 1.0, v152
	v_cmp_gt_f32_e64 s[74:75], s3, v24
	v_cmp_gt_f32_e64 s[76:77], s3, v46
	v_cmp_gt_f32_e64 s[78:79], s3, v116
	v_cmp_gt_f32_e64 s[80:81], s3, v152
	v_cndmask_b32_e64 v44, 0, 32, s[74:75]
	v_cndmask_b32_e64 v64, 0, 32, s[76:77]
	v_cndmask_b32_e64 v134, 0, 32, s[78:79]
	v_cndmask_b32_e64 v170, 0, 32, s[80:81]
	v_ldexp_f32 v24, v24, v44
	v_ldexp_f32 v46, v46, v64
	v_ldexp_f32 v116, v116, v134
	v_ldexp_f32 v152, v152, v170
	v_log_f32_e32 v24, v24
	v_log_f32_e32 v46, v46
	v_log_f32_e32 v116, v116
	v_log_f32_e32 v152, v152
	v_cndmask_b32_e64 v44, 0, v148, s[74:75]
	v_cndmask_b32_e64 v64, 0, v148, s[76:77]
	v_cndmask_b32_e64 v134, 0, v148, s[78:79]
	v_cndmask_b32_e64 v170, 0, v148, s[80:81]
	v_mul_f32_e32 v45, 0x3f317217, v24
	v_mul_f32_e32 v114, 0x3f317217, v46
	v_mul_f32_e32 v135, 0x3f317217, v116
	v_mul_f32_e32 v171, 0x3f317217, v152
	v_fma_f32 v45, v24, s10, -v45
	v_fma_f32 v114, v46, s10, -v114
	v_fma_f32 v135, v116, s10, -v135
	v_fma_f32 v171, v152, s10, -v171
	v_fmac_f32_e32 v45, 0x3377d1cf, v24
	v_fmac_f32_e32 v114, 0x3377d1cf, v46
	v_fmac_f32_e32 v135, 0x3377d1cf, v116
	v_fmac_f32_e32 v171, 0x3377d1cf, v152
	v_fmac_f32_e32 v45, 0x3f317217, v24
	v_fmac_f32_e32 v114, 0x3f317217, v46
	v_fmac_f32_e32 v135, 0x3f317217, v116
	v_fmac_f32_e32 v171, 0x3f317217, v152
	v_cmp_lt_f32_e64 s[74:75], |v24|, s11
	v_cmp_lt_f32_e64 s[76:77], |v46|, s11
	v_cmp_lt_f32_e64 s[78:79], |v116|, s11
	v_cmp_lt_f32_e64 s[80:81], |v152|, s11
	v_cndmask_b32_e64 v24, v24, v45, s[74:75]
	v_cndmask_b32_e64 v46, v46, v114, s[76:77]
	v_cndmask_b32_e64 v116, v116, v135, s[78:79]
	v_cndmask_b32_e64 v152, v152, v171, s[80:81]
	v_sub_f32_e32 v24, v24, v44
	v_sub_f32_e32 v46, v46, v64
	v_sub_f32_e32 v116, v116, v134
	v_sub_f32_e32 v152, v152, v170
	v_sub_f32_e32 v24, v43, v24
	v_sub_f32_e32 v46, v63, v46
	v_sub_f32_e32 v116, v133, v116
	v_sub_f32_e32 v152, v169, v152
	v_mul_f32_e32 v24, 0x3d800000, v24
	v_mul_f32_e32 v46, 0x3d800000, v46
	v_mul_f32_e32 v116, 0x3d800000, v116
	v_mul_f32_e32 v152, 0x3d800000, v152
	ds_write_b32 v21, v24
	ds_write_b32 v21, v46 offset:1024
	ds_write_b32 v21, v116 offset:2048
	ds_write_b32 v21, v152 offset:3072
	v_add_u32_e32 v21, 0x1000, v21
	s_cmp_eq_u32 s2, 0
	s_cbranch_scc0 .Lgate_loop
; DI void gla_prep_item(const KP& P, int layer, int b, int tb, LAS unsigned char* lds) {
;     ...
;     __syncthreads();
;     if (tid < 256) { const int dir = tid >> 7, ch = tid & 127; float run = 0.f;
;         for (int step = 0; step < 64; ++step) { const int t = dir ? 63 - step : step;
;             run += Bc[(dir * 64 + t) * 128 + ch]; Bc[(dir * 64 + t) * 128 + ch] = run; BG[(R0 + t) * 256 + dir * 128 + ch] = run; } }
	s_movk_i32 s2, 0x100
	v_cmp_gt_i32_e32 vcc, s2, v11
	s_waitcnt lgkmcnt(0)
	s_barrier
	s_and_saveexec_b64 s[2:3], vcc
	s_cbranch_execz .LBB0_286
	s_movk_i32 s9, 0x80
	v_lshlrev_b32_e32 v0, 8, v11
	v_cmp_gt_u32_e32 vcc, s9, v11
	v_and_b32_e32 v0, 0xffff8000, v0
	v_lshlrev_b32_e32 v112, 2, v13
	v_add3_u32 v4, 0, v0, v112
	v_cndmask_b32_e64 v2, 63, 0, vcc
	v_lshl_add_u32 v3, v2, 9, v4
	v_mov_b32_e32 v6, 0x200
	v_mov_b32_e32 v7, 0xfffffe00
	v_mov_b32_e32 v14, 0x400
	v_mov_b32_e32 v15, 0xfffffc00
	v_cndmask_b32_e32 v8, v7, v6, vcc
	v_cndmask_b32_e32 v14, v15, v14, vcc
	v_mov_b32_e32 v9, v3
	v_and_b32_e32 v0, 0xffffff80, v11
	v_readlane_b32 s10, v254, 14
	v_ashrrev_i32_e32 v1, 31, v0
	v_readlane_b32 s11, v254, 15
	v_ashrrev_i32_e32 v15, 31, v14
	v_or_b32_e32 v6, s0, v2
	v_mov_b32_e32 v7, s1
	v_lshl_add_u64 v[0:1], v[0:1], 2, s[10:11]
	v_lshl_add_u64 v[0:1], v[0:1], 0, v[112:113]
	v_lshlrev_b64 v[6:7], 10, v[6:7]
	v_lshl_add_u64 v[6:7], v[0:1], 0, v[6:7]
	v_mov_b32_e32 v5, 0
	ds_read_b32 v20, v3 offset:53248
	v_add_u32_e32 v3, v8, v3
	ds_read_b32 v21, v3 offset:53248
	v_add_u32_e32 v3, v8, v3
	ds_read_b32 v22, v3 offset:53248
	v_add_u32_e32 v3, v8, v3
	ds_read_b32 v23, v3 offset:53248
	v_add_u32_e32 v3, v8, v3
	ds_read_b32 v24, v3 offset:53248
	v_add_u32_e32 v3, v8, v3
	ds_read_b32 v25, v3 offset:53248
	v_add_u32_e32 v3, v8, v3
	ds_read_b32 v26, v3 offset:53248
	v_add_u32_e32 v3, v8, v3
	ds_read_b32 v27, v3 offset:53248
	v_add_u32_e32 v3, v8, v3
	ds_read_b32 v28, v3 offset:53248
	v_add_u32_e32 v3, v8, v3
	ds_read_b32 v29, v3 offset:53248
	v_add_u32_e32 v3, v8, v3
	ds_read_b32 v30, v3 offset:53248
	v_add_u32_e32 v3, v8, v3
	ds_read_b32 v31, v3 offset:53248
	v_add_u32_e32 v3, v8, v3
	ds_read_b32 v32, v3 offset:53248
	v_add_u32_e32 v3, v8, v3
	ds_read_b32 v33, v3 offset:53248
	v_add_u32_e32 v3, v8, v3
	ds_read_b32 v34, v3 offset:53248
	v_add_u32_e32 v3, v8, v3
	ds_read_b32 v35, v3 offset:53248
	v_add_u32_e32 v3, v8, v3
	s_waitcnt lgkmcnt(0)
	v_add_f32_e32 v5, v5, v20
	ds_write_b32 v9, v5 offset:53248
	global_store_dword v[6:7], v5, off
	v_add_u32_e32 v9, v8, v9
	v_lshl_add_u64 v[6:7], v[6:7], 0, v[14:15]
	v_add_f32_e32 v5, v5, v21
	ds_write_b32 v9, v5 offset:53248
	global_store_dword v[6:7], v5, off
	v_add_u32_e32 v9, v8, v9
	v_lshl_add_u64 v[6:7], v[6:7], 0, v[14:15]
	v_add_f32_e32 v5, v5, v22
	ds_write_b32 v9, v5 offset:53248
	global_store_dword v[6:7], v5, off
	v_add_u32_e32 v9, v8, v9
	v_lshl_add_u64 v[6:7], v[6:7], 0, v[14:15]
	v_add_f32_e32 v5, v5, v23
	ds_write_b32 v9, v5 offset:53248
	global_store_dword v[6:7], v5, off
	v_add_u32_e32 v9, v8, v9
	v_lshl_add_u64 v[6:7], v[6:7], 0, v[14:15]
	v_add_f32_e32 v5, v5, v24
	ds_write_b32 v9, v5 offset:53248
	global_store_dword v[6:7], v5, off
	v_add_u32_e32 v9, v8, v9
	v_lshl_add_u64 v[6:7], v[6:7], 0, v[14:15]
	v_add_f32_e32 v5, v5, v25
	ds_write_b32 v9, v5 offset:53248
	global_store_dword v[6:7], v5, off
	v_add_u32_e32 v9, v8, v9
	v_lshl_add_u64 v[6:7], v[6:7], 0, v[14:15]
	v_add_f32_e32 v5, v5, v26
	ds_write_b32 v9, v5 offset:53248
	global_store_dword v[6:7], v5, off
	v_add_u32_e32 v9, v8, v9
	v_lshl_add_u64 v[6:7], v[6:7], 0, v[14:15]
	v_add_f32_e32 v5, v5, v27
	ds_write_b32 v9, v5 offset:53248
	global_store_dword v[6:7], v5, off
	v_add_u32_e32 v9, v8, v9
	v_lshl_add_u64 v[6:7], v[6:7], 0, v[14:15]
	v_add_f32_e32 v5, v5, v28
	ds_write_b32 v9, v5 offset:53248
	global_store_dword v[6:7], v5, off
	v_add_u32_e32 v9, v8, v9
	v_lshl_add_u64 v[6:7], v[6:7], 0, v[14:15]
	v_add_f32_e32 v5, v5, v29
	ds_write_b32 v9, v5 offset:53248
	global_store_dword v[6:7], v5, off
	v_add_u32_e32 v9, v8, v9
	v_lshl_add_u64 v[6:7], v[6:7], 0, v[14:15]
	v_add_f32_e32 v5, v5, v30
	ds_write_b32 v9, v5 offset:53248
	global_store_dword v[6:7], v5, off
	v_add_u32_e32 v9, v8, v9
	v_lshl_add_u64 v[6:7], v[6:7], 0, v[14:15]
	v_add_f32_e32 v5, v5, v31
	ds_write_b32 v9, v5 offset:53248
	global_store_dword v[6:7], v5, off
	v_add_u32_e32 v9, v8, v9
	v_lshl_add_u64 v[6:7], v[6:7], 0, v[14:15]
	v_add_f32_e32 v5, v5, v32
	ds_write_b32 v9, v5 offset:53248
	global_store_dword v[6:7], v5, off
	v_add_u32_e32 v9, v8, v9
	v_lshl_add_u64 v[6:7], v[6:7], 0, v[14:15]
	v_add_f32_e32 v5, v5, v33
	ds_write_b32 v9, v5 offset:53248
	global_store_dword v[6:7], v5, off
	v_add_u32_e32 v9, v8, v9
	v_lshl_add_u64 v[6:7], v[6:7], 0, v[14:15]
	v_add_f32_e32 v5, v5, v34
	ds_write_b32 v9, v5 offset:53248
	global_store_dword v[6:7], v5, off
	v_add_u32_e32 v9, v8, v9
	v_lshl_add_u64 v[6:7], v[6:7], 0, v[14:15]
	v_add_f32_e32 v5, v5, v35
	ds_write_b32 v9, v5 offset:53248
	global_store_dword v[6:7], v5, off
	v_add_u32_e32 v9, v8, v9
	v_lshl_add_u64 v[6:7], v[6:7], 0, v[14:15]
	ds_read_b32 v20, v3 offset:53248
	v_add_u32_e32 v3, v8, v3
	ds_read_b32 v21, v3 offset:53248
	v_add_u32_e32 v3, v8, v3
	ds_read_b32 v22, v3 offset:53248
	v_add_u32_e32 v3, v8, v3
	ds_read_b32 v23, v3 offset:53248
	v_add_u32_e32 v3, v8, v3
	ds_read_b32 v24, v3 offset:53248
	v_add_u32_e32 v3, v8, v3
	ds_read_b32 v25, v3 offset:53248
	v_add_u32_e32 v3, v8, v3
	ds_read_b32 v26, v3 offset:53248
	v_add_u32_e32 v3, v8, v3
	ds_read_b32 v27, v3 offset:53248
	v_add_u32_e32 v3, v8, v3
	ds_read_b32 v28, v3 offset:53248
	v_add_u32_e32 v3, v8, v3
	ds_read_b32 v29, v3 offset:53248
	v_add_u32_e32 v3, v8, v3
	ds_read_b32 v30, v3 offset:53248
	v_add_u32_e32 v3, v8, v3
	ds_read_b32 v31, v3 offset:53248
	v_add_u32_e32 v3, v8, v3
	ds_read_b32 v32, v3 offset:53248
	v_add_u32_e32 v3, v8, v3
	ds_read_b32 v33, v3 offset:53248
	v_add_u32_e32 v3, v8, v3
	ds_read_b32 v34, v3 offset:53248
	v_add_u32_e32 v3, v8, v3
	ds_read_b32 v35, v3 offset:53248
	v_add_u32_e32 v3, v8, v3
	s_waitcnt lgkmcnt(0)
; DI void gla_prep_item(const KP& P, int layer, int b, int tb, LAS unsigned char* lds) {
;     ...
;     if (tid < 256) { const int dir = tid >> 7, ch = tid & 127; float run = 0.f;
;         for (int step = 0; step < 64; ++step) { const int t = dir ? 63 - step : step;
;             run += Bc[(dir * 64 + t) * 128 + ch]; Bc[(dir * 64 + t) * 128 + ch] = run; BG[(R0 + t) * 256 + dir * 128 + ch] = run; } }
	v_add_f32_e32 v5, v5, v20
	ds_write_b32 v9, v5 offset:53248
	global_store_dword v[6:7], v5, off
	v_add_u32_e32 v9, v8, v9
	v_lshl_add_u64 v[6:7], v[6:7], 0, v[14:15]
	v_add_f32_e32 v5, v5, v21
	ds_write_b32 v9, v5 offset:53248
	global_store_dword v[6:7], v5, off
	v_add_u32_e32 v9, v8, v9
	v_lshl_add_u64 v[6:7], v[6:7], 0, v[14:15]
	v_add_f32_e32 v5, v5, v22
	ds_write_b32 v9, v5 offset:53248
	global_store_dword v[6:7], v5, off
	v_add_u32_e32 v9, v8, v9
	v_lshl_add_u64 v[6:7], v[6:7], 0, v[14:15]
	v_add_f32_e32 v5, v5, v23
	ds_write_b32 v9, v5 offset:53248
	global_store_dword v[6:7], v5, off
	v_add_u32_e32 v9, v8, v9
	v_lshl_add_u64 v[6:7], v[6:7], 0, v[14:15]
	v_add_f32_e32 v5, v5, v24
	ds_write_b32 v9, v5 offset:53248
	global_store_dword v[6:7], v5, off
	v_add_u32_e32 v9, v8, v9
	v_lshl_add_u64 v[6:7], v[6:7], 0, v[14:15]
	v_add_f32_e32 v5, v5, v25
	ds_write_b32 v9, v5 offset:53248
	global_store_dword v[6:7], v5, off
	v_add_u32_e32 v9, v8, v9
	v_lshl_add_u64 v[6:7], v[6:7], 0, v[14:15]
	v_add_f32_e32 v5, v5, v26
	ds_write_b32 v9, v5 offset:53248
	global_store_dword v[6:7], v5, off
	v_add_u32_e32 v9, v8, v9
	v_lshl_add_u64 v[6:7], v[6:7], 0, v[14:15]
	v_add_f32_e32 v5, v5, v27
	ds_write_b32 v9, v5 offset:53248
	global_store_dword v[6:7], v5, off
	v_add_u32_e32 v9, v8, v9
	v_lshl_add_u64 v[6:7], v[6:7], 0, v[14:15]
	v_add_f32_e32 v5, v5, v28
	ds_write_b32 v9, v5 offset:53248
	global_store_dword v[6:7], v5, off
	v_add_u32_e32 v9, v8, v9
	v_lshl_add_u64 v[6:7], v[6:7], 0, v[14:15]
	v_add_f32_e32 v5, v5, v29
	ds_write_b32 v9, v5 offset:53248
	global_store_dword v[6:7], v5, off
	v_add_u32_e32 v9, v8, v9
	v_lshl_add_u64 v[6:7], v[6:7], 0, v[14:15]
	v_add_f32_e32 v5, v5, v30
	ds_write_b32 v9, v5 offset:53248
	global_store_dword v[6:7], v5, off
	v_add_u32_e32 v9, v8, v9
	v_lshl_add_u64 v[6:7], v[6:7], 0, v[14:15]
	v_add_f32_e32 v5, v5, v31
	ds_write_b32 v9, v5 offset:53248
	global_store_dword v[6:7], v5, off
	v_add_u32_e32 v9, v8, v9
	v_lshl_add_u64 v[6:7], v[6:7], 0, v[14:15]
	v_add_f32_e32 v5, v5, v32
	ds_write_b32 v9, v5 offset:53248
	global_store_dword v[6:7], v5, off
	v_add_u32_e32 v9, v8, v9
	v_lshl_add_u64 v[6:7], v[6:7], 0, v[14:15]
	v_add_f32_e32 v5, v5, v33
	ds_write_b32 v9, v5 offset:53248
	global_store_dword v[6:7], v5, off
	v_add_u32_e32 v9, v8, v9
	v_lshl_add_u64 v[6:7], v[6:7], 0, v[14:15]
	v_add_f32_e32 v5, v5, v34
	ds_write_b32 v9, v5 offset:53248
	global_store_dword v[6:7], v5, off
	v_add_u32_e32 v9, v8, v9
	v_lshl_add_u64 v[6:7], v[6:7], 0, v[14:15]
	v_add_f32_e32 v5, v5, v35
	ds_write_b32 v9, v5 offset:53248
	global_store_dword v[6:7], v5, off
	v_add_u32_e32 v9, v8, v9
	v_lshl_add_u64 v[6:7], v[6:7], 0, v[14:15]
	ds_read_b32 v20, v3 offset:53248
	v_add_u32_e32 v3, v8, v3
	ds_read_b32 v21, v3 offset:53248
	v_add_u32_e32 v3, v8, v3
	ds_read_b32 v22, v3 offset:53248
	v_add_u32_e32 v3, v8, v3
	ds_read_b32 v23, v3 offset:53248
	v_add_u32_e32 v3, v8, v3
	ds_read_b32 v24, v3 offset:53248
	v_add_u32_e32 v3, v8, v3
	ds_read_b32 v25, v3 offset:53248
	v_add_u32_e32 v3, v8, v3
	ds_read_b32 v26, v3 offset:53248
	v_add_u32_e32 v3, v8, v3
	ds_read_b32 v27, v3 offset:53248
	v_add_u32_e32 v3, v8, v3
	ds_read_b32 v28, v3 offset:53248
	v_add_u32_e32 v3, v8, v3
	ds_read_b32 v29, v3 offset:53248
	v_add_u32_e32 v3, v8, v3
	ds_read_b32 v30, v3 offset:53248
	v_add_u32_e32 v3, v8, v3
	ds_read_b32 v31, v3 offset:53248
	v_add_u32_e32 v3, v8, v3
	ds_read_b32 v32, v3 offset:53248
	v_add_u32_e32 v3, v8, v3
	ds_read_b32 v33, v3 offset:53248
	v_add_u32_e32 v3, v8, v3
	ds_read_b32 v34, v3 offset:53248
	v_add_u32_e32 v3, v8, v3
	ds_read_b32 v35, v3 offset:53248
	v_add_u32_e32 v3, v8, v3
	s_waitcnt lgkmcnt(0)
; DI void gla_prep_item(const KP& P, int layer, int b, int tb, LAS unsigned char* lds) {
;     ...
;     if (tid < 256) { const int dir = tid >> 7, ch = tid & 127; float run = 0.f;
;         for (int step = 0; step < 64; ++step) { const int t = dir ? 63 - step : step;
;             run += Bc[(dir * 64 + t) * 128 + ch]; Bc[(dir * 64 + t) * 128 + ch] = run; BG[(R0 + t) * 256 + dir * 128 + ch] = run; } }
	v_add_f32_e32 v5, v5, v20
	ds_write_b32 v9, v5 offset:53248
	global_store_dword v[6:7], v5, off
	v_add_u32_e32 v9, v8, v9
	v_lshl_add_u64 v[6:7], v[6:7], 0, v[14:15]
	v_add_f32_e32 v5, v5, v21
	ds_write_b32 v9, v5 offset:53248
	global_store_dword v[6:7], v5, off
	v_add_u32_e32 v9, v8, v9
	v_lshl_add_u64 v[6:7], v[6:7], 0, v[14:15]
	v_add_f32_e32 v5, v5, v22
	ds_write_b32 v9, v5 offset:53248
	global_store_dword v[6:7], v5, off
	v_add_u32_e32 v9, v8, v9
	v_lshl_add_u64 v[6:7], v[6:7], 0, v[14:15]
	v_add_f32_e32 v5, v5, v23
	ds_write_b32 v9, v5 offset:53248
	global_store_dword v[6:7], v5, off
	v_add_u32_e32 v9, v8, v9
	v_lshl_add_u64 v[6:7], v[6:7], 0, v[14:15]
	v_add_f32_e32 v5, v5, v24
	ds_write_b32 v9, v5 offset:53248
	global_store_dword v[6:7], v5, off
	v_add_u32_e32 v9, v8, v9
	v_lshl_add_u64 v[6:7], v[6:7], 0, v[14:15]
	v_add_f32_e32 v5, v5, v25
	ds_write_b32 v9, v5 offset:53248
	global_store_dword v[6:7], v5, off
	v_add_u32_e32 v9, v8, v9
	v_lshl_add_u64 v[6:7], v[6:7], 0, v[14:15]
	v_add_f32_e32 v5, v5, v26
	ds_write_b32 v9, v5 offset:53248
	global_store_dword v[6:7], v5, off
	v_add_u32_e32 v9, v8, v9
	v_lshl_add_u64 v[6:7], v[6:7], 0, v[14:15]
	v_add_f32_e32 v5, v5, v27
	ds_write_b32 v9, v5 offset:53248
	global_store_dword v[6:7], v5, off
	v_add_u32_e32 v9, v8, v9
	v_lshl_add_u64 v[6:7], v[6:7], 0, v[14:15]
	v_add_f32_e32 v5, v5, v28
	ds_write_b32 v9, v5 offset:53248
	global_store_dword v[6:7], v5, off
	v_add_u32_e32 v9, v8, v9
	v_lshl_add_u64 v[6:7], v[6:7], 0, v[14:15]
	v_add_f32_e32 v5, v5, v29
	ds_write_b32 v9, v5 offset:53248
	global_store_dword v[6:7], v5, off
	v_add_u32_e32 v9, v8, v9
	v_lshl_add_u64 v[6:7], v[6:7], 0, v[14:15]
	v_add_f32_e32 v5, v5, v30
	ds_write_b32 v9, v5 offset:53248
	global_store_dword v[6:7], v5, off
	v_add_u32_e32 v9, v8, v9
	v_lshl_add_u64 v[6:7], v[6:7], 0, v[14:15]
	v_add_f32_e32 v5, v5, v31
	ds_write_b32 v9, v5 offset:53248
	global_store_dword v[6:7], v5, off
	v_add_u32_e32 v9, v8, v9
	v_lshl_add_u64 v[6:7], v[6:7], 0, v[14:15]
	v_add_f32_e32 v5, v5, v32
	ds_write_b32 v9, v5 offset:53248
	global_store_dword v[6:7], v5, off
	v_add_u32_e32 v9, v8, v9
	v_lshl_add_u64 v[6:7], v[6:7], 0, v[14:15]
	v_add_f32_e32 v5, v5, v33
	ds_write_b32 v9, v5 offset:53248
	global_store_dword v[6:7], v5, off
	v_add_u32_e32 v9, v8, v9
	v_lshl_add_u64 v[6:7], v[6:7], 0, v[14:15]
	v_add_f32_e32 v5, v5, v34
	ds_write_b32 v9, v5 offset:53248
	global_store_dword v[6:7], v5, off
	v_add_u32_e32 v9, v8, v9
	v_lshl_add_u64 v[6:7], v[6:7], 0, v[14:15]
	v_add_f32_e32 v5, v5, v35
	ds_write_b32 v9, v5 offset:53248
	global_store_dword v[6:7], v5, off
	v_add_u32_e32 v9, v8, v9
	v_lshl_add_u64 v[6:7], v[6:7], 0, v[14:15]
	ds_read_b32 v20, v3 offset:53248
	v_add_u32_e32 v3, v8, v3
	ds_read_b32 v21, v3 offset:53248
	v_add_u32_e32 v3, v8, v3
	ds_read_b32 v22, v3 offset:53248
	v_add_u32_e32 v3, v8, v3
	ds_read_b32 v23, v3 offset:53248
	v_add_u32_e32 v3, v8, v3
	ds_read_b32 v24, v3 offset:53248
	v_add_u32_e32 v3, v8, v3
	ds_read_b32 v25, v3 offset:53248
	v_add_u32_e32 v3, v8, v3
	ds_read_b32 v26, v3 offset:53248
	v_add_u32_e32 v3, v8, v3
	ds_read_b32 v27, v3 offset:53248
	v_add_u32_e32 v3, v8, v3
	ds_read_b32 v28, v3 offset:53248
	v_add_u32_e32 v3, v8, v3
	ds_read_b32 v29, v3 offset:53248
	v_add_u32_e32 v3, v8, v3
	ds_read_b32 v30, v3 offset:53248
	v_add_u32_e32 v3, v8, v3
	ds_read_b32 v31, v3 offset:53248
	v_add_u32_e32 v3, v8, v3
	ds_read_b32 v32, v3 offset:53248
	v_add_u32_e32 v3, v8, v3
	ds_read_b32 v33, v3 offset:53248
	v_add_u32_e32 v3, v8, v3
	ds_read_b32 v34, v3 offset:53248
	v_add_u32_e32 v3, v8, v3
	ds_read_b32 v35, v3 offset:53248
	v_add_u32_e32 v3, v8, v3
	s_waitcnt lgkmcnt(0)
	v_add_f32_e32 v5, v5, v20
	ds_write_b32 v9, v5 offset:53248
	global_store_dword v[6:7], v5, off
	v_add_u32_e32 v9, v8, v9
	v_lshl_add_u64 v[6:7], v[6:7], 0, v[14:15]
	v_add_f32_e32 v5, v5, v21
	ds_write_b32 v9, v5 offset:53248
	global_store_dword v[6:7], v5, off
	v_add_u32_e32 v9, v8, v9
	v_lshl_add_u64 v[6:7], v[6:7], 0, v[14:15]
	v_add_f32_e32 v5, v5, v22
	ds_write_b32 v9, v5 offset:53248
	global_store_dword v[6:7], v5, off
	v_add_u32_e32 v9, v8, v9
	v_lshl_add_u64 v[6:7], v[6:7], 0, v[14:15]
	v_add_f32_e32 v5, v5, v23
	ds_write_b32 v9, v5 offset:53248
	global_store_dword v[6:7], v5, off
	v_add_u32_e32 v9, v8, v9
	v_lshl_add_u64 v[6:7], v[6:7], 0, v[14:15]
	v_add_f32_e32 v5, v5, v24
	ds_write_b32 v9, v5 offset:53248
	global_store_dword v[6:7], v5, off
	v_add_u32_e32 v9, v8, v9
	v_lshl_add_u64 v[6:7], v[6:7], 0, v[14:15]
	v_add_f32_e32 v5, v5, v25
	ds_write_b32 v9, v5 offset:53248
	global_store_dword v[6:7], v5, off
	v_add_u32_e32 v9, v8, v9
	v_lshl_add_u64 v[6:7], v[6:7], 0, v[14:15]
	v_add_f32_e32 v5, v5, v26
	ds_write_b32 v9, v5 offset:53248
	global_store_dword v[6:7], v5, off
	v_add_u32_e32 v9, v8, v9
	v_lshl_add_u64 v[6:7], v[6:7], 0, v[14:15]
	v_add_f32_e32 v5, v5, v27
	ds_write_b32 v9, v5 offset:53248
	global_store_dword v[6:7], v5, off
	v_add_u32_e32 v9, v8, v9
	v_lshl_add_u64 v[6:7], v[6:7], 0, v[14:15]
	v_add_f32_e32 v5, v5, v28
	ds_write_b32 v9, v5 offset:53248
	global_store_dword v[6:7], v5, off
	v_add_u32_e32 v9, v8, v9
	v_lshl_add_u64 v[6:7], v[6:7], 0, v[14:15]
	v_add_f32_e32 v5, v5, v29
	ds_write_b32 v9, v5 offset:53248
	global_store_dword v[6:7], v5, off
	v_add_u32_e32 v9, v8, v9
	v_lshl_add_u64 v[6:7], v[6:7], 0, v[14:15]
	v_add_f32_e32 v5, v5, v30
	ds_write_b32 v9, v5 offset:53248
	global_store_dword v[6:7], v5, off
	v_add_u32_e32 v9, v8, v9
	v_lshl_add_u64 v[6:7], v[6:7], 0, v[14:15]
	v_add_f32_e32 v5, v5, v31
	ds_write_b32 v9, v5 offset:53248
	global_store_dword v[6:7], v5, off
	v_add_u32_e32 v9, v8, v9
	v_lshl_add_u64 v[6:7], v[6:7], 0, v[14:15]
	v_add_f32_e32 v5, v5, v32
	ds_write_b32 v9, v5 offset:53248
	global_store_dword v[6:7], v5, off
	v_add_u32_e32 v9, v8, v9
	v_lshl_add_u64 v[6:7], v[6:7], 0, v[14:15]
	v_add_f32_e32 v5, v5, v33
	ds_write_b32 v9, v5 offset:53248
	global_store_dword v[6:7], v5, off
	v_add_u32_e32 v9, v8, v9
	v_lshl_add_u64 v[6:7], v[6:7], 0, v[14:15]
	v_add_f32_e32 v5, v5, v34
	ds_write_b32 v9, v5 offset:53248
	global_store_dword v[6:7], v5, off
	v_add_u32_e32 v9, v8, v9
	v_lshl_add_u64 v[6:7], v[6:7], 0, v[14:15]
	v_add_f32_e32 v5, v5, v35
	ds_write_b32 v9, v5 offset:53248
	global_store_dword v[6:7], v5, off
	v_add_u32_e32 v9, v8, v9
	v_lshl_add_u64 v[6:7], v[6:7], 0, v[14:15]

; DI unsigned pk2(float lo, float hi) { f32x2 v = {lo, hi}; bf2_t r = __builtin_convertvector(v, bf2_t); return __builtin_bit_cast(unsigned, r); }
; DI float bflo(unsigned u) { return __uint_as_float(u << 16); }
; DI float bfhi(unsigned u) { return __uint_as_float(u & 0xffff0000u); }
; DI void mlstm_out_item(const KP& P, int layer, int b, int tb, LAS unsigned char* lds) {
;     ...
;     float ss = 0.f;
; #pragma unroll
;     for (int nt = 0; nt < 2; ++nt)
; #pragma unroll
;         for (int i = 0; i < 16; ++i) ss += hs[nt][i] * hs[nt][i];
;     ss += __shfl_xor(ss, 32);
;     const float rstd = rsqrtf(ss * (1.f / 64.f) + EPS);
;     u32x2 og[8];
; #pragma unroll
;     for (int nt = 0; nt < 2; ++nt)
; #pragma unroll
;         for (int g4 = 0; g4 < 4; ++g4) { const int dv = 32 * nt + 8 * g4 + 4 * h;
;             const u32x2 ov = ldg8(Z + (R0 + t) * ZW + C_OD + hd * 64 + dv); const f32x4 gg = *(const f32x4*)(P.g_mlstm_out + layer * 64 + dv);
;             const float oo[4] = {bflo(ov.x), bfhi(ov.x), bflo(ov.y), bfhi(ov.y)}; float y[4];
; #pragma unroll
;             for (int e = 0; e < 4; ++e) { const float sg = 1.f / (1.f + __expf(-oo[e])); y[e] = hs[nt][4 * g4 + e] * rstd * gg[e] * sg; }
;             og[4 * nt + g4].x = pk2(y[0], y[1]); og[4 * nt + g4].y = pk2(y[2], y[3]); }
;     store_row8(O + (R0 + t) * D + 768 + hd * 64, og, h);
.LBB0_531:
	v_mul_f32_e32 v10, v155, v155
	v_fmac_f32_e32 v10, v154, v154
	v_fmac_f32_e32 v10, v146, v146
	v_fmac_f32_e32 v10, v147, v147
	v_fmac_f32_e32 v10, v142, v142
	v_fmac_f32_e32 v10, v143, v143
	v_fmac_f32_e32 v10, v140, v140
	v_fmac_f32_e32 v10, v141, v141
	v_fmac_f32_e32 v10, v138, v138
	v_fmac_f32_e32 v10, v139, v139
	v_fmac_f32_e32 v10, v136, v136
	v_fmac_f32_e32 v10, v137, v137
	v_fmac_f32_e32 v10, v134, v134
	v_fmac_f32_e32 v10, v135, v135
	v_fmac_f32_e32 v10, v132, v132
	v_fmac_f32_e32 v10, v133, v133
	v_fmac_f32_e32 v10, v130, v130
	v_fmac_f32_e32 v10, v131, v131
	v_fmac_f32_e32 v10, v128, v128
	v_fmac_f32_e32 v10, v129, v129
	v_fmac_f32_e32 v10, v126, v126
	v_fmac_f32_e32 v10, v127, v127
	v_pk_mul_f32 v[8:9], v[124:125], v[124:125]
	v_pk_mul_f32 v[6:7], v[122:123], v[122:123]
	v_add_f32_e32 v8, v8, v10
	v_add_f32_e32 v8, v9, v8
	v_add_f32_e32 v6, v6, v8
	v_pk_mul_f32 v[4:5], v[120:121], v[120:121]
	v_add_f32_e32 v6, v7, v6
	v_add_f32_e32 v4, v4, v6
	v_pk_mul_f32 v[2:3], v[118:119], v[118:119]
	v_add_f32_e32 v4, v5, v4
	v_add_f32_e32 v2, v2, v4
	v_pk_mul_f32 v[0:1], v[116:117], v[116:117]
	v_add_f32_e32 v2, v3, v2
	v_add_f32_e32 v0, v0, v2
	v_add_f32_e32 v0, v1, v0
	ds_bpermute_b32 v1, v112, v0
	v_mov_b32_e32 v2, 0x358637bd
	s_mov_b32 s0, 0x800000
	v_ashrrev_i32_e32 v145, 31, v144
	s_movk_i32 s2, 0x1800
	s_waitcnt lgkmcnt(0)
	v_add_f32_e32 v0, v0, v1
	v_fmamk_f32 v0, v0, 0x3c800000, v2
	v_cmp_gt_f32_e32 vcc, s0, v0
	v_mul_f32_e32 v1, 0x4b800000, v0
	v_readlane_b32 s0, v255, 6
	v_cndmask_b32_e32 v0, v0, v1, vcc
	v_rsq_f32_e32 v0, v0
	v_readlane_b32 s1, v255, 7
	v_lshlrev_b32_e32 v112, 1, v150
	v_lshlrev_b32_e32 v16, 2, v115
	v_lshl_add_u64 v[20:21], s[0:1], 0, v[144:145]
	v_readlane_b32 s0, v253, 12
	v_mul_f32_e32 v1, 0x45800000, v0
	v_readlane_b32 s1, v253, 13
	v_cndmask_b32_e32 v18, v0, v1, vcc
	v_readlane_b32 s20, v255, 3
	v_mov_b64_e32 v[0:1], s[0:1]
	v_mad_u64_u32 v[0:1], s[0:1], v20, s2, v[0:1]
	v_mov_b32_e32 v2, v1
	v_mad_u64_u32 v[2:3], s[0:1], v21, s2, v[2:3]
	v_mov_b32_e32 v1, v2
	v_lshl_add_u64 v[0:1], v[0:1], 0, v[112:113]
	v_lshlrev_b32_e32 v2, 1, v115
	v_mov_b32_e32 v3, v113
	v_lshl_add_u64 v[0:1], v[0:1], 0, v[2:3]
	s_mov_b64 s[0:1], 0x1440
	v_lshl_add_u64 v[14:15], v[0:1], 0, s[0:1]
	s_movk_i32 s0, 0x1000
	v_add_co_u32_e32 v0, vcc, s0, v0
	v_readlane_b32 s2, v255, 1
	s_nop 0
	v_addc_co_u32_e32 v1, vcc, 0, v1, vcc
	global_load_dwordx2 v[4:5], v[0:1], off offset:1088
	v_readlane_b32 s3, v255, 2
	s_movk_i32 s68, 0x1800
	v_readlane_b32 s21, v254, 36
	s_movk_i32 s36, 0x44
	s_waitcnt vmcnt(0)
	v_lshlrev_b32_e32 v6, 16, v4
	global_load_dwordx4 v[0:3], v16, s[2:3]
	global_load_dwordx2 v[156:157], v[14:15], off offset:16
	global_load_dwordx4 v[204:207], v16, s[2:3] offset:32
	global_load_dwordx2 v[158:159], v[14:15], off offset:32
	global_load_dwordx4 v[208:211], v16, s[2:3] offset:64
	global_load_dwordx2 v[160:161], v[14:15], off offset:48
	global_load_dwordx4 v[212:215], v16, s[2:3] offset:96
	global_load_dwordx2 v[162:163], v[14:15], off offset:64
	global_load_dwordx4 v[216:219], v16, s[2:3] offset:128
	global_load_dwordx2 v[164:165], v[14:15], off offset:80
	global_load_dwordx4 v[220:223], v16, s[2:3] offset:160
	global_load_dwordx2 v[166:167], v[14:15], off offset:96
	global_load_dwordx4 v[224:227], v16, s[2:3] offset:192
	global_load_dwordx2 v[168:169], v[14:15], off offset:112
	global_load_dwordx4 v[228:231], v16, s[2:3] offset:224
	v_and_b32_e32 v7, 0xffff0000, v4
	v_lshlrev_b32_e32 v8, 16, v5
	v_and_b32_e32 v9, 0xffff0000, v5
	v_mul_f32_e32 v4, 0xbfb8aa3b, v6
	v_mul_f32_e32 v5, 0xbfb8aa3b, v7
	v_exp_f32_e32 v4, v4
	v_exp_f32_e32 v5, v5
	s_nop 0
	v_pk_add_f32 v[4:5], v[4:5], 1.0 op_sel_hi:[1,0]
	s_nop 0
	v_div_scale_f32 v6, s[0:1], v5, v5, 1.0
	v_rcp_f32_e32 v7, v6
	s_nop 0
	v_fma_f32 v10, -v6, v7, 1.0
	v_fmac_f32_e32 v7, v10, v7
	v_div_scale_f32 v10, vcc, 1.0, v5, 1.0
	v_mul_f32_e32 v11, v10, v7
	v_fma_f32 v12, -v6, v11, v10
	v_fmac_f32_e32 v11, v12, v7
	v_fma_f32 v6, -v6, v11, v10
	v_div_fmas_f32 v6, v6, v7, v11
	v_div_fixup_f32 v5, v6, v5, 1.0
	v_div_scale_f32 v6, s[0:1], v4, v4, 1.0
	v_rcp_f32_e32 v7, v6
	s_nop 0
	v_fma_f32 v10, -v6, v7, 1.0
	v_fmac_f32_e32 v7, v10, v7
	v_div_scale_f32 v10, vcc, 1.0, v4, 1.0
	v_mul_f32_e32 v11, v10, v7
	v_fma_f32 v12, -v6, v11, v10
	v_fmac_f32_e32 v11, v12, v7
	v_fma_f32 v6, -v6, v11, v10
	v_div_fmas_f32 v6, v6, v7, v11
	v_div_fixup_f32 v4, v6, v4, 1.0
	v_pk_mul_f32 v[6:7], v[154:155], v[18:19] op_sel_hi:[1,0]
	s_waitcnt vmcnt(14)
	v_pk_mul_f32 v[0:1], v[0:1], v[6:7]
	s_nop 0
	v_pk_mul_f32 v[0:1], v[4:5], v[0:1]
	v_mul_f32_e32 v4, 0xbfb8aa3b, v8
	v_mul_f32_e32 v5, 0xbfb8aa3b, v9
	v_exp_f32_e32 v4, v4
	v_exp_f32_e32 v5, v5
	v_cvt_pk_bf16_f32 v0, v0, v1
	v_pk_add_f32 v[4:5], v[4:5], 1.0 op_sel_hi:[1,0]
	s_nop 0
	v_div_scale_f32 v6, s[0:1], v5, v5, 1.0
	v_rcp_f32_e32 v7, v6
	s_nop 0
	v_fma_f32 v8, -v6, v7, 1.0
	v_fmac_f32_e32 v7, v8, v7
	v_div_scale_f32 v8, vcc, 1.0, v5, 1.0
	v_mul_f32_e32 v9, v8, v7
	v_fma_f32 v10, -v6, v9, v8
	v_fmac_f32_e32 v9, v10, v7
	v_fma_f32 v6, -v6, v9, v8
	v_div_fmas_f32 v6, v6, v7, v9
	v_div_fixup_f32 v5, v6, v5, 1.0
	v_div_scale_f32 v6, s[0:1], v4, v4, 1.0
	v_rcp_f32_e32 v7, v6
	s_nop 0
	v_fma_f32 v8, -v6, v7, 1.0
	v_fmac_f32_e32 v7, v8, v7
	v_div_scale_f32 v8, vcc, 1.0, v4, 1.0
	v_mul_f32_e32 v9, v8, v7
	v_fma_f32 v10, -v6, v9, v8
	v_fmac_f32_e32 v9, v10, v7
	v_fma_f32 v6, -v6, v9, v8
	v_div_fmas_f32 v6, v6, v7, v9
	v_div_fixup_f32 v4, v6, v4, 1.0
	v_pk_mul_f32 v[6:7], v[146:147], v[18:19] op_sel_hi:[1,0]
	s_nop 0
	v_pk_mul_f32 v[2:3], v[2:3], v[6:7]
	s_nop 0
	v_pk_mul_f32 v[2:3], v[4:5], v[2:3]
	s_nop 0
	v_cvt_pk_bf16_f32 v1, v2, v3
	s_waitcnt vmcnt(13)
; DI unsigned pk2(float lo, float hi) { f32x2 v = {lo, hi}; bf2_t r = __builtin_convertvector(v, bf2_t); return __builtin_bit_cast(unsigned, r); }
; DI float bflo(unsigned u) { return __uint_as_float(u << 16); }
; DI float bfhi(unsigned u) { return __uint_as_float(u & 0xffff0000u); }
; DI void mlstm_out_item(const KP& P, int layer, int b, int tb, LAS unsigned char* lds) {
;     ...
; #pragma unroll
;     for (int nt = 0; nt < 2; ++nt)
; #pragma unroll
;         for (int g4 = 0; g4 < 4; ++g4) { const int dv = 32 * nt + 8 * g4 + 4 * h;
;             const u32x2 ov = ldg8(Z + (R0 + t) * ZW + C_OD + hd * 64 + dv); const f32x4 gg = *(const f32x4*)(P.g_mlstm_out + layer * 64 + dv);
;             const float oo[4] = {bflo(ov.x), bfhi(ov.x), bflo(ov.y), bfhi(ov.y)}; float y[4];
; #pragma unroll
;             for (int e = 0; e < 4; ++e) { const float sg = 1.f / (1.f + __expf(-oo[e])); y[e] = hs[nt][4 * g4 + e] * rstd * gg[e] * sg; }
;             og[4 * nt + g4].x = pk2(y[0], y[1]); og[4 * nt + g4].y = pk2(y[2], y[3]); }
	v_mov_b32_e32 v6, v156
	v_mov_b32_e32 v7, v157
	s_nop 0
	s_nop 0
	v_lshlrev_b32_e32 v8, 16, v6
	v_and_b32_e32 v9, 0xffff0000, v6
	v_lshlrev_b32_e32 v10, 16, v7
	v_and_b32_e32 v11, 0xffff0000, v7
	v_mul_f32_e32 v6, 0xbfb8aa3b, v8
	v_mul_f32_e32 v7, 0xbfb8aa3b, v9
	v_exp_f32_e32 v6, v6
	v_exp_f32_e32 v7, v7
	s_nop 0
	v_pk_add_f32 v[6:7], v[6:7], 1.0 op_sel_hi:[1,0]
	s_nop 0
	v_div_scale_f32 v8, s[0:1], v7, v7, 1.0
	v_rcp_f32_e32 v9, v8
	s_nop 0
	v_fma_f32 v12, -v8, v9, 1.0
	v_fmac_f32_e32 v9, v12, v9
	v_div_scale_f32 v12, vcc, 1.0, v7, 1.0
	v_mul_f32_e32 v13, v12, v9
	v_fma_f32 v17, -v8, v13, v12
	v_fmac_f32_e32 v13, v17, v9
	v_fma_f32 v8, -v8, v13, v12
	v_div_fmas_f32 v8, v8, v9, v13
	v_div_fixup_f32 v7, v8, v7, 1.0
	v_div_scale_f32 v8, s[0:1], v6, v6, 1.0
	v_rcp_f32_e32 v9, v8
	s_nop 0
	v_fma_f32 v12, -v8, v9, 1.0
	v_fmac_f32_e32 v9, v12, v9
	v_div_scale_f32 v12, vcc, 1.0, v6, 1.0
	v_mul_f32_e32 v13, v12, v9
	v_fma_f32 v17, -v8, v13, v12
	v_fmac_f32_e32 v13, v17, v9
	v_fma_f32 v8, -v8, v13, v12
	v_div_fmas_f32 v8, v8, v9, v13
	v_div_fixup_f32 v6, v8, v6, 1.0
	v_pk_mul_f32 v[8:9], v[142:143], v[18:19] op_sel_hi:[1,0]
	s_waitcnt vmcnt(12)
	v_mov_b32_e32 v2, v204
	v_mov_b32_e32 v3, v205
	v_mov_b32_e32 v4, v206
	v_mov_b32_e32 v5, v207
	v_pk_mul_f32 v[2:3], v[2:3], v[8:9]
	s_nop 0
	v_pk_mul_f32 v[2:3], v[6:7], v[2:3]
	v_mul_f32_e32 v6, 0xbfb8aa3b, v10
	v_mul_f32_e32 v7, 0xbfb8aa3b, v11
	v_exp_f32_e32 v6, v6
	v_exp_f32_e32 v7, v7
	v_cvt_pk_bf16_f32 v2, v2, v3
	s_nop 1
	v_permlane32_swap_b32_e32 v0, v2
	v_pk_add_f32 v[6:7], v[6:7], 1.0 op_sel_hi:[1,0]
	s_nop 0
	v_div_scale_f32 v8, s[0:1], v7, v7, 1.0
	v_rcp_f32_e32 v9, v8
	s_nop 0
	v_fma_f32 v10, -v8, v9, 1.0
	v_fmac_f32_e32 v9, v10, v9
	v_div_scale_f32 v10, vcc, 1.0, v7, 1.0
	v_mul_f32_e32 v11, v10, v9
	v_fma_f32 v12, -v8, v11, v10
	v_fmac_f32_e32 v11, v12, v9
	v_fma_f32 v8, -v8, v11, v10
	v_div_fmas_f32 v8, v8, v9, v11
	v_div_fixup_f32 v7, v8, v7, 1.0
	v_div_scale_f32 v8, s[0:1], v6, v6, 1.0
	v_rcp_f32_e32 v9, v8
	s_nop 0
	v_fma_f32 v10, -v8, v9, 1.0
	v_fmac_f32_e32 v9, v10, v9
	v_div_scale_f32 v10, vcc, 1.0, v6, 1.0
	v_mul_f32_e32 v11, v10, v9
	v_fma_f32 v12, -v8, v11, v10
	v_fmac_f32_e32 v11, v12, v9
	v_fma_f32 v8, -v8, v11, v10
	v_div_fmas_f32 v8, v8, v9, v11
	v_div_fixup_f32 v6, v8, v6, 1.0
	v_pk_mul_f32 v[8:9], v[140:141], v[18:19] op_sel_hi:[1,0]
	s_nop 0
	v_pk_mul_f32 v[4:5], v[4:5], v[8:9]
	s_nop 0
	v_pk_mul_f32 v[4:5], v[6:7], v[4:5]
	s_nop 0
	v_cvt_pk_bf16_f32 v3, v4, v5
	s_waitcnt vmcnt(11)
	v_mov_b32_e32 v8, v158
	v_mov_b32_e32 v9, v159
	s_nop 0
	v_permlane32_swap_b32_e32 v1, v3
	s_nop 0
	v_lshlrev_b32_e32 v10, 16, v8
	v_and_b32_e32 v11, 0xffff0000, v8
	v_lshlrev_b32_e32 v12, 16, v9
	v_and_b32_e32 v13, 0xffff0000, v9
	v_mul_f32_e32 v8, 0xbfb8aa3b, v10
	v_mul_f32_e32 v9, 0xbfb8aa3b, v11
	v_exp_f32_e32 v8, v8
	v_exp_f32_e32 v9, v9
	s_nop 0
	v_pk_add_f32 v[8:9], v[8:9], 1.0 op_sel_hi:[1,0]
	s_nop 0
	v_div_scale_f32 v10, s[0:1], v9, v9, 1.0
	v_rcp_f32_e32 v11, v10
	s_nop 0
	v_fma_f32 v17, -v10, v11, 1.0
	v_fmac_f32_e32 v11, v17, v11
	v_div_scale_f32 v17, vcc, 1.0, v9, 1.0
	v_mul_f32_e32 v19, v17, v11
	v_fma_f32 v22, -v10, v19, v17
	v_fmac_f32_e32 v19, v22, v11
	v_fma_f32 v10, -v10, v19, v17
	v_div_fmas_f32 v10, v10, v11, v19
	v_div_fixup_f32 v9, v10, v9, 1.0
	v_div_scale_f32 v10, s[0:1], v8, v8, 1.0
	v_rcp_f32_e32 v11, v10
	s_nop 0
	v_fma_f32 v17, -v10, v11, 1.0
	v_fmac_f32_e32 v11, v17, v11
	v_div_scale_f32 v17, vcc, 1.0, v8, 1.0
	v_mul_f32_e32 v19, v17, v11
	v_fma_f32 v22, -v10, v19, v17
	v_fmac_f32_e32 v19, v22, v11
	v_fma_f32 v10, -v10, v19, v17
	v_div_fmas_f32 v10, v10, v11, v19
	v_div_fixup_f32 v8, v10, v8, 1.0
	v_pk_mul_f32 v[10:11], v[138:139], v[18:19] op_sel_hi:[1,0]
	s_waitcnt vmcnt(10)
	v_mov_b32_e32 v4, v208
	v_mov_b32_e32 v5, v209
	v_mov_b32_e32 v6, v210
	v_mov_b32_e32 v7, v211
	v_pk_mul_f32 v[4:5], v[4:5], v[10:11]
	s_nop 0
	v_pk_mul_f32 v[4:5], v[4:5], v[8:9]
	v_mul_f32_e32 v8, 0xbfb8aa3b, v12
	v_mul_f32_e32 v9, 0xbfb8aa3b, v13
	v_exp_f32_e32 v8, v8
	v_exp_f32_e32 v9, v9
	v_cvt_pk_bf16_f32 v4, v4, v5
	v_pk_add_f32 v[8:9], v[8:9], 1.0 op_sel_hi:[1,0]
	s_nop 0
	v_div_scale_f32 v10, s[0:1], v9, v9, 1.0
	v_rcp_f32_e32 v11, v10
	s_nop 0
	v_fma_f32 v12, -v10, v11, 1.0
	v_fmac_f32_e32 v11, v12, v11
	v_div_scale_f32 v12, vcc, 1.0, v9, 1.0
	v_mul_f32_e32 v13, v12, v11
	v_fma_f32 v17, -v10, v13, v12
	v_fmac_f32_e32 v13, v17, v11
	v_fma_f32 v10, -v10, v13, v12
	v_div_fmas_f32 v10, v10, v11, v13
	v_div_fixup_f32 v9, v10, v9, 1.0
	v_div_scale_f32 v10, s[0:1], v8, v8, 1.0
	v_rcp_f32_e32 v11, v10
	s_nop 0
	v_fma_f32 v12, -v10, v11, 1.0
	v_fmac_f32_e32 v11, v12, v11
	v_div_scale_f32 v12, vcc, 1.0, v8, 1.0
	v_mul_f32_e32 v13, v12, v11
	v_fma_f32 v17, -v10, v13, v12
	v_fmac_f32_e32 v13, v17, v11
	v_fma_f32 v10, -v10, v13, v12
	v_div_fmas_f32 v10, v10, v11, v13
	v_div_fixup_f32 v8, v10, v8, 1.0
	v_pk_mul_f32 v[10:11], v[136:137], v[18:19] op_sel_hi:[1,0]
	s_nop 0
	v_pk_mul_f32 v[6:7], v[6:7], v[10:11]
	s_nop 0
	v_pk_mul_f32 v[6:7], v[6:7], v[8:9]
	s_nop 0
	v_cvt_pk_bf16_f32 v5, v6, v7
	s_waitcnt vmcnt(9)
; DI unsigned pk2(float lo, float hi) { f32x2 v = {lo, hi}; bf2_t r = __builtin_convertvector(v, bf2_t); return __builtin_bit_cast(unsigned, r); }
; DI float bflo(unsigned u) { return __uint_as_float(u << 16); }
; DI float bfhi(unsigned u) { return __uint_as_float(u & 0xffff0000u); }
; DI void mlstm_out_item(const KP& P, int layer, int b, int tb, LAS unsigned char* lds) {
;     ...
; #pragma unroll
;     for (int nt = 0; nt < 2; ++nt)
; #pragma unroll
;         for (int g4 = 0; g4 < 4; ++g4) { const int dv = 32 * nt + 8 * g4 + 4 * h;
;             const u32x2 ov = ldg8(Z + (R0 + t) * ZW + C_OD + hd * 64 + dv); const f32x4 gg = *(const f32x4*)(P.g_mlstm_out + layer * 64 + dv);
;             const float oo[4] = {bflo(ov.x), bfhi(ov.x), bflo(ov.y), bfhi(ov.y)}; float y[4];
; #pragma unroll
;             for (int e = 0; e < 4; ++e) { const float sg = 1.f / (1.f + __expf(-oo[e])); y[e] = hs[nt][4 * g4 + e] * rstd * gg[e] * sg; }
;             og[4 * nt + g4].x = pk2(y[0], y[1]); og[4 * nt + g4].y = pk2(y[2], y[3]); }
	v_mov_b32_e32 v10, v160
	v_mov_b32_e32 v11, v161
	s_nop 0
	s_nop 0
	v_lshlrev_b32_e32 v12, 16, v10
	v_and_b32_e32 v13, 0xffff0000, v10
	v_lshlrev_b32_e32 v17, 16, v11
	v_and_b32_e32 v19, 0xffff0000, v11
	v_mul_f32_e32 v10, 0xbfb8aa3b, v12
	v_mul_f32_e32 v11, 0xbfb8aa3b, v13
	v_exp_f32_e32 v10, v10
	v_exp_f32_e32 v11, v11
	s_nop 0
	v_pk_add_f32 v[10:11], v[10:11], 1.0 op_sel_hi:[1,0]
	s_nop 0
	v_div_scale_f32 v12, s[0:1], v11, v11, 1.0
	v_rcp_f32_e32 v13, v12
	s_nop 0
	v_fma_f32 v22, -v12, v13, 1.0
	v_fmac_f32_e32 v13, v22, v13
	v_div_scale_f32 v22, vcc, 1.0, v11, 1.0
	v_mul_f32_e32 v23, v22, v13
	v_fma_f32 v24, -v12, v23, v22
	v_fmac_f32_e32 v23, v24, v13
	v_fma_f32 v12, -v12, v23, v22
	v_div_fmas_f32 v12, v12, v13, v23
	v_div_fixup_f32 v11, v12, v11, 1.0
	v_div_scale_f32 v12, s[0:1], v10, v10, 1.0
	v_rcp_f32_e32 v13, v12
	s_nop 0
	v_fma_f32 v22, -v12, v13, 1.0
	v_fmac_f32_e32 v13, v22, v13
	v_div_scale_f32 v22, vcc, 1.0, v10, 1.0
	v_mul_f32_e32 v23, v22, v13
	v_fma_f32 v24, -v12, v23, v22
	v_fmac_f32_e32 v23, v24, v13
	v_fma_f32 v12, -v12, v23, v22
	v_div_fmas_f32 v12, v12, v13, v23
	v_div_fixup_f32 v10, v12, v10, 1.0
	v_pk_mul_f32 v[12:13], v[134:135], v[18:19] op_sel_hi:[1,0]
	s_waitcnt vmcnt(8)
	v_mov_b32_e32 v6, v212
	v_mov_b32_e32 v7, v213
	v_mov_b32_e32 v8, v214
	v_mov_b32_e32 v9, v215
	v_pk_mul_f32 v[6:7], v[6:7], v[12:13]
	s_nop 0
	v_pk_mul_f32 v[6:7], v[6:7], v[10:11]
	v_mul_f32_e32 v10, 0xbfb8aa3b, v17
	v_mul_f32_e32 v11, 0xbfb8aa3b, v19
	v_exp_f32_e32 v10, v10
	v_exp_f32_e32 v11, v11
	v_cvt_pk_bf16_f32 v6, v6, v7
	s_nop 1
	v_permlane32_swap_b32_e32 v4, v6
	v_pk_add_f32 v[10:11], v[10:11], 1.0 op_sel_hi:[1,0]
	s_nop 0
	v_div_scale_f32 v12, s[0:1], v11, v11, 1.0
	v_rcp_f32_e32 v13, v12
	s_nop 0
	v_fma_f32 v17, -v12, v13, 1.0
	v_fmac_f32_e32 v13, v17, v13
	v_div_scale_f32 v17, vcc, 1.0, v11, 1.0
	v_mul_f32_e32 v19, v17, v13
	v_fma_f32 v22, -v12, v19, v17
	v_fmac_f32_e32 v19, v22, v13
	v_fma_f32 v12, -v12, v19, v17
	v_div_fmas_f32 v12, v12, v13, v19
	v_div_fixup_f32 v11, v12, v11, 1.0
	v_div_scale_f32 v12, s[0:1], v10, v10, 1.0
	v_rcp_f32_e32 v13, v12
	s_nop 0
	v_fma_f32 v17, -v12, v13, 1.0
	v_fmac_f32_e32 v13, v17, v13
	v_div_scale_f32 v17, vcc, 1.0, v10, 1.0
	v_mul_f32_e32 v19, v17, v13
	v_fma_f32 v22, -v12, v19, v17
	v_fmac_f32_e32 v19, v22, v13
	v_fma_f32 v12, -v12, v19, v17
	v_div_fmas_f32 v12, v12, v13, v19
	v_div_fixup_f32 v10, v12, v10, 1.0
	v_pk_mul_f32 v[12:13], v[132:133], v[18:19] op_sel_hi:[1,0]
	s_nop 0
	v_pk_mul_f32 v[8:9], v[8:9], v[12:13]
	s_nop 0
	v_pk_mul_f32 v[8:9], v[8:9], v[10:11]
	s_nop 0
	v_cvt_pk_bf16_f32 v7, v8, v9
	s_waitcnt vmcnt(7)
	v_mov_b32_e32 v12, v162
	v_mov_b32_e32 v13, v163
	s_nop 0
	v_permlane32_swap_b32_e32 v5, v7
	s_nop 0
	v_lshlrev_b32_e32 v17, 16, v12
	v_and_b32_e32 v19, 0xffff0000, v12
	v_lshlrev_b32_e32 v24, 16, v13
	v_and_b32_e32 v25, 0xffff0000, v13
	v_mul_f32_e32 v12, 0xbfb8aa3b, v17
	v_mul_f32_e32 v13, 0xbfb8aa3b, v19
	v_exp_f32_e32 v12, v12
	v_exp_f32_e32 v13, v13
	s_nop 0
	v_pk_add_f32 v[12:13], v[12:13], 1.0 op_sel_hi:[1,0]
	s_nop 0
	v_div_scale_f32 v17, s[0:1], v13, v13, 1.0
	v_rcp_f32_e32 v19, v17
	s_nop 0
	v_fma_f32 v22, -v17, v19, 1.0
	v_fmac_f32_e32 v19, v22, v19
	v_div_scale_f32 v22, vcc, 1.0, v13, 1.0
	v_mul_f32_e32 v23, v22, v19
	v_fma_f32 v26, -v17, v23, v22
	v_fmac_f32_e32 v23, v26, v19
	v_fma_f32 v17, -v17, v23, v22
	v_div_fmas_f32 v17, v17, v19, v23
	v_div_fixup_f32 v13, v17, v13, 1.0
	v_div_scale_f32 v17, s[0:1], v12, v12, 1.0
	v_rcp_f32_e32 v19, v17
	s_nop 0
	v_fma_f32 v22, -v17, v19, 1.0
	v_fmac_f32_e32 v19, v22, v19
	v_div_scale_f32 v22, vcc, 1.0, v12, 1.0
	v_mul_f32_e32 v23, v22, v19
	v_fma_f32 v26, -v17, v23, v22
	v_fmac_f32_e32 v23, v26, v19
	v_fma_f32 v17, -v17, v23, v22
	v_div_fmas_f32 v17, v17, v19, v23
	v_pk_mul_f32 v[22:23], v[130:131], v[18:19] op_sel_hi:[1,0]
	v_div_fixup_f32 v12, v17, v12, 1.0
	s_waitcnt vmcnt(6)
	v_mov_b32_e32 v8, v216
	v_mov_b32_e32 v9, v217
	v_mov_b32_e32 v10, v218
	v_mov_b32_e32 v11, v219
	v_pk_mul_f32 v[8:9], v[22:23], v[8:9]
	s_nop 0
	v_pk_mul_f32 v[8:9], v[8:9], v[12:13]
	v_mul_f32_e32 v12, 0xbfb8aa3b, v24
	v_mul_f32_e32 v13, 0xbfb8aa3b, v25
	v_exp_f32_e32 v12, v12
	v_exp_f32_e32 v13, v13
	v_cvt_pk_bf16_f32 v8, v8, v9
	v_pk_add_f32 v[12:13], v[12:13], 1.0 op_sel_hi:[1,0]
	s_nop 0
	v_div_scale_f32 v17, s[0:1], v13, v13, 1.0
	v_rcp_f32_e32 v19, v17
	s_nop 0
	v_fma_f32 v22, -v17, v19, 1.0
	v_fmac_f32_e32 v19, v22, v19
	v_div_scale_f32 v22, vcc, 1.0, v13, 1.0
	v_mul_f32_e32 v23, v22, v19
	v_fma_f32 v24, -v17, v23, v22
	v_fmac_f32_e32 v23, v24, v19
	v_fma_f32 v17, -v17, v23, v22
	v_div_fmas_f32 v17, v17, v19, v23
	v_div_fixup_f32 v13, v17, v13, 1.0
	v_div_scale_f32 v17, s[0:1], v12, v12, 1.0
	v_rcp_f32_e32 v19, v17
	s_nop 0
	v_fma_f32 v22, -v17, v19, 1.0
	v_fmac_f32_e32 v19, v22, v19
	v_div_scale_f32 v22, vcc, 1.0, v12, 1.0
	v_mul_f32_e32 v23, v22, v19
	v_fma_f32 v24, -v17, v23, v22
	v_fmac_f32_e32 v23, v24, v19
	v_fma_f32 v17, -v17, v23, v22
	v_div_fmas_f32 v17, v17, v19, v23
	v_pk_mul_f32 v[22:23], v[128:129], v[18:19] op_sel_hi:[1,0]
	v_div_fixup_f32 v12, v17, v12, 1.0
	v_pk_mul_f32 v[10:11], v[22:23], v[10:11]
	s_nop 0
	v_pk_mul_f32 v[10:11], v[10:11], v[12:13]
	s_nop 0
	v_cvt_pk_bf16_f32 v9, v10, v11
	s_waitcnt vmcnt(5)
; DI unsigned pk2(float lo, float hi) { f32x2 v = {lo, hi}; bf2_t r = __builtin_convertvector(v, bf2_t); return __builtin_bit_cast(unsigned, r); }
; DI float bflo(unsigned u) { return __uint_as_float(u << 16); }
; DI float bfhi(unsigned u) { return __uint_as_float(u & 0xffff0000u); }
; DI void mlstm_out_item(const KP& P, int layer, int b, int tb, LAS unsigned char* lds) {
;     ...
; #pragma unroll
;     for (int nt = 0; nt < 2; ++nt)
; #pragma unroll
;         for (int g4 = 0; g4 < 4; ++g4) { const int dv = 32 * nt + 8 * g4 + 4 * h;
;             const u32x2 ov = ldg8(Z + (R0 + t) * ZW + C_OD + hd * 64 + dv); const f32x4 gg = *(const f32x4*)(P.g_mlstm_out + layer * 64 + dv);
;             const float oo[4] = {bflo(ov.x), bfhi(ov.x), bflo(ov.y), bfhi(ov.y)}; float y[4];
; #pragma unroll
;             for (int e = 0; e < 4; ++e) { const float sg = 1.f / (1.f + __expf(-oo[e])); y[e] = hs[nt][4 * g4 + e] * rstd * gg[e] * sg; }
;             og[4 * nt + g4].x = pk2(y[0], y[1]); og[4 * nt + g4].y = pk2(y[2], y[3]); }
	v_mov_b32_e32 v22, v164
	v_mov_b32_e32 v23, v165
	s_nop 0
	s_nop 0
	v_lshlrev_b32_e32 v17, 16, v22
	v_and_b32_e32 v19, 0xffff0000, v22
	v_mul_f32_e32 v17, 0xbfb8aa3b, v17
	v_exp_f32_e32 v22, v17
	v_mul_f32_e32 v17, 0xbfb8aa3b, v19
	v_lshlrev_b32_e32 v26, 16, v23
	v_and_b32_e32 v27, 0xffff0000, v23
	v_exp_f32_e32 v23, v17
	s_nop 0
	v_pk_add_f32 v[22:23], v[22:23], 1.0 op_sel_hi:[1,0]
	s_nop 0
	v_div_scale_f32 v17, s[0:1], v23, v23, 1.0
	v_rcp_f32_e32 v19, v17
	s_nop 0
	v_fma_f32 v24, -v17, v19, 1.0
	v_fmac_f32_e32 v19, v24, v19
	v_div_scale_f32 v24, vcc, 1.0, v23, 1.0
	v_mul_f32_e32 v25, v24, v19
	v_fma_f32 v28, -v17, v25, v24
	v_fmac_f32_e32 v25, v28, v19
	v_fma_f32 v17, -v17, v25, v24
	v_div_fmas_f32 v17, v17, v19, v25
	v_div_fixup_f32 v23, v17, v23, 1.0
	v_div_scale_f32 v17, s[0:1], v22, v22, 1.0
	v_rcp_f32_e32 v19, v17
	s_nop 0
	v_fma_f32 v24, -v17, v19, 1.0
	v_fmac_f32_e32 v19, v24, v19
	v_div_scale_f32 v24, vcc, 1.0, v22, 1.0
	v_mul_f32_e32 v25, v24, v19
	v_fma_f32 v28, -v17, v25, v24
	v_fmac_f32_e32 v25, v28, v19
	v_fma_f32 v17, -v17, v25, v24
	v_div_fmas_f32 v17, v17, v19, v25
	v_pk_mul_f32 v[24:25], v[126:127], v[18:19] op_sel_hi:[1,0]
	v_div_fixup_f32 v22, v17, v22, 1.0
	s_waitcnt vmcnt(4)
	v_mov_b32_e32 v10, v220
	v_mov_b32_e32 v11, v221
	v_mov_b32_e32 v12, v222
	v_mov_b32_e32 v13, v223
	v_pk_mul_f32 v[10:11], v[24:25], v[10:11]
	v_mul_f32_e32 v17, 0xbfb8aa3b, v26
	v_pk_mul_f32 v[10:11], v[10:11], v[22:23]
	v_exp_f32_e32 v22, v17
	v_mul_f32_e32 v17, 0xbfb8aa3b, v27
	v_exp_f32_e32 v23, v17
	v_cvt_pk_bf16_f32 v10, v10, v11
	s_nop 1
	v_permlane32_swap_b32_e32 v8, v10
	v_pk_add_f32 v[22:23], v[22:23], 1.0 op_sel_hi:[1,0]
	s_nop 0
	v_div_scale_f32 v17, s[0:1], v23, v23, 1.0
	v_rcp_f32_e32 v19, v17
	s_nop 0
	v_fma_f32 v24, -v17, v19, 1.0
	v_fmac_f32_e32 v19, v24, v19
	v_div_scale_f32 v24, vcc, 1.0, v23, 1.0
	v_mul_f32_e32 v25, v24, v19
	v_fma_f32 v26, -v17, v25, v24
	v_fmac_f32_e32 v25, v26, v19
	v_fma_f32 v17, -v17, v25, v24
	v_div_fmas_f32 v17, v17, v19, v25
	v_div_fixup_f32 v23, v17, v23, 1.0
	v_div_scale_f32 v17, s[0:1], v22, v22, 1.0
	v_rcp_f32_e32 v19, v17
	s_nop 0
	v_fma_f32 v24, -v17, v19, 1.0
	v_fmac_f32_e32 v19, v24, v19
	v_div_scale_f32 v24, vcc, 1.0, v22, 1.0
	v_mul_f32_e32 v25, v24, v19
	v_fma_f32 v26, -v17, v25, v24
	v_fmac_f32_e32 v25, v26, v19
	v_fma_f32 v17, -v17, v25, v24
	v_div_fmas_f32 v17, v17, v19, v25
	v_pk_mul_f32 v[24:25], v[124:125], v[18:19] op_sel_hi:[1,0]
	v_div_fixup_f32 v22, v17, v22, 1.0
	v_pk_mul_f32 v[12:13], v[24:25], v[12:13]
	s_nop 0
	v_pk_mul_f32 v[12:13], v[12:13], v[22:23]
	s_nop 0
	v_cvt_pk_bf16_f32 v11, v12, v13
	s_waitcnt vmcnt(3)
	v_mov_b32_e32 v12, v166
	v_mov_b32_e32 v13, v167
	s_nop 0
	v_permlane32_swap_b32_e32 v9, v11
	s_nop 0
	v_lshlrev_b32_e32 v17, 16, v12
	v_and_b32_e32 v19, 0xffff0000, v12
	v_lshlrev_b32_e32 v28, 16, v13
	v_and_b32_e32 v29, 0xffff0000, v13
	v_mul_f32_e32 v12, 0xbfb8aa3b, v17
	v_mul_f32_e32 v13, 0xbfb8aa3b, v19
	v_exp_f32_e32 v12, v12
	v_exp_f32_e32 v13, v13
	s_nop 0
	v_pk_add_f32 v[12:13], v[12:13], 1.0 op_sel_hi:[1,0]
	s_nop 0
	v_div_scale_f32 v17, s[0:1], v13, v13, 1.0
	v_rcp_f32_e32 v19, v17
	s_nop 0
	v_fma_f32 v26, -v17, v19, 1.0
	v_fmac_f32_e32 v19, v26, v19
	v_div_scale_f32 v26, vcc, 1.0, v13, 1.0
	v_mul_f32_e32 v27, v26, v19
	v_fma_f32 v30, -v17, v27, v26
	v_fmac_f32_e32 v27, v30, v19
	v_fma_f32 v17, -v17, v27, v26
	v_div_fmas_f32 v17, v17, v19, v27
	v_div_fixup_f32 v13, v17, v13, 1.0
	v_div_scale_f32 v17, s[0:1], v12, v12, 1.0
	v_rcp_f32_e32 v19, v17
	s_nop 0
	v_fma_f32 v26, -v17, v19, 1.0
	v_fmac_f32_e32 v19, v26, v19
	v_div_scale_f32 v26, vcc, 1.0, v12, 1.0
	v_mul_f32_e32 v27, v26, v19
	v_fma_f32 v30, -v17, v27, v26
	v_fmac_f32_e32 v27, v30, v19
	v_fma_f32 v17, -v17, v27, v26
	v_div_fmas_f32 v17, v17, v19, v27
	v_pk_mul_f32 v[26:27], v[122:123], v[18:19] op_sel_hi:[1,0]
	v_div_fixup_f32 v12, v17, v12, 1.0
	s_waitcnt vmcnt(2)
; DI unsigned pk2(float lo, float hi) { f32x2 v = {lo, hi}; bf2_t r = __builtin_convertvector(v, bf2_t); return __builtin_bit_cast(unsigned, r); }
; DI float bflo(unsigned u) { return __uint_as_float(u << 16); }
; DI float bfhi(unsigned u) { return __uint_as_float(u & 0xffff0000u); }
; DI void mlstm_out_item(const KP& P, int layer, int b, int tb, LAS unsigned char* lds) {
;     ...
; #pragma unroll
;     for (int nt = 0; nt < 2; ++nt)
; #pragma unroll
;         for (int g4 = 0; g4 < 4; ++g4) { const int dv = 32 * nt + 8 * g4 + 4 * h;
;             const u32x2 ov = ldg8(Z + (R0 + t) * ZW + C_OD + hd * 64 + dv); const f32x4 gg = *(const f32x4*)(P.g_mlstm_out + layer * 64 + dv);
;             const float oo[4] = {bflo(ov.x), bfhi(ov.x), bflo(ov.y), bfhi(ov.y)}; float y[4];
; #pragma unroll
;             for (int e = 0; e < 4; ++e) { const float sg = 1.f / (1.f + __expf(-oo[e])); y[e] = hs[nt][4 * g4 + e] * rstd * gg[e] * sg; }
;             og[4 * nt + g4].x = pk2(y[0], y[1]); og[4 * nt + g4].y = pk2(y[2], y[3]); }
;     store_row8(O + (R0 + t) * D + 768 + hd * 64, og, h);
;     __syncthreads();
	v_mov_b32_e32 v22, v224
	v_mov_b32_e32 v23, v225
	v_mov_b32_e32 v24, v226
	v_mov_b32_e32 v25, v227
	v_pk_mul_f32 v[22:23], v[26:27], v[22:23]
	v_mul_f32_e32 v17, 0xbfb8aa3b, v28
	v_pk_mul_f32 v[12:13], v[22:23], v[12:13]
	v_exp_f32_e32 v22, v17
	v_mul_f32_e32 v17, 0xbfb8aa3b, v29
	v_exp_f32_e32 v23, v17
	v_cvt_pk_bf16_f32 v12, v12, v13
	v_pk_add_f32 v[22:23], v[22:23], 1.0 op_sel_hi:[1,0]
	s_nop 0
	v_div_scale_f32 v17, s[0:1], v23, v23, 1.0
	v_rcp_f32_e32 v19, v17
	s_nop 0
	v_fma_f32 v26, -v17, v19, 1.0
	v_fmac_f32_e32 v19, v26, v19
	v_div_scale_f32 v26, vcc, 1.0, v23, 1.0
	v_mul_f32_e32 v27, v26, v19
	v_fma_f32 v28, -v17, v27, v26
	v_fmac_f32_e32 v27, v28, v19
	v_fma_f32 v17, -v17, v27, v26
	v_div_fmas_f32 v17, v17, v19, v27
	v_div_fixup_f32 v23, v17, v23, 1.0
	v_div_scale_f32 v17, s[0:1], v22, v22, 1.0
	v_rcp_f32_e32 v19, v17
	s_nop 0
	v_fma_f32 v26, -v17, v19, 1.0
	v_fmac_f32_e32 v19, v26, v19
	v_div_scale_f32 v26, vcc, 1.0, v22, 1.0
	v_mul_f32_e32 v27, v26, v19
	v_fma_f32 v28, -v17, v27, v26
	v_fmac_f32_e32 v27, v28, v19
	v_fma_f32 v17, -v17, v27, v26
	v_div_fmas_f32 v17, v17, v19, v27
	v_pk_mul_f32 v[26:27], v[120:121], v[18:19] op_sel_hi:[1,0]
	v_div_fixup_f32 v22, v17, v22, 1.0
	v_pk_mul_f32 v[24:25], v[26:27], v[24:25]
	s_nop 0
	v_pk_mul_f32 v[22:23], v[24:25], v[22:23]
	s_nop 0
	v_cvt_pk_bf16_f32 v13, v22, v23
	s_waitcnt vmcnt(1)
	v_mov_b32_e32 v22, v168
	v_mov_b32_e32 v23, v169
	s_nop 0
	s_nop 0
	v_readlane_b32 s2, v251, 3
	s_add_i32 s20, s20, s2
	s_nop 0
	v_lshlrev_b32_e32 v19, 16, v22
	v_and_b32_e32 v24, 0xffff0000, v22
	v_mul_f32_e32 v19, 0xbfb8aa3b, v19
	v_exp_f32_e32 v22, v19
	v_mul_f32_e32 v19, 0xbfb8aa3b, v24
	v_lshlrev_b32_e32 v26, 16, v23
	v_and_b32_e32 v27, 0xffff0000, v23
	v_exp_f32_e32 v23, v19
	s_nop 0
	v_pk_add_f32 v[22:23], v[22:23], 1.0 op_sel_hi:[1,0]
	s_nop 0
	v_div_scale_f32 v19, s[0:1], v23, v23, 1.0
	v_rcp_f32_e32 v24, v19
	s_nop 0
	v_fma_f32 v25, -v19, v24, 1.0
	v_fmac_f32_e32 v24, v25, v24
	v_div_scale_f32 v25, vcc, 1.0, v23, 1.0
	v_mul_f32_e32 v28, v25, v24
	v_fma_f32 v29, -v19, v28, v25
	v_fmac_f32_e32 v28, v29, v24
	v_fma_f32 v19, -v19, v28, v25
	v_div_fmas_f32 v19, v19, v24, v28
	v_div_fixup_f32 v23, v19, v23, 1.0
	v_div_scale_f32 v19, s[0:1], v22, v22, 1.0
	v_rcp_f32_e32 v24, v19
	s_nop 0
	v_fma_f32 v25, -v19, v24, 1.0
	v_fmac_f32_e32 v24, v25, v24
	v_div_scale_f32 v25, vcc, 1.0, v22, 1.0
	v_mul_f32_e32 v28, v25, v24
	v_fma_f32 v29, -v19, v28, v25
	v_fmac_f32_e32 v28, v29, v24
	v_fma_f32 v19, -v19, v28, v25
	v_div_fmas_f32 v19, v19, v24, v28
	v_pk_mul_f32 v[24:25], v[118:119], v[18:19] op_sel_hi:[1,0]
	v_div_fixup_f32 v22, v19, v22, 1.0
	s_waitcnt vmcnt(0)
	v_mov_b32_e32 v14, v228
	v_mov_b32_e32 v15, v229
	v_mov_b32_e32 v16, v230
	v_mov_b32_e32 v17, v231
	v_pk_mul_f32 v[14:15], v[24:25], v[14:15]
	v_mul_f32_e32 v19, 0xbfb8aa3b, v26
	v_pk_mul_f32 v[14:15], v[14:15], v[22:23]
	v_exp_f32_e32 v22, v19
	v_mul_f32_e32 v19, 0xbfb8aa3b, v27
	v_exp_f32_e32 v23, v19
	v_cvt_pk_bf16_f32 v14, v14, v15
	s_nop 1
	v_permlane32_swap_b32_e32 v12, v14
	v_pk_add_f32 v[22:23], v[22:23], 1.0 op_sel_hi:[1,0]
	s_nop 0
	v_div_scale_f32 v19, s[0:1], v23, v23, 1.0
	v_rcp_f32_e32 v24, v19
	s_nop 0
	v_fma_f32 v25, -v19, v24, 1.0
	v_fmac_f32_e32 v24, v25, v24
	v_div_scale_f32 v25, vcc, 1.0, v23, 1.0
	v_mul_f32_e32 v26, v25, v24
	v_fma_f32 v27, -v19, v26, v25
	v_fmac_f32_e32 v26, v27, v24
	v_fma_f32 v19, -v19, v26, v25
	v_div_fmas_f32 v19, v19, v24, v26
	v_div_fixup_f32 v23, v19, v23, 1.0
	v_div_scale_f32 v19, s[0:1], v22, v22, 1.0
	v_rcp_f32_e32 v24, v19
	v_readlane_b32 s0, v251, 1
	v_readlane_b32 s1, v251, 2
	v_fma_f32 v25, -v19, v24, 1.0
	v_fmac_f32_e32 v24, v25, v24
	v_div_scale_f32 v25, vcc, 1.0, v22, 1.0
	v_mul_f32_e32 v26, v25, v24
	v_fma_f32 v27, -v19, v26, v25
	v_fmac_f32_e32 v26, v27, v24
	v_fma_f32 v19, -v19, v26, v25
	v_div_fmas_f32 v19, v19, v24, v26
	v_div_fixup_f32 v22, v19, v22, 1.0
	v_pk_mul_f32 v[18:19], v[116:117], v[18:19] op_sel_hi:[1,0]
	s_nop 0
	v_pk_mul_f32 v[16:17], v[18:19], v[16:17]
	s_nop 0
	v_pk_mul_f32 v[16:17], v[16:17], v[22:23]
	s_nop 0
	v_cvt_pk_bf16_f32 v15, v16, v17
	v_lshlrev_b64 v[16:17], 11, v[20:21]
	v_lshl_add_u64 v[16:17], s[0:1], 0, v[16:17]
	v_lshl_add_u64 v[16:17], v[16:17], 0, v[112:113]
	v_lshlrev_b32_e32 v112, 1, v114
	v_lshl_add_u64 v[16:17], v[16:17], 0, v[112:113]
	s_mov_b64 s[0:1], 0x1046c600
	v_lshl_add_u64 v[18:19], v[16:17], 0, s[0:1]
	s_mov_b32 s0, 0x1046c000
	v_add_co_u32_e32 v16, vcc, s0, v16
	v_readlane_b32 s0, v255, 0
	s_nop 0
	v_addc_co_u32_e32 v17, vcc, 0, v17, vcc
	v_permlane32_swap_b32_e32 v13, v15
	s_cmp_ge_i32 s20, s0
	global_store_dwordx4 v[16:17], v[0:3], off offset:1536
	global_store_dwordx4 v[18:19], v[4:7], off offset:32
	global_store_dwordx4 v[18:19], v[8:11], off offset:64
	global_store_dwordx4 v[18:19], v[12:15], off offset:96
	s_barrier
	s_cbranch_scc1 .LBB0_610

; DI float bflo(unsigned u) { return __uint_as_float(u << 16); }
; DI float bfhi(unsigned u) { return __uint_as_float(u & 0xffff0000u); }
; DI int crow(int i, int h) { return (i & 3) + 8 * (i >> 2) + 4 * h; }
; #define MFMA32(a, b, c) __builtin_amdgcn_mfma_f32_32x32x16_bf16((a), (b), (c), 0, 0, 0)
; DI void mlstm_out_item(const KP& P, int layer, int b, int tb, LAS unsigned char* lds) {
;     ...
;         const int c = dir ? (tb < 4 ? 3 - tb : 71 - tb) : tb, chain = (b * 2 + dir) * 4 + hd, gi = dir * 4 + hd;
;         const bf16_t* sgp = SG + ((size_t)chain * NTB + c) * 4096 + (size_t)r * 64 + 8 * h;
;         f32x16 aI[2];
; #pragma unroll
;         for (int nt = 0; nt < 2; ++nt) { aI[nt] = zero16();
; #pragma unroll
;             for (int kk = 0; kk < 4; ++kk) aI[nt] = MFMA32(as_bf8(ldg16(sgp + nt * 2048 + 16 * kk)), Qf[kk], aI[nt]); }
;         const float* np = NP + ((size_t)chain * NTB + c) * 64;
;         float qn = 0.f;
; #pragma unroll
;         for (int kk = 0; kk < 4; ++kk) { const f32x4 n0 = *(const f32x4*)(np + 16 * kk + 8 * h), n1 = *(const f32x4*)(np + 16 * kk + 8 * h + 4); const u32x4 qv = __builtin_bit_cast(u32x4, Qf[kk]);
;             qn += bflo(qv.x) * n0[0] + bfhi(qv.x) * n0[1] + bflo(qv.y) * n0[2] + bfhi(qv.y) * n0[3] + bflo(qv.z) * n1[0] + bfhi(qv.z) * n1[1] + bflo(qv.w) * n1[2] + bfhi(qv.w) * n1[3]; }
;         qn += __shfl_xor(qn, 32);
;         const float Ft = Fs[t * 8 + gi];
;         float den = 0.f;
;         f32x16 aP[2]; aP[0] = zero16(); aP[1] = zero16();
; #pragma unroll
;         for (int jt = 0; jt < 2; ++jt) { f32x16 Pv;
; #pragma unroll
;             for (int i = 0; i < 16; ++i) { const int s = 32 * jt + crow(i, h); const bool keep = dir ? (s >= t) : (s <= t);
;                 const float as = As[s * 8 + gi];
;                 const float pe = keep ? S[jt][i] * (__expf(Ft + as) * 0.125f) : 0.f; Pv[i] = pe; den += pe; }
.LBB0_546:
	s_and_b64 vcc, s[2:3], exec
	v_readlane_b32 s37, v255, 5
	s_cselect_b32 s37, s37, s33
	s_ashr_i32 vcc_lo, s37, 31
	v_or_b32_e32 v34, s36, v160
	v_mov_b32_e32 v32, s37
	v_mov_b32_e32 v33, vcc_lo
	s_movk_i32 s37, 0x44
	v_mad_i64_i32 v[68:69], vcc, v34, s37, v[32:33]
	v_lshlrev_b64 v[32:33], 13, v[68:69]
	v_lshl_add_u64 v[36:37], v[156:157], 0, v[32:33]
	s_movk_i32 s37, 0x1000
	v_add_co_u32_e32 v70, vcc, s37, v36
	v_lshlrev_b64 v[152:153], 8, v[68:69]
	s_nop 0
	v_addc_co_u32_e32 v71, vcc, 0, v37, vcc
	v_lshl_add_u64 v[152:153], v[158:159], 0, v[152:153]
	global_load_dwordx4 v[192:195], v[36:37], off
	global_load_dwordx4 v[196:199], v[36:37], off offset:32
	global_load_dwordx4 v[224:227], v[36:37], off offset:64
	global_load_dwordx4 v[228:231], v[36:37], off offset:96
	global_load_dwordx4 v[232:235], v[70:71], off
	global_load_dwordx4 v[236:239], v[70:71], off offset:32
	global_load_dwordx4 v[240:243], v[70:71], off offset:64
	global_load_dwordx4 v[244:247], v[70:71], off offset:96
	global_load_dwordx4 v[68:71], v[152:153], off
	global_load_dwordx4 v[64:67], v[152:153], off offset:16
	global_load_dwordx4 v[76:79], v[152:153], off offset:64
	global_load_dwordx4 v[72:75], v[152:153], off offset:80
	global_load_dwordx4 v[84:87], v[152:153], off offset:128
	global_load_dwordx4 v[80:83], v[152:153], off offset:144
	global_load_dwordx4 v[92:95], v[152:153], off offset:192
	global_load_dwordx4 v[88:91], v[152:153], off offset:208
	v_mov_b32_e32 v222, 0
	s_waitcnt vmcnt(15)
	v_mfma_f32_32x32x16_bf16 v[48:63], v[192:195], v[96:99], 0
	s_waitcnt vmcnt(14)
	v_mfma_f32_32x32x16_bf16 v[48:63], v[196:199], v[100:103], v[48:63]
	s_waitcnt vmcnt(13)
	v_mfma_f32_32x32x16_bf16 v[48:63], v[224:227], v[104:107], v[48:63]
	s_waitcnt vmcnt(12)
	v_mfma_f32_32x32x16_bf16 v[48:63], v[228:231], v[108:111], v[48:63]
	s_waitcnt vmcnt(11)
	v_mfma_f32_32x32x16_bf16 v[32:47], v[232:235], v[96:99], 0
	s_waitcnt vmcnt(10)
	v_mfma_f32_32x32x16_bf16 v[32:47], v[236:239], v[100:103], v[32:47]
	s_waitcnt vmcnt(9)
	v_mfma_f32_32x32x16_bf16 v[32:47], v[240:243], v[104:107], v[32:47]
	s_waitcnt vmcnt(8)
	v_mfma_f32_32x32x16_bf16 v[32:47], v[244:247], v[108:111], v[32:47]
	s_waitcnt vmcnt(6)
	v_and_b32_e32 v219, 0xffff0000, v96
	v_mul_f32_e32 v149, v69, v219
	v_lshlrev_b32_e32 v219, 16, v96
	v_fmac_f32_e32 v149, v68, v219
	v_lshlrev_b32_e32 v219, 16, v97
	v_fmac_f32_e32 v149, v70, v219
	v_and_b32_e32 v219, 0xffff0000, v97
	v_fmac_f32_e32 v149, v71, v219
	v_lshlrev_b32_e32 v219, 16, v98
	v_fmac_f32_e32 v149, v64, v219
	v_and_b32_e32 v219, 0xffff0000, v98
	v_fmac_f32_e32 v149, v65, v219
	v_lshlrev_b32_e32 v219, 16, v99
	v_fmac_f32_e32 v149, v66, v219
	v_and_b32_e32 v219, 0xffff0000, v99
	v_fmac_f32_e32 v149, v67, v219
	v_add_f32_e32 v218, 0, v149
	s_waitcnt vmcnt(4)
	v_and_b32_e32 v219, 0xffff0000, v100
	v_mul_f32_e32 v149, v77, v219
	v_lshlrev_b32_e32 v219, 16, v100
	v_fmac_f32_e32 v149, v76, v219
	v_lshlrev_b32_e32 v219, 16, v101
	v_fmac_f32_e32 v149, v78, v219
	v_and_b32_e32 v219, 0xffff0000, v101
	v_fmac_f32_e32 v149, v79, v219
	v_lshlrev_b32_e32 v219, 16, v102
	v_fmac_f32_e32 v149, v72, v219
	v_and_b32_e32 v219, 0xffff0000, v102
	v_fmac_f32_e32 v149, v73, v219
	v_lshlrev_b32_e32 v219, 16, v103
	v_fmac_f32_e32 v149, v74, v219
	v_and_b32_e32 v219, 0xffff0000, v103
	v_fmac_f32_e32 v149, v75, v219
	v_add_f32_e32 v218, v218, v149
	s_waitcnt vmcnt(2)
	v_and_b32_e32 v219, 0xffff0000, v104
	v_mul_f32_e32 v149, v85, v219
	v_lshlrev_b32_e32 v219, 16, v104
	v_fmac_f32_e32 v149, v84, v219
	v_lshlrev_b32_e32 v219, 16, v105
	v_fmac_f32_e32 v149, v86, v219
	v_and_b32_e32 v219, 0xffff0000, v105
	v_fmac_f32_e32 v149, v87, v219
	v_lshlrev_b32_e32 v219, 16, v106
	v_fmac_f32_e32 v149, v80, v219
	v_and_b32_e32 v219, 0xffff0000, v106
	v_fmac_f32_e32 v149, v81, v219
	v_lshlrev_b32_e32 v219, 16, v107
	v_fmac_f32_e32 v149, v82, v219
	v_fmac_f32_e32 v149, v83, v163
	v_add_f32_e32 v218, v218, v149
	s_waitcnt vmcnt(0)
	v_mul_f32_e32 v149, v93, v165
	v_fmac_f32_e32 v149, v92, v164
	v_fmac_f32_e32 v149, v94, v166
	v_fmac_f32_e32 v149, v95, v167
	v_fmac_f32_e32 v149, v88, v168
	v_or_b32_e32 v64, s36, v145
	v_fmac_f32_e32 v149, v89, v169
	v_lshlrev_b32_e32 v64, 2, v64
	v_readlane_b32 s36, v254, 42
	v_fmac_f32_e32 v149, v90, v170
	v_fmac_f32_e32 v149, v91, v171
	v_add_u32_e32 v221, s36, v64
	v_readlane_b32 s36, v255, 10
	v_readlane_b32 s37, v255, 11
	v_add_f32_e32 v218, v218, v149
	v_add_u32_e32 v65, v161, v64
	v_cndmask_b32_e64 v64, 0, 1, s[36:37]
	v_readlane_b32 s36, v255, 8
	ds_bpermute_b32 v219, v112, v218
	ds_read_b32 v220, v65
	v_add_u32_e32 v66, v221, v172
	ds_read_b32 v222, v66
	v_add_u32_e32 v67, v221, v173
	ds_read_b32 v224, v67
	v_add_u32_e32 v68, v221, v174
	ds_read_b32 v223, v68
	v_add_u32_e32 v69, v221, v175
	ds_read_b32 v226, v69
	v_add_u32_e32 v70, v221, v176
	ds_read_b32 v225, v70
	v_add_u32_e32 v71, v221, v177
	ds_read_b32 v228, v71
	v_add_u32_e32 v72, v221, v178
	ds_read_b32 v227, v72
	v_add_u32_e32 v73, v221, v179
	ds_read_b32 v230, v73
	v_add_u32_e32 v74, v221, v180
	ds_read_b32 v229, v74
	v_add_u32_e32 v75, v221, v181
	ds_read_b32 v232, v75
	v_add_u32_e32 v76, v221, v182
	ds_read_b32 v231, v76
	v_add_u32_e32 v77, v221, v183
	ds_read_b32 v234, v77
	v_add_u32_e32 v78, v221, v184
	ds_read_b32 v233, v78
	v_add_u32_e32 v79, v221, v185
	ds_read_b32 v236, v79
	v_add_u32_e32 v80, v221, v186
	ds_read_b32 v235, v80
	v_add_u32_e32 v81, v221, v187
	ds_read_b32 v238, v81
	v_readlane_b32 s37, v255, 9
	s_nop 1
	v_cndmask_b32_e64 v65, 0, 1, s[36:37]
	v_cndmask_b32_e64 v64, v65, v64, s[2:3]
	v_and_b32_e32 v64, 1, v64
	v_cmp_eq_u32_e32 vcc, 1, v64
	s_waitcnt lgkmcnt(0)
	v_add_f32_e32 v64, v220, v222
	v_mov_b32_e32 v222, 0
	s_and_saveexec_b64 s[36:37], vcc
	s_cbranch_execz .LBB0_548
	v_mul_f32_e32 v64, 0x3fb8aa3b, v64
	v_exp_f32_e32 v64, v64
	s_nop 0
	v_mul_f32_e32 v64, 0x3e000000, v64
	v_mul_f32_e32 v222, v0, v64
; DI int crow(int i, int h) { return (i & 3) + 8 * (i >> 2) + 4 * h; }
; DI void mlstm_out_item(const KP& P, int layer, int b, int tb, LAS unsigned char* lds) {
;     ...
;         for (int jt = 0; jt < 2; ++jt) { f32x16 Pv;
; #pragma unroll
;             for (int i = 0; i < 16; ++i) { const int s = 32 * jt + crow(i, h); const bool keep = dir ? (s >= t) : (s <= t);
;                 const float as = As[s * 8 + gi];
;                 const float pe = keep ? S[jt][i] * (__expf(Ft + as) * 0.125f) : 0.f; Pv[i] = pe; den += pe; }
.LBB0_548:
	s_or_b64 exec, exec, s[36:37]
	v_readlane_b32 s36, v255, 14
	v_readlane_b32 s37, v255, 15
	v_cndmask_b32_e64 v64, 0, 1, s[36:37]
	v_readlane_b32 s36, v255, 12
	v_readlane_b32 s37, v255, 13
	s_nop 1
	v_cndmask_b32_e64 v65, 0, 1, s[36:37]
	v_cndmask_b32_e64 v64, v65, v64, s[2:3]
	v_and_b32_e32 v64, 1, v64
	v_cmp_eq_u32_e32 vcc, 1, v64
	v_add_f32_e32 v64, v220, v224
	v_mov_b32_e32 v224, 0
	s_and_saveexec_b64 s[36:37], vcc
	s_cbranch_execz .LBB0_550
	v_mul_f32_e32 v64, 0x3fb8aa3b, v64
	v_exp_f32_e32 v64, v64
	s_nop 0
	v_mul_f32_e32 v64, 0x3e000000, v64
	v_mul_f32_e32 v224, v1, v64
.LBB0_550:
	s_or_b64 exec, exec, s[36:37]
	v_readlane_b32 s36, v255, 18
	v_readlane_b32 s37, v255, 19
	s_nop 1
	v_cndmask_b32_e64 v64, 0, 1, s[36:37]
	v_readlane_b32 s36, v255, 16
	v_readlane_b32 s37, v255, 17
	s_nop 1
	v_cndmask_b32_e64 v65, 0, 1, s[36:37]
	v_cndmask_b32_e64 v64, v65, v64, s[2:3]
	v_and_b32_e32 v64, 1, v64
	v_cmp_eq_u32_e32 vcc, 1, v64
	v_add_f32_e32 v64, v220, v223
	v_mov_b32_e32 v223, 0
	s_and_saveexec_b64 s[36:37], vcc
	s_cbranch_execz .LBB0_552
	v_mul_f32_e32 v64, 0x3fb8aa3b, v64
	v_exp_f32_e32 v64, v64
	s_nop 0
	v_mul_f32_e32 v64, 0x3e000000, v64
	v_mul_f32_e32 v223, v2, v64
.LBB0_552:
	s_or_b64 exec, exec, s[36:37]
	v_readlane_b32 s36, v255, 22
	v_readlane_b32 s37, v255, 23
	v_cndmask_b32_e64 v64, 0, 1, s[36:37]
	v_readlane_b32 s36, v255, 20
	v_readlane_b32 s37, v255, 21
	s_nop 1
	v_cndmask_b32_e64 v65, 0, 1, s[36:37]
	v_cndmask_b32_e64 v64, v65, v64, s[2:3]
	v_and_b32_e32 v64, 1, v64
	v_cmp_eq_u32_e32 vcc, 1, v64
	v_add_f32_e32 v64, v220, v226
	v_mov_b32_e32 v226, 0
	s_and_saveexec_b64 s[36:37], vcc
	s_cbranch_execz .LBB0_554
	v_mul_f32_e32 v64, 0x3fb8aa3b, v64
	v_exp_f32_e32 v64, v64
	s_nop 0
	v_mul_f32_e32 v64, 0x3e000000, v64
	v_mul_f32_e32 v226, v3, v64
.LBB0_554:
	s_or_b64 exec, exec, s[36:37]
	v_readlane_b32 s36, v255, 26
	v_readlane_b32 s37, v255, 27
	s_nop 1
	v_cndmask_b32_e64 v64, 0, 1, s[36:37]
	v_readlane_b32 s36, v255, 24
	v_readlane_b32 s37, v255, 25
	s_nop 1
	v_cndmask_b32_e64 v65, 0, 1, s[36:37]
	v_cndmask_b32_e64 v64, v65, v64, s[2:3]
	v_and_b32_e32 v64, 1, v64
	v_cmp_eq_u32_e32 vcc, 1, v64
	v_add_f32_e32 v64, v220, v225
	v_mov_b32_e32 v225, 0
	s_and_saveexec_b64 s[36:37], vcc
	s_cbranch_execz .LBB0_556
	v_mul_f32_e32 v64, 0x3fb8aa3b, v64
	v_exp_f32_e32 v64, v64
	s_nop 0
	v_mul_f32_e32 v64, 0x3e000000, v64
	v_mul_f32_e32 v225, v4, v64
.LBB0_556:
	s_or_b64 exec, exec, s[36:37]
	v_readlane_b32 s36, v255, 30
	v_readlane_b32 s37, v255, 31
	v_cndmask_b32_e64 v64, 0, 1, s[36:37]
	v_readlane_b32 s36, v255, 28
	v_readlane_b32 s37, v255, 29
	s_nop 1
	v_cndmask_b32_e64 v65, 0, 1, s[36:37]
	v_cndmask_b32_e64 v64, v65, v64, s[2:3]
	v_and_b32_e32 v64, 1, v64
	v_cmp_eq_u32_e32 vcc, 1, v64
	v_add_f32_e32 v64, v220, v228
	v_mov_b32_e32 v228, 0
	s_and_saveexec_b64 s[36:37], vcc
	s_cbranch_execz .LBB0_558
	v_mul_f32_e32 v64, 0x3fb8aa3b, v64
	v_exp_f32_e32 v64, v64
	s_nop 0
	v_mul_f32_e32 v64, 0x3e000000, v64
	v_mul_f32_e32 v228, v5, v64
.LBB0_558:
	s_or_b64 exec, exec, s[36:37]
	v_readlane_b32 s36, v255, 34
	v_readlane_b32 s37, v255, 35
	s_nop 1
	v_cndmask_b32_e64 v64, 0, 1, s[36:37]
	v_readlane_b32 s36, v255, 32
	v_readlane_b32 s37, v255, 33
	s_nop 1
	v_cndmask_b32_e64 v65, 0, 1, s[36:37]
	v_cndmask_b32_e64 v64, v65, v64, s[2:3]
	v_and_b32_e32 v64, 1, v64
	v_cmp_eq_u32_e32 vcc, 1, v64
	v_add_f32_e32 v64, v220, v227
	v_mov_b32_e32 v227, 0
	s_and_saveexec_b64 s[36:37], vcc
	s_cbranch_execz .LBB0_560
	v_mul_f32_e32 v64, 0x3fb8aa3b, v64
	v_exp_f32_e32 v64, v64
	s_nop 0
	v_mul_f32_e32 v64, 0x3e000000, v64
	v_mul_f32_e32 v227, v6, v64
.LBB0_560:
	s_or_b64 exec, exec, s[36:37]
	v_readlane_b32 s36, v255, 38
	v_readlane_b32 s37, v255, 39
	v_cndmask_b32_e64 v64, 0, 1, s[36:37]
	v_readlane_b32 s36, v255, 36
	v_readlane_b32 s37, v255, 37
	s_nop 1
	v_cndmask_b32_e64 v65, 0, 1, s[36:37]
	v_cndmask_b32_e64 v64, v65, v64, s[2:3]
	v_and_b32_e32 v64, 1, v64
	v_cmp_eq_u32_e32 vcc, 1, v64
	v_add_f32_e32 v64, v220, v230
	v_mov_b32_e32 v230, 0
	s_and_saveexec_b64 s[36:37], vcc
	s_cbranch_execz .LBB0_562
	v_mul_f32_e32 v64, 0x3fb8aa3b, v64
	v_exp_f32_e32 v64, v64
	s_nop 0
	v_mul_f32_e32 v64, 0x3e000000, v64
	v_mul_f32_e32 v230, v7, v64
.LBB0_562:
	s_or_b64 exec, exec, s[36:37]
	v_readlane_b32 s36, v255, 42
	v_readlane_b32 s37, v255, 43
	s_nop 1
	v_cndmask_b32_e64 v64, 0, 1, s[36:37]
	v_readlane_b32 s36, v255, 40
	v_readlane_b32 s37, v255, 41
	s_nop 1
	v_cndmask_b32_e64 v65, 0, 1, s[36:37]
	v_cndmask_b32_e64 v64, v65, v64, s[2:3]
	v_and_b32_e32 v64, 1, v64
	v_cmp_eq_u32_e32 vcc, 1, v64
	v_add_f32_e32 v64, v220, v229
	v_mov_b32_e32 v229, 0
	s_and_saveexec_b64 s[36:37], vcc
	s_cbranch_execz .LBB0_564
	v_mul_f32_e32 v64, 0x3fb8aa3b, v64
	v_exp_f32_e32 v64, v64
	s_nop 0
	v_mul_f32_e32 v64, 0x3e000000, v64
	v_mul_f32_e32 v229, v8, v64
.LBB0_564:
	s_or_b64 exec, exec, s[36:37]
	v_cndmask_b32_e64 v64, 0, 1, s[40:41]
	v_cndmask_b32_e64 v65, 0, 1, s[38:39]
	v_cndmask_b32_e64 v64, v65, v64, s[2:3]
	v_and_b32_e32 v64, 1, v64
	v_cmp_eq_u32_e32 vcc, 1, v64
	v_add_f32_e32 v64, v220, v232
	v_mov_b32_e32 v232, 0
	s_and_saveexec_b64 s[36:37], vcc
	s_cbranch_execz .LBB0_566
	v_mul_f32_e32 v64, 0x3fb8aa3b, v64
	v_exp_f32_e32 v64, v64
	s_nop 0
	v_mul_f32_e32 v64, 0x3e000000, v64
	v_mul_f32_e32 v232, v9, v64
.LBB0_566:
	s_or_b64 exec, exec, s[36:37]
	v_cndmask_b32_e64 v64, 0, 1, s[44:45]
	v_cndmask_b32_e64 v65, 0, 1, s[42:43]
	v_cndmask_b32_e64 v64, v65, v64, s[2:3]
	v_and_b32_e32 v64, 1, v64
	v_cmp_eq_u32_e32 vcc, 1, v64
	v_add_f32_e32 v64, v220, v231
	v_mov_b32_e32 v231, 0
	s_and_saveexec_b64 s[36:37], vcc
	s_cbranch_execz .LBB0_568
	v_mul_f32_e32 v64, 0x3fb8aa3b, v64
	v_exp_f32_e32 v64, v64
	s_nop 0
	v_mul_f32_e32 v64, 0x3e000000, v64
	v_mul_f32_e32 v231, v10, v64
; #define LAS __attribute__((address_space(3)))
; DI int crow(int i, int h) { return (i & 3) + 8 * (i >> 2) + 4 * h; }
; #define MFMA32(a, b, c) __builtin_amdgcn_mfma_f32_32x32x16_bf16((a), (b), (c), 0, 0, 0)
; DI s16x4 trr(const LAS bf16_t* p) { return __builtin_amdgcn_ds_read_tr16_b64_v4i16((LAS s16x4*)p); }
; DI bf16x8 cat4(s16x4 a, s16x4 b) { return __builtin_shufflevector(a, b, 0, 1, 2, 3, 4, 5, 6, 7); }
; DI void mlstm_out_item(const KP& P, int layer, int b, int tb, LAS unsigned char* lds) {
;     ...
;         for (int jt = 0; jt < 2; ++jt) { f32x16 Pv;
; #pragma unroll
;             for (int i = 0; i < 16; ++i) { const int s = 32 * jt + crow(i, h); const bool keep = dir ? (s >= t) : (s <= t);
;                 const float as = As[s * 8 + gi];
;                 const float pe = keep ? S[jt][i] * (__expf(Ft + as) * 0.125f) : 0.f; Pv[i] = pe; den += pe; }
;             const bf16x8 Pf0 = pack8(Pv, 0), Pf1 = pack8(Pv, 1);
; #pragma unroll
;             for (int nt = 0; nt < 2; ++nt) { const LAS bf16_t* vp = Vt + vtr + (32 * jt) * VP + 32 * nt;
;                 aP[nt] = MFMA32(cat4(trr(vp), trr(vp + 8 * VP)), Pf0, aP[nt]);
;                 aP[nt] = MFMA32(cat4(trr(vp + 16 * VP), trr(vp + 24 * VP)), Pf1, aP[nt]); } }
.LBB0_568:
	s_or_b64 exec, exec, s[36:37]
	v_cndmask_b32_e64 v64, 0, 1, s[48:49]
	v_cndmask_b32_e64 v65, 0, 1, s[46:47]
	v_cndmask_b32_e64 v64, v65, v64, s[2:3]
	v_and_b32_e32 v64, 1, v64
	v_cmp_eq_u32_e32 vcc, 1, v64
	v_add_f32_e32 v64, v220, v234
	v_mov_b32_e32 v234, 0
	s_and_saveexec_b64 s[36:37], vcc
	s_cbranch_execz .LBB0_570
	v_mul_f32_e32 v64, 0x3fb8aa3b, v64
	v_exp_f32_e32 v64, v64
	s_nop 0
	v_mul_f32_e32 v64, 0x3e000000, v64
	v_mul_f32_e32 v234, v11, v64
.LBB0_570:
	s_or_b64 exec, exec, s[36:37]
	v_cndmask_b32_e64 v64, 0, 1, s[52:53]
	v_cndmask_b32_e64 v65, 0, 1, s[50:51]
	v_cndmask_b32_e64 v64, v65, v64, s[2:3]
	v_and_b32_e32 v64, 1, v64
	v_cmp_eq_u32_e32 vcc, 1, v64
	v_add_f32_e32 v64, v220, v233
	v_mov_b32_e32 v233, 0
	s_and_saveexec_b64 s[36:37], vcc
	s_cbranch_execz .LBB0_572
	v_mul_f32_e32 v64, 0x3fb8aa3b, v64
	v_exp_f32_e32 v64, v64
	s_nop 0
	v_mul_f32_e32 v64, 0x3e000000, v64
	v_mul_f32_e32 v233, v12, v64
.LBB0_572:
	s_or_b64 exec, exec, s[36:37]
	v_cndmask_b32_e64 v64, 0, 1, s[56:57]
	v_cndmask_b32_e64 v65, 0, 1, s[54:55]
	v_cndmask_b32_e64 v64, v65, v64, s[2:3]
	v_and_b32_e32 v64, 1, v64
	v_cmp_eq_u32_e32 vcc, 1, v64
	v_add_f32_e32 v64, v220, v236
	v_mov_b32_e32 v236, 0
	s_and_saveexec_b64 s[36:37], vcc
	s_cbranch_execz .LBB0_574
	v_mul_f32_e32 v64, 0x3fb8aa3b, v64
	v_exp_f32_e32 v64, v64
	s_nop 0
	v_mul_f32_e32 v64, 0x3e000000, v64
	v_mul_f32_e32 v236, v13, v64
.LBB0_574:
	s_or_b64 exec, exec, s[36:37]
	v_cndmask_b32_e64 v64, 0, 1, s[60:61]
	v_cndmask_b32_e64 v65, 0, 1, s[58:59]
	v_cndmask_b32_e64 v64, v65, v64, s[2:3]
	v_and_b32_e32 v64, 1, v64
	v_cmp_eq_u32_e32 vcc, 1, v64
	v_add_f32_e32 v64, v220, v235
	v_mov_b32_e32 v235, 0
	s_and_saveexec_b64 s[36:37], vcc
	s_cbranch_execz .LBB0_576
	v_mul_f32_e32 v64, 0x3fb8aa3b, v64
	v_exp_f32_e32 v64, v64
	s_nop 0
	v_mul_f32_e32 v64, 0x3e000000, v64
	v_mul_f32_e32 v235, v14, v64
.LBB0_576:
	s_or_b64 exec, exec, s[36:37]
	v_cndmask_b32_e64 v64, 0, 1, s[64:65]
	v_cndmask_b32_e64 v65, 0, 1, s[62:63]
	v_cndmask_b32_e64 v64, v65, v64, s[2:3]
	v_and_b32_e32 v64, 1, v64
	v_cmp_eq_u32_e32 vcc, 1, v64
	v_add_f32_e32 v64, v220, v238
	v_mov_b32_e32 v238, 0
	s_and_saveexec_b64 s[36:37], vcc
	s_cbranch_execz .LBB0_578
	v_mul_f32_e32 v64, 0x3fb8aa3b, v64
	v_exp_f32_e32 v64, v64
	s_nop 0
	v_mul_f32_e32 v64, 0x3e000000, v64
	v_mul_f32_e32 v238, v15, v64
.LBB0_578:
	s_or_b64 exec, exec, s[36:37]
	ds_read_b64_tr_b16 v[68:69], v162
	ds_read_b64_tr_b16 v[70:71], v162 offset:4352
	v_cvt_pk_bf16_f32 v64, v222, v224
	v_cvt_pk_bf16_f32 v65, v223, v226
	v_cvt_pk_bf16_f32 v66, v225, v228
	v_cvt_pk_bf16_f32 v67, v227, v230
	v_cvt_pk_bf16_f32 v192, v229, v232
	v_cvt_pk_bf16_f32 v193, v231, v234
	s_waitcnt lgkmcnt(0)
	v_mfma_f32_32x32x16_bf16 v[80:95], v[68:71], v[64:67], 0
	ds_read_b64_tr_b16 v[68:69], v162 offset:8704
	ds_read_b64_tr_b16 v[70:71], v162 offset:13056
	v_cvt_pk_bf16_f32 v194, v233, v236
	v_cvt_pk_bf16_f32 v195, v235, v238
	v_add_u32_e32 v152, v221, v188
	ds_read_b32 v237, v152
	v_add_u32_e32 v153, v221, v189
	ds_read_b32 v240, v153
	v_add_u32_e32 v149, v221, v204
	ds_read_b32 v239, v149
	v_add_u32_e32 v152, v221, v205
	ds_read_b32 v242, v152
	v_add_u32_e32 v153, v221, v206
	ds_read_b32 v241, v153
	v_add_u32_e32 v149, v221, v207
	ds_read_b32 v244, v149
	v_add_u32_e32 v152, v221, v208
	ds_read_b32 v243, v152
	v_add_u32_e32 v153, v221, v209
	ds_read_b32 v246, v153
	v_add_u32_e32 v149, v221, v210
	ds_read_b32 v245, v149
	v_add_u32_e32 v152, v221, v211
	ds_read_b32 v248, v152
	v_add_u32_e32 v153, v221, v212
	ds_read_b32 v247, v153
	v_add_u32_e32 v149, v221, v213
	ds_read_b32 v250, v149
	v_add_u32_e32 v152, v221, v214
	ds_read_b32 v249, v152
	v_cndmask_b32_e64 v149, 0, 1, s[68:69]
	v_cndmask_b32_e64 v152, 0, 1, s[66:67]
	v_cndmask_b32_e64 v149, v152, v149, s[2:3]
	v_and_b32_e32 v149, 1, v149
	s_waitcnt lgkmcnt(0)
	v_mfma_f32_32x32x16_bf16 v[80:95], v[68:71], v[192:195], v[80:95]
	ds_read_b64_tr_b16 v[68:69], v162 offset:64
	ds_read_b64_tr_b16 v[70:71], v162 offset:4416
	ds_read_b64_tr_b16 v[196:197], v162 offset:8768
	ds_read_b64_tr_b16 v[198:199], v162 offset:13120
	v_cmp_eq_u32_e32 vcc, 1, v149
	s_waitcnt lgkmcnt(2)
	v_mfma_f32_32x32x16_bf16 v[64:79], v[68:71], v[64:67], 0
	s_waitcnt lgkmcnt(0)
	v_mfma_f32_32x32x16_bf16 v[64:79], v[196:199], v[192:195], v[64:79]
	v_add_f32_e32 v149, v220, v237
	v_mov_b32_e32 v237, 0
	s_and_saveexec_b64 s[36:37], vcc
	s_cbranch_execz .LBB0_580
	v_mul_f32_e32 v149, 0x3fb8aa3b, v149
	v_exp_f32_e32 v149, v149
	s_nop 0
	v_mul_f32_e32 v149, 0x3e000000, v149
	v_mul_f32_e32 v237, v16, v149
.LBB0_580:
	s_or_b64 exec, exec, s[36:37]
	v_cndmask_b32_e64 v149, 0, 1, s[72:73]
	v_cndmask_b32_e64 v152, 0, 1, s[70:71]
	v_cndmask_b32_e64 v149, v152, v149, s[2:3]
	v_and_b32_e32 v149, 1, v149
	v_cmp_eq_u32_e32 vcc, 1, v149
	v_add_f32_e32 v149, v220, v240
	v_mov_b32_e32 v240, 0
	s_and_saveexec_b64 s[36:37], vcc
	s_cbranch_execz .LBB0_582
	v_mul_f32_e32 v149, 0x3fb8aa3b, v149
	v_exp_f32_e32 v149, v149
	s_nop 0
	v_mul_f32_e32 v149, 0x3e000000, v149
	v_mul_f32_e32 v240, v17, v149
; DI int crow(int i, int h) { return (i & 3) + 8 * (i >> 2) + 4 * h; }
; DI void mlstm_out_item(const KP& P, int layer, int b, int tb, LAS unsigned char* lds) {
;     ...
;         for (int jt = 0; jt < 2; ++jt) { f32x16 Pv;
; #pragma unroll
;             for (int i = 0; i < 16; ++i) { const int s = 32 * jt + crow(i, h); const bool keep = dir ? (s >= t) : (s <= t);
;                 const float as = As[s * 8 + gi];
;                 const float pe = keep ? S[jt][i] * (__expf(Ft + as) * 0.125f) : 0.f; Pv[i] = pe; den += pe; }
.LBB0_582:
	s_or_b64 exec, exec, s[36:37]
	v_cndmask_b32_e64 v149, 0, 1, s[76:77]
	v_cndmask_b32_e64 v152, 0, 1, s[74:75]
	v_cndmask_b32_e64 v149, v152, v149, s[2:3]
	v_and_b32_e32 v149, 1, v149
	v_cmp_eq_u32_e32 vcc, 1, v149
	v_add_f32_e32 v149, v220, v239
	v_mov_b32_e32 v239, 0
	s_and_saveexec_b64 s[36:37], vcc
	s_cbranch_execz .LBB0_584
	v_mul_f32_e32 v149, 0x3fb8aa3b, v149
	v_exp_f32_e32 v149, v149
	s_nop 0
	v_mul_f32_e32 v149, 0x3e000000, v149
	v_mul_f32_e32 v239, v18, v149
.LBB0_584:
	s_or_b64 exec, exec, s[36:37]
	v_cndmask_b32_e64 v149, 0, 1, s[80:81]
	v_cndmask_b32_e64 v152, 0, 1, s[78:79]
	v_cndmask_b32_e64 v149, v152, v149, s[2:3]
	v_and_b32_e32 v149, 1, v149
	v_cmp_eq_u32_e32 vcc, 1, v149
	v_add_f32_e32 v149, v220, v242
	v_mov_b32_e32 v242, 0
	s_and_saveexec_b64 s[36:37], vcc
	s_cbranch_execz .LBB0_586
	v_mul_f32_e32 v149, 0x3fb8aa3b, v149
	v_exp_f32_e32 v149, v149
	s_nop 0
	v_mul_f32_e32 v149, 0x3e000000, v149
	v_mul_f32_e32 v242, v19, v149
.LBB0_586:
	s_or_b64 exec, exec, s[36:37]
	v_cndmask_b32_e64 v149, 0, 1, s[84:85]
	v_cndmask_b32_e64 v152, 0, 1, s[82:83]
	v_cndmask_b32_e64 v149, v152, v149, s[2:3]
	v_and_b32_e32 v149, 1, v149
	v_cmp_eq_u32_e32 vcc, 1, v149
	v_add_f32_e32 v149, v220, v241
	v_mov_b32_e32 v241, 0
	s_and_saveexec_b64 s[36:37], vcc
	s_cbranch_execz .LBB0_588
	v_mul_f32_e32 v149, 0x3fb8aa3b, v149
	v_exp_f32_e32 v149, v149
	s_nop 0
	v_mul_f32_e32 v149, 0x3e000000, v149
	v_mul_f32_e32 v241, v20, v149
.LBB0_588:
	s_or_b64 exec, exec, s[36:37]
	v_cndmask_b32_e64 v149, 0, 1, s[88:89]
	v_cndmask_b32_e64 v152, 0, 1, s[86:87]
	v_cndmask_b32_e64 v149, v152, v149, s[2:3]
	v_and_b32_e32 v149, 1, v149
	v_cmp_eq_u32_e32 vcc, 1, v149
	v_add_f32_e32 v149, v220, v244
	v_mov_b32_e32 v244, 0
	s_and_saveexec_b64 s[36:37], vcc
	s_cbranch_execz .LBB0_590
	v_mul_f32_e32 v149, 0x3fb8aa3b, v149
	v_exp_f32_e32 v149, v149
	s_nop 0
	v_mul_f32_e32 v149, 0x3e000000, v149
	v_mul_f32_e32 v244, v21, v149
.LBB0_590:
	s_or_b64 exec, exec, s[36:37]
	v_cndmask_b32_e64 v149, 0, 1, s[92:93]
	v_cndmask_b32_e64 v152, 0, 1, s[90:91]
	v_cndmask_b32_e64 v149, v152, v149, s[2:3]
	v_and_b32_e32 v149, 1, v149
	v_cmp_eq_u32_e32 vcc, 1, v149
	v_add_f32_e32 v149, v220, v243
	v_mov_b32_e32 v243, 0
	s_and_saveexec_b64 s[36:37], vcc
	s_cbranch_execz .LBB0_592
	v_mul_f32_e32 v149, 0x3fb8aa3b, v149
	v_exp_f32_e32 v149, v149
	s_nop 0
	v_mul_f32_e32 v149, 0x3e000000, v149
	v_mul_f32_e32 v243, v22, v149
.LBB0_592:
	s_or_b64 exec, exec, s[36:37]
	v_cndmask_b32_e64 v149, 0, 1, s[96:97]
	v_cndmask_b32_e64 v152, 0, 1, s[94:95]
	v_cndmask_b32_e64 v149, v152, v149, s[2:3]
	v_and_b32_e32 v149, 1, v149
	v_cmp_eq_u32_e32 vcc, 1, v149
	v_add_f32_e32 v149, v220, v246
	v_mov_b32_e32 v246, 0
	s_and_saveexec_b64 s[36:37], vcc
	s_cbranch_execz .LBB0_594
	v_mul_f32_e32 v149, 0x3fb8aa3b, v149
	v_exp_f32_e32 v149, v149
	s_nop 0
	v_mul_f32_e32 v149, 0x3e000000, v149
	v_mul_f32_e32 v246, v23, v149
.LBB0_594:
	s_or_b64 exec, exec, s[36:37]
	v_cndmask_b32_e64 v149, 0, 1, s[34:35]
	v_cndmask_b32_e64 v152, 0, 1, s[0:1]
	v_cndmask_b32_e64 v149, v152, v149, s[2:3]
	v_and_b32_e32 v149, 1, v149
	v_cmp_eq_u32_e32 vcc, 1, v149
	v_add_f32_e32 v149, v220, v245
	v_mov_b32_e32 v245, 0
	s_and_saveexec_b64 s[36:37], vcc
	s_cbranch_execz .LBB0_596
	v_mul_f32_e32 v149, 0x3fb8aa3b, v149
	v_exp_f32_e32 v149, v149
	s_nop 0
	v_mul_f32_e32 v149, 0x3e000000, v149
	v_mul_f32_e32 v245, v24, v149
.LBB0_596:
	s_or_b64 exec, exec, s[36:37]
	v_cndmask_b32_e64 v149, 0, 1, s[6:7]
	v_cndmask_b32_e64 v152, 0, 1, s[4:5]
	v_cndmask_b32_e64 v149, v152, v149, s[2:3]
	v_and_b32_e32 v149, 1, v149
	v_cmp_eq_u32_e32 vcc, 1, v149
	v_add_f32_e32 v149, v220, v248
	v_mov_b32_e32 v248, 0
	s_and_saveexec_b64 s[36:37], vcc
	s_cbranch_execz .LBB0_598
	v_mul_f32_e32 v149, 0x3fb8aa3b, v149
	v_exp_f32_e32 v149, v149
	s_nop 0
	v_mul_f32_e32 v149, 0x3e000000, v149
	v_mul_f32_e32 v248, v25, v149
.LBB0_598:
	s_or_b64 exec, exec, s[36:37]
	v_cndmask_b32_e64 v149, 0, 1, s[10:11]
	v_cndmask_b32_e64 v152, 0, 1, s[8:9]
	v_cndmask_b32_e64 v149, v152, v149, s[2:3]
	v_and_b32_e32 v149, 1, v149
	v_cmp_eq_u32_e32 vcc, 1, v149
	v_add_f32_e32 v149, v220, v247
	v_mov_b32_e32 v247, 0
	s_and_saveexec_b64 s[36:37], vcc
	s_cbranch_execz .LBB0_600
	v_mul_f32_e32 v149, 0x3fb8aa3b, v149
	v_exp_f32_e32 v149, v149
	s_nop 0
	v_mul_f32_e32 v149, 0x3e000000, v149
	v_mul_f32_e32 v247, v26, v149
.LBB0_600:
	s_or_b64 exec, exec, s[36:37]
	v_cndmask_b32_e64 v149, 0, 1, s[14:15]
	v_cndmask_b32_e64 v152, 0, 1, s[12:13]
	v_cndmask_b32_e64 v149, v152, v149, s[2:3]
	v_and_b32_e32 v149, 1, v149
	v_cmp_eq_u32_e32 vcc, 1, v149
	v_add_f32_e32 v149, v220, v250
	v_mov_b32_e32 v250, 0
	s_and_saveexec_b64 s[36:37], vcc
	s_cbranch_execz .LBB0_602
	v_mul_f32_e32 v149, 0x3fb8aa3b, v149
	v_exp_f32_e32 v149, v149
	s_nop 0
	v_mul_f32_e32 v149, 0x3e000000, v149
	v_mul_f32_e32 v250, v27, v149
.LBB0_602:
	s_or_b64 exec, exec, s[36:37]
	v_cndmask_b32_e64 v149, 0, 1, s[18:19]
	v_cndmask_b32_e64 v152, 0, 1, s[16:17]
	v_cndmask_b32_e64 v149, v152, v149, s[2:3]
	v_and_b32_e32 v149, 1, v149
	v_cmp_eq_u32_e32 vcc, 1, v149
	v_add_f32_e32 v149, v220, v249
	v_mov_b32_e32 v249, 0
	s_and_saveexec_b64 s[36:37], vcc
	s_cbranch_execz .LBB0_604
	v_mul_f32_e32 v149, 0x3fb8aa3b, v149
	v_exp_f32_e32 v149, v149
	s_nop 0
	v_mul_f32_e32 v149, 0x3e000000, v149
	v_mul_f32_e32 v249, v28, v149

; #define LAS __attribute__((address_space(3)))
; DI unsigned pk2(float lo, float hi) { f32x2 v = {lo, hi}; bf2_t r = __builtin_convertvector(v, bf2_t); return __builtin_bit_cast(unsigned, r); }
; DI float bflo(unsigned u) { return __uint_as_float(u << 16); }
; DI float bfhi(unsigned u) { return __uint_as_float(u & 0xffff0000u); }
; DI void gla_out_item(const KP& P, int layer, int b, int tb, LAS unsigned char* lds) {
;     ...
;         const int c = dir ? (tb < 4 ? 3 - tb : 71 - tb) : tb, chain = (b * 2 + dir) * 4 + hd;
;         const bf16_t* sgp = SG + ((size_t)chain * NTB + c) * 2048 + (size_t)r * 32 + 8 * h;
;         u32x4 Sf[2][2];
; #pragma unroll
;         for (int nt = 0; nt < 2; ++nt)
; #pragma unroll
;             for (int kk = 0; kk < 2; ++kk) Sf[nt][kk] = ldg16(sgp + nt * 1024 + 16 * kk);
;         bf16x8 Qf[2];
; #pragma unroll
;         for (int kk = 0; kk < 2; ++kk) { const int d0 = hd * 32 + 16 * kk + 8 * h; const u32x4 qv = *(const LAS u32x4*)(Qt + t * QP + d0);
;             const LAS float* bp = Bt + t * BP + dir * 128 + d0; const f32x4 b0 = *(const LAS f32x4*)bp, b1 = *(const LAS f32x4*)(bp + 4);
;             const float sc = 0.17677669529663687f;
;             u32x4 o; o.x = pk2(bflo(qv.x) * __expf(b0[0]) * sc, bfhi(qv.x) * __expf(b0[1]) * sc); o.y = pk2(bflo(qv.y) * __expf(b0[2]) * sc, bfhi(qv.y) * __expf(b0[3]) * sc);
;             o.z = pk2(bflo(qv.z) * __expf(b1[0]) * sc, bfhi(qv.z) * __expf(b1[1]) * sc); o.w = pk2(bflo(qv.w) * __expf(b1[2]) * sc, bfhi(qv.w) * __expf(b1[3]) * sc);
;             Qf[kk] = as_bf8(o); }
; #pragma unroll
;         for (int jt = 0; jt < 2; ++jt) { f32x16 S = zero16();
; #pragma unroll
;             for (int kk = 0; kk < 2; ++kk) { const int d0 = hd * 32 + 16 * kk + 8 * h; const u32x4 kv = *(const LAS u32x4*)(Kt + (32 * jt + r) * QP + d0);
;                 const LAS float* bp = Bt + (32 * jt + r) * BP + dir * 128 + d0; const f32x4 b0 = *(const LAS f32x4*)bp, b1 = *(const LAS f32x4*)(bp + 4);
;                 u32x4 o; o.x = pk2(bflo(kv.x) * __expf(-b0[0]), bfhi(kv.x) * __expf(-b0[1])); o.y = pk2(bflo(kv.y) * __expf(-b0[2]), bfhi(kv.y) * __expf(-b0[3]));
;                 o.z = pk2(bflo(kv.z) * __expf(-b1[0]), bfhi(kv.z) * __expf(-b1[1])); o.w = pk2(bflo(kv.w) * __expf(-b1[2]), bfhi(kv.w) * __expf(-b1[3]));
;                 S = MFMA32(as_bf8(o), Qf[kk], S); }
.LBB0_618:
	s_and_b64 vcc, s[2:3], exec
	v_readlane_b32 vcc_lo, v255, 5
	s_cselect_b32 vcc_lo, s73, vcc_lo
	s_ashr_i32 vcc_hi, vcc_lo, 31
	v_lshl_or_b32 v34, s33, 2, v130
	v_mov_b32_e32 v32, vcc_lo
	v_mov_b32_e32 v33, vcc_hi
	s_movk_i32 vcc_lo, 0x44
	v_mad_i64_i32 v[32:33], vcc, v34, vcc_lo, v[32:33]
	v_lshlrev_b64 v[32:33], 12, v[32:33]
	s_lshl_b32 s33, s33, 9
	v_lshl_add_u64 v[32:33], v[76:77], 0, v[32:33]
	v_add_u32_e32 v40, s33, v132
	global_load_dwordx4 v[56:59], v[32:33], off
	global_load_dwordx4 v[60:63], v[32:33], off offset:32
	global_load_dwordx4 v[52:55], v[32:33], off offset:2048
	global_load_dwordx4 v[48:51], v[32:33], off offset:2080
	ds_read_b128 v[32:35], v40
	ds_read_b128 v[36:39], v40 offset:16
	s_add_i32 s33, s33, 0
	s_add_i32 s33, s33, 0x11000
	v_add3_u32 v133, s33, v112, v131
	s_waitcnt lgkmcnt(1)
	v_mul_f32_e32 v32, 0x3fb8aa3b, v32
	v_mul_f32_e32 v33, 0x3fb8aa3b, v33
	v_exp_f32_e32 v32, v32
	v_exp_f32_e32 v33, v33
	v_readlane_b32 vcc_lo, v255, 10
	v_readlane_b32 vcc_hi, v255, 11
	v_pk_mul_f32 v[32:33], v[32:33], v[78:79]
	s_nop 0
	v_pk_mul_f32 v[32:33], v[32:33], s[72:73] op_sel_hi:[1,0]
	s_nop 0
	v_cvt_pk_bf16_f32 v64, v32, v33
	v_mul_f32_e32 v32, 0x3fb8aa3b, v34
	v_mul_f32_e32 v33, 0x3fb8aa3b, v35
	v_exp_f32_e32 v32, v32
	v_exp_f32_e32 v33, v33
	s_nop 0
	v_pk_mul_f32 v[32:33], v[32:33], v[80:81]
	s_nop 0
	v_pk_mul_f32 v[32:33], v[32:33], s[72:73] op_sel_hi:[1,0]
	s_nop 0
	v_cvt_pk_bf16_f32 v65, v32, v33
	s_waitcnt lgkmcnt(0)
	v_mul_f32_e32 v32, 0x3fb8aa3b, v36
	v_mul_f32_e32 v33, 0x3fb8aa3b, v37
	v_exp_f32_e32 v32, v32
	v_exp_f32_e32 v33, v33
	s_nop 0
	v_pk_mul_f32 v[32:33], v[32:33], v[82:83]
	s_nop 0
	v_pk_mul_f32 v[32:33], v[32:33], s[72:73] op_sel_hi:[1,0]
	s_nop 0
	v_cvt_pk_bf16_f32 v66, v32, v33
	v_mul_f32_e32 v32, 0x3fb8aa3b, v38
	v_mul_f32_e32 v33, 0x3fb8aa3b, v39
	v_exp_f32_e32 v32, v32
	v_exp_f32_e32 v33, v33
	s_nop 0
	v_pk_mul_f32 v[32:33], v[32:33], v[84:85]
	s_nop 0
	v_pk_mul_f32 v[32:33], v[32:33], s[72:73] op_sel_hi:[1,0]
	s_nop 0
	v_cvt_pk_bf16_f32 v67, v32, v33
	ds_read_b128 v[32:35], v40 offset:64
	ds_read_b128 v[36:39], v40 offset:80
	s_waitcnt lgkmcnt(1)
	v_mul_f32_e32 v32, 0x3fb8aa3b, v32
	v_mul_f32_e32 v33, 0x3fb8aa3b, v33
	v_exp_f32_e32 v32, v32
	v_exp_f32_e32 v33, v33
	s_nop 0
	v_pk_mul_f32 v[32:33], v[32:33], v[86:87]
	s_nop 0
	v_pk_mul_f32 v[32:33], v[32:33], s[72:73] op_sel_hi:[1,0]
	s_nop 0
	v_cvt_pk_bf16_f32 v68, v32, v33
	v_mul_f32_e32 v32, 0x3fb8aa3b, v34
	v_mul_f32_e32 v33, 0x3fb8aa3b, v35
	v_exp_f32_e32 v32, v32
	v_exp_f32_e32 v33, v33
	s_nop 0
	v_pk_mul_f32 v[32:33], v[32:33], v[88:89]
	s_nop 0
	v_pk_mul_f32 v[32:33], v[32:33], s[72:73] op_sel_hi:[1,0]
	s_nop 0
	v_cvt_pk_bf16_f32 v69, v32, v33
	s_waitcnt lgkmcnt(0)
	v_mul_f32_e32 v32, 0x3fb8aa3b, v36
	v_mul_f32_e32 v33, 0x3fb8aa3b, v37
	v_exp_f32_e32 v32, v32
	v_exp_f32_e32 v33, v33
	s_nop 0
	v_pk_mul_f32 v[32:33], v[32:33], v[90:91]
	s_nop 0
	v_pk_mul_f32 v[32:33], v[32:33], s[72:73] op_sel_hi:[1,0]
	s_nop 0
	v_cvt_pk_bf16_f32 v70, v32, v33
	v_mul_f32_e32 v32, 0x3fb8aa3b, v38
	v_mul_f32_e32 v33, 0x3fb8aa3b, v39
	v_exp_f32_e32 v32, v32
	v_exp_f32_e32 v33, v33
	s_nop 0
	v_pk_mul_f32 v[32:33], v[32:33], v[92:93]
	s_nop 0
	v_pk_mul_f32 v[32:33], v[32:33], s[72:73] op_sel_hi:[1,0]
	s_nop 0
	v_cvt_pk_bf16_f32 v71, v32, v33
	ds_read_b128 v[32:35], v133
	ds_read_b128 v[36:39], v133 offset:16
	ds_read_b128 v[134:137], v133 offset:64
	ds_read_b128 v[138:141], v133 offset:80
	s_waitcnt lgkmcnt(3)
	v_mul_f32_e32 v32, 0xbfb8aa3b, v32
	v_mul_f32_e32 v33, 0xbfb8aa3b, v33
	v_exp_f32_e32 v32, v32
	v_exp_f32_e32 v33, v33
	s_waitcnt lgkmcnt(1)
	v_mul_f32_e32 v133, 0xbfb8aa3b, v134
	v_exp_f32_e32 v134, v133
	v_mul_f32_e32 v133, 0xbfb8aa3b, v135
	v_pk_mul_f32 v[32:33], v[32:33], v[94:95]
	v_exp_f32_e32 v135, v133
	v_cvt_pk_bf16_f32 v32, v32, v33
	v_mul_f32_e32 v33, 0xbfb8aa3b, v34
	v_exp_f32_e32 v34, v33
	v_mul_f32_e32 v33, 0xbfb8aa3b, v35
	v_exp_f32_e32 v35, v33
	v_mul_f32_e32 v133, 0xbfb8aa3b, v136
	v_exp_f32_e32 v136, v133
	v_mul_f32_e32 v133, 0xbfb8aa3b, v137
	v_pk_mul_f32 v[34:35], v[34:35], v[96:97]
	v_exp_f32_e32 v137, v133
	v_cvt_pk_bf16_f32 v33, v34, v35
	v_mul_f32_e32 v34, 0xbfb8aa3b, v36
	v_mul_f32_e32 v35, 0xbfb8aa3b, v37
	v_exp_f32_e32 v34, v34
	v_exp_f32_e32 v35, v35
	v_pk_mul_f32 v[134:135], v[134:135], v[102:103]
	v_pk_mul_f32 v[136:137], v[136:137], v[104:105]
	s_waitcnt lgkmcnt(0)
; #define LAS __attribute__((address_space(3)))
; DI int crow(int i, int h) { return (i & 3) + 8 * (i >> 2) + 4 * h; }
; #define MFMA32(a, b, c) __builtin_amdgcn_mfma_f32_32x32x16_bf16((a), (b), (c), 0, 0, 0)
; DI s16x4 trr(const LAS bf16_t* p) { return __builtin_amdgcn_ds_read_tr16_b64_v4i16((LAS s16x4*)p); }
; DI bf16x8 cat4(s16x4 a, s16x4 b) { return __builtin_shufflevector(a, b, 0, 1, 2, 3, 4, 5, 6, 7); }
; DI void gla_out_item(const KP& P, int layer, int b, int tb, LAS unsigned char* lds) {
;     ...
; #pragma unroll
;             for (int i = 0; i < 16; ++i) { const int s = 32 * jt + crow(i, h); const bool keep = dir ? (s >= t) : (s <= t); S[i] = keep ? S[i] : 0.f; }
;             const bf16x8 Pf0 = pack8(S, 0), Pf1 = pack8(S, 1);
; #pragma unroll
;             for (int nt = 0; nt < 2; ++nt) { const LAS bf16_t* vp = Vt + vtr + (32 * jt) * VP + 32 * nt;
;                 accO[nt] = MFMA32(cat4(trr(vp), trr(vp + 8 * VP)), Pf0, accO[nt]);
;                 accO[nt] = MFMA32(cat4(trr(vp + 16 * VP), trr(vp + 24 * VP)), Pf1, accO[nt]); } }
	v_mul_f32_e32 v133, 0xbfb8aa3b, v138
	v_pk_mul_f32 v[34:35], v[34:35], v[98:99]
	v_cvt_pk_bf16_f32 v134, v134, v135
	v_cvt_pk_bf16_f32 v34, v34, v35
	v_mul_f32_e32 v35, 0xbfb8aa3b, v38
	v_exp_f32_e32 v36, v35
	v_mul_f32_e32 v35, 0xbfb8aa3b, v39
	v_exp_f32_e32 v37, v35
	v_cvt_pk_bf16_f32 v135, v136, v137
	v_exp_f32_e32 v136, v133
	v_mul_f32_e32 v133, 0xbfb8aa3b, v139
	v_pk_mul_f32 v[36:37], v[36:37], v[100:101]
	v_exp_f32_e32 v137, v133
	v_cvt_pk_bf16_f32 v35, v36, v37
	v_mul_f32_e32 v133, 0xbfb8aa3b, v140
	v_exp_f32_e32 v138, v133
	v_mul_f32_e32 v133, 0xbfb8aa3b, v141
	v_exp_f32_e32 v139, v133
	v_mfma_f32_32x32x16_bf16 v[32:47], v[32:35], v[64:67], 0
	v_mul_f32_e64 v136, v136, v106
	v_mul_f32_e64 v137, v137, v107
	v_cndmask_b32_e64 v133, 0, 1, vcc
	v_mul_f32_e64 v138, v138, v108
	v_mul_f32_e64 v139, v139, v109
	v_cvt_pk_bf16_f32 v136, v136, v137
	v_cvt_pk_bf16_f32 v137, v138, v139
	v_readlane_b32 vcc_lo, v255, 8
	v_readlane_b32 vcc_hi, v255, 9
	v_mfma_f32_32x32x16_bf16 v[32:47], v[134:137], v[68:71], v[32:47]
	s_nop 0
	v_cndmask_b32_e64 v134, 0, 1, vcc
	v_cndmask_b32_e64 v133, v134, v133, s[2:3]
	v_and_b32_e32 v133, 1, v133
	v_cmp_eq_u32_e32 vcc, 1, v133
	s_nop 6
	v_cndmask_b32_e32 v32, 0, v32, vcc
	v_readlane_b32 vcc_lo, v255, 14
	v_readlane_b32 vcc_hi, v255, 15
	s_nop 1
	v_cndmask_b32_e64 v133, 0, 1, vcc
	v_readlane_b32 vcc_lo, v255, 12
	v_readlane_b32 vcc_hi, v255, 13
	s_nop 1
	v_cndmask_b32_e64 v134, 0, 1, vcc
	v_cndmask_b32_e64 v133, v134, v133, s[2:3]
	v_and_b32_e32 v133, 1, v133
	v_cmp_eq_u32_e32 vcc, 1, v133
	s_nop 1
	v_cndmask_b32_e32 v33, 0, v33, vcc
	v_readlane_b32 vcc_lo, v255, 18
	v_readlane_b32 vcc_hi, v255, 19
	v_cvt_pk_bf16_f32 v32, v32, v33
	s_nop 0
	v_cndmask_b32_e64 v133, 0, 1, vcc
	v_readlane_b32 vcc_lo, v255, 16
	v_readlane_b32 vcc_hi, v255, 17
	s_nop 1
	v_cndmask_b32_e64 v134, 0, 1, vcc
	v_cndmask_b32_e64 v133, v134, v133, s[2:3]
	v_and_b32_e32 v133, 1, v133
	v_cmp_eq_u32_e32 vcc, 1, v133
	s_nop 1
	v_cndmask_b32_e32 v34, 0, v34, vcc
	v_readlane_b32 vcc_lo, v255, 22
	v_readlane_b32 vcc_hi, v255, 23
	s_nop 1
	v_cndmask_b32_e64 v133, 0, 1, vcc
	v_readlane_b32 vcc_lo, v255, 20
	v_readlane_b32 vcc_hi, v255, 21
	s_nop 1
	v_cndmask_b32_e64 v134, 0, 1, vcc
	v_cndmask_b32_e64 v133, v134, v133, s[2:3]
	v_and_b32_e32 v133, 1, v133
	v_cmp_eq_u32_e32 vcc, 1, v133
	s_nop 1
	v_cndmask_b32_e32 v35, 0, v35, vcc
	v_readlane_b32 vcc_lo, v255, 26
	v_readlane_b32 vcc_hi, v255, 27
	v_cvt_pk_bf16_f32 v33, v34, v35
	s_nop 0
	v_cndmask_b32_e64 v133, 0, 1, vcc
	v_readlane_b32 vcc_lo, v255, 24
	v_readlane_b32 vcc_hi, v255, 25
	s_nop 1
	v_cndmask_b32_e64 v134, 0, 1, vcc
	v_cndmask_b32_e64 v133, v134, v133, s[2:3]
	v_and_b32_e32 v133, 1, v133
	v_cmp_eq_u32_e32 vcc, 1, v133
	s_nop 1
	v_cndmask_b32_e32 v36, 0, v36, vcc
	v_readlane_b32 vcc_lo, v255, 30
	v_readlane_b32 vcc_hi, v255, 31
	s_nop 1
	v_cndmask_b32_e64 v133, 0, 1, vcc
	v_readlane_b32 vcc_lo, v255, 28
	v_readlane_b32 vcc_hi, v255, 29
	s_nop 1
	v_cndmask_b32_e64 v134, 0, 1, vcc
	v_cndmask_b32_e64 v133, v134, v133, s[2:3]
	v_and_b32_e32 v133, 1, v133
	v_cmp_eq_u32_e32 vcc, 1, v133
	s_nop 1
	v_cndmask_b32_e32 v37, 0, v37, vcc
	v_readlane_b32 vcc_lo, v255, 34
	v_readlane_b32 vcc_hi, v255, 35
	v_cvt_pk_bf16_f32 v34, v36, v37
	s_nop 0
	v_cndmask_b32_e64 v133, 0, 1, vcc
	v_readlane_b32 vcc_lo, v255, 32
	v_readlane_b32 vcc_hi, v255, 33
	s_nop 1
	v_cndmask_b32_e64 v134, 0, 1, vcc
	v_cndmask_b32_e64 v133, v134, v133, s[2:3]
	v_and_b32_e32 v133, 1, v133
	v_cmp_eq_u32_e32 vcc, 1, v133
	s_nop 1
	v_cndmask_b32_e32 v38, 0, v38, vcc
	v_readlane_b32 vcc_lo, v255, 38
	v_readlane_b32 vcc_hi, v255, 39
	s_nop 1
	v_cndmask_b32_e64 v133, 0, 1, vcc
	v_readlane_b32 vcc_lo, v255, 36
	v_readlane_b32 vcc_hi, v255, 37
	s_nop 1
	v_cndmask_b32_e64 v134, 0, 1, vcc
	v_cndmask_b32_e64 v133, v134, v133, s[2:3]
	v_and_b32_e32 v133, 1, v133
	v_cmp_eq_u32_e32 vcc, 1, v133
	s_nop 1
	v_cndmask_b32_e32 v39, 0, v39, vcc
	v_readlane_b32 vcc_lo, v255, 42
	v_readlane_b32 vcc_hi, v255, 43
	v_cvt_pk_bf16_f32 v35, v38, v39
	s_nop 0
	v_cndmask_b32_e64 v133, 0, 1, vcc
	v_readlane_b32 vcc_lo, v255, 40
	v_readlane_b32 vcc_hi, v255, 41
	s_nop 1
	v_cndmask_b32_e64 v134, 0, 1, vcc
	v_cndmask_b32_e64 v133, v134, v133, s[2:3]
	v_and_b32_e32 v133, 1, v133
	v_cmp_eq_u32_e32 vcc, 1, v133
	v_cndmask_b32_e64 v133, 0, 1, s[76:77]
	v_cndmask_b32_e64 v134, 0, 1, s[74:75]
	v_cndmask_b32_e64 v133, v134, v133, s[2:3]
	v_and_b32_e32 v133, 1, v133
	v_cndmask_b32_e32 v40, 0, v40, vcc
	v_cmp_eq_u32_e32 vcc, 1, v133
	v_cndmask_b32_e64 v133, 0, 1, s[80:81]
	v_cndmask_b32_e64 v134, 0, 1, s[78:79]
	v_cndmask_b32_e64 v133, v134, v133, s[2:3]
	v_and_b32_e32 v133, 1, v133
	v_cndmask_b32_e32 v41, 0, v41, vcc
	v_cmp_eq_u32_e32 vcc, 1, v133
	v_cndmask_b32_e64 v133, 0, 1, s[84:85]
	v_cndmask_b32_e64 v134, 0, 1, s[82:83]
	v_cndmask_b32_e64 v133, v134, v133, s[2:3]
	v_and_b32_e32 v133, 1, v133
	v_cndmask_b32_e32 v42, 0, v42, vcc
	v_cmp_eq_u32_e32 vcc, 1, v133
	v_cndmask_b32_e64 v133, 0, 1, s[88:89]
	v_cndmask_b32_e64 v134, 0, 1, s[86:87]
	v_cndmask_b32_e32 v43, 0, v43, vcc
	v_cndmask_b32_e64 v133, v134, v133, s[2:3]
	v_and_b32_e32 v133, 1, v133
	v_cvt_pk_bf16_f32 v36, v40, v41
	v_cvt_pk_bf16_f32 v37, v42, v43
	ds_read_b64_tr_b16 v[40:41], v75 offset:34816
	ds_read_b64_tr_b16 v[42:43], v75 offset:39168
	v_cmp_eq_u32_e32 vcc, 1, v133
	v_cndmask_b32_e64 v133, 0, 1, s[92:93]
	v_cndmask_b32_e64 v134, 0, 1, s[90:91]
	v_cndmask_b32_e64 v133, v134, v133, s[2:3]
	v_and_b32_e32 v133, 1, v133
	v_cndmask_b32_e32 v44, 0, v44, vcc
	v_cmp_eq_u32_e32 vcc, 1, v133
	v_cndmask_b32_e64 v133, 0, 1, s[96:97]
	v_cndmask_b32_e64 v134, 0, 1, s[94:95]
	v_cndmask_b32_e64 v133, v134, v133, s[2:3]
	s_waitcnt lgkmcnt(0)
; #define LAS __attribute__((address_space(3)))
; DI unsigned pk2(float lo, float hi) { f32x2 v = {lo, hi}; bf2_t r = __builtin_convertvector(v, bf2_t); return __builtin_bit_cast(unsigned, r); }
; DI float bflo(unsigned u) { return __uint_as_float(u << 16); }
; DI float bfhi(unsigned u) { return __uint_as_float(u & 0xffff0000u); }
; DI int crow(int i, int h) { return (i & 3) + 8 * (i >> 2) + 4 * h; }
; #define MFMA32(a, b, c) __builtin_amdgcn_mfma_f32_32x32x16_bf16((a), (b), (c), 0, 0, 0)
; DI s16x4 trr(const LAS bf16_t* p) { return __builtin_amdgcn_ds_read_tr16_b64_v4i16((LAS s16x4*)p); }
; DI bf16x8 cat4(s16x4 a, s16x4 b) { return __builtin_shufflevector(a, b, 0, 1, 2, 3, 4, 5, 6, 7); }
; DI void gla_out_item(const KP& P, int layer, int b, int tb, LAS unsigned char* lds) {
;     ...
;         for (int jt = 0; jt < 2; ++jt) { f32x16 S = zero16();
; #pragma unroll
;             for (int kk = 0; kk < 2; ++kk) { const int d0 = hd * 32 + 16 * kk + 8 * h; const u32x4 kv = *(const LAS u32x4*)(Kt + (32 * jt + r) * QP + d0);
;                 const LAS float* bp = Bt + (32 * jt + r) * BP + dir * 128 + d0; const f32x4 b0 = *(const LAS f32x4*)bp, b1 = *(const LAS f32x4*)(bp + 4);
;                 u32x4 o; o.x = pk2(bflo(kv.x) * __expf(-b0[0]), bfhi(kv.x) * __expf(-b0[1])); o.y = pk2(bflo(kv.y) * __expf(-b0[2]), bfhi(kv.y) * __expf(-b0[3]));
;                 o.z = pk2(bflo(kv.z) * __expf(-b1[0]), bfhi(kv.z) * __expf(-b1[1])); o.w = pk2(bflo(kv.w) * __expf(-b1[2]), bfhi(kv.w) * __expf(-b1[3]));
;                 S = MFMA32(as_bf8(o), Qf[kk], S); }
; #pragma unroll
;             for (int i = 0; i < 16; ++i) { const int s = 32 * jt + crow(i, h); const bool keep = dir ? (s >= t) : (s <= t); S[i] = keep ? S[i] : 0.f; }
;             const bf16x8 Pf0 = pack8(S, 0), Pf1 = pack8(S, 1);
; #pragma unroll
;             for (int nt = 0; nt < 2; ++nt) { const LAS bf16_t* vp = Vt + vtr + (32 * jt) * VP + 32 * nt;
;                 accO[nt] = MFMA32(cat4(trr(vp), trr(vp + 8 * VP)), Pf0, accO[nt]);
;                 accO[nt] = MFMA32(cat4(trr(vp + 16 * VP), trr(vp + 24 * VP)), Pf1, accO[nt]); } }
	v_mfma_f32_32x32x16_bf16 v[16:31], v[40:43], v[32:35], v[16:31]
	v_and_b32_e32 v133, 1, v133
	v_cndmask_b32_e32 v45, 0, v45, vcc
	v_cmp_eq_u32_e32 vcc, 1, v133
	v_cndmask_b32_e64 v133, 0, 1, s[70:71]
	v_cndmask_b32_e64 v134, 0, 1, s[0:1]
	v_cndmask_b32_e64 v133, v134, v133, s[2:3]
	ds_read_b64_tr_b16 v[40:41], v75 offset:43520
	ds_read_b64_tr_b16 v[42:43], v75 offset:47872
	v_and_b32_e32 v133, 1, v133
	v_cndmask_b32_e32 v46, 0, v46, vcc
	v_cmp_eq_u32_e32 vcc, 1, v133
	v_cvt_pk_bf16_f32 v38, v44, v45
	v_add3_u32 v133, s33, v129, v131
	v_cndmask_b32_e32 v47, 0, v47, vcc
	v_cvt_pk_bf16_f32 v39, v46, v47
	s_mov_b32 s33, 1
	s_waitcnt lgkmcnt(0)
	v_mfma_f32_32x32x16_bf16 v[16:31], v[40:43], v[36:39], v[16:31]
	ds_read_b64_tr_b16 v[40:41], v75 offset:34880
	ds_read_b64_tr_b16 v[42:43], v75 offset:39232
	s_waitcnt lgkmcnt(0)
	v_mfma_f32_32x32x16_bf16 v[0:15], v[40:43], v[32:35], v[0:15]
	ds_read_b64_tr_b16 v[32:33], v75 offset:43584
	ds_read_b64_tr_b16 v[34:35], v75 offset:47936
	s_waitcnt lgkmcnt(0)
	v_mfma_f32_32x32x16_bf16 v[0:15], v[32:35], v[36:39], v[0:15]
	ds_read_b128 v[32:35], v133
	ds_read_b128 v[36:39], v133 offset:16
	ds_read_b128 v[134:137], v133 offset:64
	ds_read_b128 v[138:141], v133 offset:80
	s_waitcnt lgkmcnt(3)
	v_mul_f32_e32 v32, 0xbfb8aa3b, v32
	v_mul_f32_e32 v33, 0xbfb8aa3b, v33
	v_exp_f32_e32 v32, v32
	v_exp_f32_e32 v33, v33
	s_waitcnt lgkmcnt(1)
	v_mul_f32_e32 v133, 0xbfb8aa3b, v134
	v_exp_f32_e32 v134, v133
	v_mul_f32_e32 v133, 0xbfb8aa3b, v135
	v_pk_mul_f32 v[32:33], v[32:33], v[110:111]
	v_exp_f32_e32 v135, v133
	v_cvt_pk_bf16_f32 v32, v32, v33
	v_mul_f32_e32 v33, 0xbfb8aa3b, v34
	v_exp_f32_e32 v34, v33
	v_mul_f32_e32 v33, 0xbfb8aa3b, v35
	v_exp_f32_e32 v35, v33
	v_mul_f32_e32 v133, 0xbfb8aa3b, v136
	v_exp_f32_e32 v136, v133
	v_mul_f32_e32 v133, 0xbfb8aa3b, v137
	v_pk_mul_f32 v[34:35], v[34:35], v[114:115]
	v_exp_f32_e32 v137, v133
	v_cvt_pk_bf16_f32 v33, v34, v35
	v_mul_f32_e32 v34, 0xbfb8aa3b, v36
	v_mul_f32_e32 v35, 0xbfb8aa3b, v37
	v_exp_f32_e32 v34, v34
	v_exp_f32_e32 v35, v35
	v_pk_mul_f32 v[134:135], v[134:135], v[120:121]
	v_pk_mul_f32 v[136:137], v[136:137], v[122:123]
	s_waitcnt lgkmcnt(0)
	v_mul_f32_e32 v133, 0xbfb8aa3b, v138
	v_pk_mul_f32 v[34:35], v[34:35], v[116:117]
	v_cvt_pk_bf16_f32 v134, v134, v135
	v_cvt_pk_bf16_f32 v34, v34, v35
	v_mul_f32_e32 v35, 0xbfb8aa3b, v38
	v_exp_f32_e32 v36, v35
	v_mul_f32_e32 v35, 0xbfb8aa3b, v39
	v_exp_f32_e32 v37, v35
	v_cvt_pk_bf16_f32 v135, v136, v137
	v_exp_f32_e32 v136, v133
	v_mul_f32_e32 v133, 0xbfb8aa3b, v139
	v_pk_mul_f32 v[36:37], v[36:37], v[118:119]
	v_exp_f32_e32 v137, v133
	v_cvt_pk_bf16_f32 v35, v36, v37
	v_mul_f32_e32 v133, 0xbfb8aa3b, v140
	v_exp_f32_e32 v138, v133
	v_mul_f32_e32 v133, 0xbfb8aa3b, v141
	v_exp_f32_e32 v139, v133
	v_mfma_f32_32x32x16_bf16 v[32:47], v[32:35], v[64:67], 0
	v_mul_f32_e64 v136, v136, v124
	v_mul_f32_e64 v137, v137, v125
	v_cndmask_b32_e64 v133, 0, 1, s[6:7]
	v_mul_f32_e64 v138, v138, v126
	v_mul_f32_e64 v139, v139, v127
	v_cvt_pk_bf16_f32 v136, v136, v137
	v_cvt_pk_bf16_f32 v137, v138, v139
	s_nop 1
	v_mfma_f32_32x32x16_bf16 v[32:47], v[134:137], v[68:71], v[32:47]
	v_cndmask_b32_e64 v134, 0, 1, s[4:5]
	v_cndmask_b32_e64 v133, v134, v133, s[2:3]
	v_and_b32_e32 v133, 1, v133
	v_cmp_eq_u32_e32 vcc, 1, v133
	v_cndmask_b32_e64 v133, 0, 1, s[10:11]
	v_cndmask_b32_e64 v134, 0, 1, s[8:9]
	v_cndmask_b32_e64 v133, v134, v133, s[2:3]
	v_and_b32_e32 v133, 1, v133
	s_nop 3
	v_cndmask_b32_e32 v32, 0, v32, vcc
	v_cmp_eq_u32_e32 vcc, 1, v133
	v_cndmask_b32_e64 v133, 0, 1, s[14:15]
	v_cndmask_b32_e64 v134, 0, 1, s[12:13]
	v_cndmask_b32_e64 v133, v134, v133, s[2:3]
	v_and_b32_e32 v133, 1, v133
	v_cndmask_b32_e32 v33, 0, v33, vcc
	v_cmp_eq_u32_e32 vcc, 1, v133
	v_cndmask_b32_e64 v133, 0, 1, s[18:19]
	v_cndmask_b32_e64 v134, 0, 1, s[16:17]
	v_cndmask_b32_e64 v133, v134, v133, s[2:3]
	v_and_b32_e32 v133, 1, v133
	v_cndmask_b32_e32 v34, 0, v34, vcc
	v_cmp_eq_u32_e32 vcc, 1, v133
	v_cndmask_b32_e64 v133, 0, 1, s[22:23]
	v_cndmask_b32_e64 v134, 0, 1, s[20:21]
	v_cndmask_b32_e64 v133, v134, v133, s[2:3]
	v_and_b32_e32 v133, 1, v133
	v_cndmask_b32_e32 v35, 0, v35, vcc
	v_cmp_eq_u32_e32 vcc, 1, v133
	v_cndmask_b32_e64 v133, 0, 1, s[26:27]
	v_cndmask_b32_e64 v134, 0, 1, s[24:25]
	v_cndmask_b32_e64 v133, v134, v133, s[2:3]
	v_and_b32_e32 v133, 1, v133
	v_cndmask_b32_e32 v36, 0, v36, vcc
	v_cmp_eq_u32_e32 vcc, 1, v133
	v_cndmask_b32_e64 v133, 0, 1, s[30:31]
	v_cndmask_b32_e64 v134, 0, 1, s[28:29]
	v_cndmask_b32_e64 v133, v134, v133, s[2:3]
	v_and_b32_e32 v133, 1, v133
	v_cndmask_b32_e32 v37, 0, v37, vcc
	v_cmp_eq_u32_e32 vcc, 1, v133
	v_cndmask_b32_e64 v133, 0, 1, s[34:35]
	v_cndmask_b32_e64 v134, 0, 1, s[36:37]
	v_cndmask_b32_e64 v133, v134, v133, s[2:3]
	v_and_b32_e32 v133, 1, v133
	v_cndmask_b32_e32 v38, 0, v38, vcc
	v_cmp_eq_u32_e32 vcc, 1, v133
	v_cndmask_b32_e64 v133, 0, 1, s[40:41]
	v_cndmask_b32_e64 v134, 0, 1, s[38:39]
	v_cndmask_b32_e64 v133, v134, v133, s[2:3]
	v_and_b32_e32 v133, 1, v133
	v_cndmask_b32_e32 v39, 0, v39, vcc
	v_cmp_eq_u32_e32 vcc, 1, v133
	v_cndmask_b32_e64 v133, 0, 1, s[44:45]
	v_cndmask_b32_e64 v134, 0, 1, s[42:43]
	v_cndmask_b32_e64 v133, v134, v133, s[2:3]
	v_and_b32_e32 v133, 1, v133
	v_cndmask_b32_e32 v40, 0, v40, vcc
	v_cmp_eq_u32_e32 vcc, 1, v133
	v_cndmask_b32_e64 v133, 0, 1, s[48:49]
	v_cndmask_b32_e64 v134, 0, 1, s[46:47]
	v_cndmask_b32_e64 v133, v134, v133, s[2:3]
	v_and_b32_e32 v133, 1, v133
	v_cndmask_b32_e32 v41, 0, v41, vcc
	v_cmp_eq_u32_e32 vcc, 1, v133
	v_cndmask_b32_e64 v133, 0, 1, s[52:53]
	v_cndmask_b32_e64 v134, 0, 1, s[50:51]
	v_cndmask_b32_e64 v133, v134, v133, s[2:3]
	v_and_b32_e32 v133, 1, v133
	v_cndmask_b32_e32 v42, 0, v42, vcc
	v_cmp_eq_u32_e32 vcc, 1, v133
	v_cndmask_b32_e64 v133, 0, 1, s[56:57]
	v_cndmask_b32_e64 v134, 0, 1, s[54:55]
	v_cndmask_b32_e32 v43, 0, v43, vcc
	v_cndmask_b32_e64 v133, v134, v133, s[2:3]
	v_and_b32_e32 v133, 1, v133
	v_cvt_pk_bf16_f32 v32, v32, v33
	v_cvt_pk_bf16_f32 v33, v34, v35
	v_cvt_pk_bf16_f32 v34, v36, v37
	v_cvt_pk_bf16_f32 v36, v40, v41
	v_cvt_pk_bf16_f32 v37, v42, v43
	ds_read_b64_tr_b16 v[40:41], v75 offset:52224
	ds_read_b64_tr_b16 v[42:43], v75 offset:56576
	v_cmp_eq_u32_e32 vcc, 1, v133
	v_cndmask_b32_e64 v133, 0, 1, s[60:61]
	v_cndmask_b32_e64 v134, 0, 1, s[58:59]
	v_cndmask_b32_e64 v133, v134, v133, s[2:3]
	v_and_b32_e32 v133, 1, v133
	v_cndmask_b32_e32 v44, 0, v44, vcc
	v_cmp_eq_u32_e32 vcc, 1, v133
	v_cndmask_b32_e64 v133, 0, 1, s[64:65]
	v_cndmask_b32_e64 v134, 0, 1, s[62:63]
	v_cvt_pk_bf16_f32 v35, v38, v39
	v_cndmask_b32_e64 v133, v134, v133, s[2:3]
	v_and_b32_e32 v133, 1, v133
	s_waitcnt lgkmcnt(0)
; #define LAS __attribute__((address_space(3)))
; DI unsigned pk2(float lo, float hi) { f32x2 v = {lo, hi}; bf2_t r = __builtin_convertvector(v, bf2_t); return __builtin_bit_cast(unsigned, r); }
; DI float bflo(unsigned u) { return __uint_as_float(u << 16); }
; DI float bfhi(unsigned u) { return __uint_as_float(u & 0xffff0000u); }
; #define MFMA32(a, b, c) __builtin_amdgcn_mfma_f32_32x32x16_bf16((a), (b), (c), 0, 0, 0)
; DI s16x4 trr(const LAS bf16_t* p) { return __builtin_amdgcn_ds_read_tr16_b64_v4i16((LAS s16x4*)p); }
; DI bf16x8 cat4(s16x4 a, s16x4 b) { return __builtin_shufflevector(a, b, 0, 1, 2, 3, 4, 5, 6, 7); }
; DI void gla_out_item(const KP& P, int layer, int b, int tb, LAS unsigned char* lds) {
;     ...
;             for (int nt = 0; nt < 2; ++nt) { const LAS bf16_t* vp = Vt + vtr + (32 * jt) * VP + 32 * nt;
;                 accO[nt] = MFMA32(cat4(trr(vp), trr(vp + 8 * VP)), Pf0, accO[nt]);
;                 accO[nt] = MFMA32(cat4(trr(vp + 16 * VP), trr(vp + 24 * VP)), Pf1, accO[nt]); } }
; #pragma unroll
;         for (int nt = 0; nt < 2; ++nt)
; #pragma unroll
;             for (int kk = 0; kk < 2; ++kk) accO[nt] = MFMA32(as_bf8(Sf[nt][kk]), Qf[kk], accO[nt]);
;     }
;     float ss = 0.f;
; #pragma unroll
;     for (int nt = 0; nt < 2; ++nt)
; #pragma unroll
;         for (int i = 0; i < 16; ++i) ss += accO[nt][i] * accO[nt][i];
;     ss += __shfl_xor(ss, 32);
;     const float rstd = rsqrtf(ss * (1.f / 64.f) + EPS);
;     u32x2 og[8];
; #pragma unroll
;     for (int nt = 0; nt < 2; ++nt)
; #pragma unroll
;         for (int g4 = 0; g4 < 4; ++g4) { const int dv = 32 * nt + 8 * g4 + 4 * h;
;             const u32x2 rv = ldg8(Z + (R0 + t) * ZW + C_RC + hd * 64 + dv); const f32x4 gg = *(const f32x4*)(P.g_gla_out + layer * 64 + dv);
;             const float rr[4] = {bflo(rv.x), bfhi(rv.x), bflo(rv.y), bfhi(rv.y)}; float y[4];
; #pragma unroll
;             for (int e = 0; e < 4; ++e) { const float sl = rr[e] / (1.f + __expf(-rr[e])); y[e] = accO[nt][4 * g4 + e] * rstd * gg[e] * sl; }
;             og[4 * nt + g4].x = pk2(y[0], y[1]); og[4 * nt + g4].y = pk2(y[2], y[3]); }
	v_mfma_f32_32x32x16_bf16 v[16:31], v[40:43], v[32:35], v[16:31]
	v_cndmask_b32_e32 v45, 0, v45, vcc
	v_cmp_eq_u32_e32 vcc, 1, v133
	v_cndmask_b32_e64 v133, 0, 1, s[68:69]
	v_cndmask_b32_e64 v134, 0, 1, s[66:67]
	v_cndmask_b32_e64 v133, v134, v133, s[2:3]
	ds_read_b64_tr_b16 v[40:41], v75 offset:60928
	ds_read_b64_tr_b16 v[42:43], v75 offset:65280
	v_and_b32_e32 v133, 1, v133
	v_cndmask_b32_e32 v46, 0, v46, vcc
	v_cmp_eq_u32_e32 vcc, 1, v133
	v_cvt_pk_bf16_f32 v38, v44, v45
	s_nop 0
	v_cndmask_b32_e32 v47, 0, v47, vcc
	v_cvt_pk_bf16_f32 v39, v46, v47
	s_and_b64 vcc, s[2:3], exec
	s_mov_b64 s[2:3], 0
	s_waitcnt lgkmcnt(0)
	v_mfma_f32_32x32x16_bf16 v[16:31], v[40:43], v[36:39], v[16:31]
	ds_read_b64_tr_b16 v[40:41], v75 offset:52288
	ds_read_b64_tr_b16 v[42:43], v75 offset:56640
	s_waitcnt lgkmcnt(0)
	v_mfma_f32_32x32x16_bf16 v[0:15], v[40:43], v[32:35], v[0:15]
	ds_read_b64_tr_b16 v[32:33], v75 offset:60992
	ds_read_b64_tr_b16 v[34:35], v75 offset:65344
	s_waitcnt lgkmcnt(0)
	v_mfma_f32_32x32x16_bf16 v[0:15], v[32:35], v[36:39], v[0:15]
	s_waitcnt vmcnt(3)
	v_mfma_f32_32x32x16_bf16 v[16:31], v[56:59], v[64:67], v[16:31]
	s_waitcnt vmcnt(1)
	v_mfma_f32_32x32x16_bf16 v[0:15], v[52:55], v[64:67], v[0:15]
	v_mfma_f32_32x32x16_bf16 v[16:31], v[60:63], v[68:71], v[16:31]
	s_waitcnt vmcnt(0)
	v_mfma_f32_32x32x16_bf16 v[0:15], v[48:51], v[68:71], v[0:15]
	s_cbranch_vccnz .LBB0_618
	s_nop 8
	v_mul_f32_e32 v42, v17, v17
	v_fmac_f32_e32 v42, v16, v16
	v_fmac_f32_e32 v42, v18, v18
	v_fmac_f32_e32 v42, v19, v19
	v_fmac_f32_e32 v42, v20, v20
	v_fmac_f32_e32 v42, v21, v21
	v_fmac_f32_e32 v42, v22, v22
	v_fmac_f32_e32 v42, v23, v23
	v_fmac_f32_e32 v42, v24, v24
	v_fmac_f32_e32 v42, v25, v25
	v_fmac_f32_e32 v42, v26, v26
	v_fmac_f32_e32 v42, v27, v27
	v_fmac_f32_e32 v42, v28, v28
	v_fmac_f32_e32 v42, v29, v29
	v_fmac_f32_e32 v42, v30, v30
	v_fmac_f32_e32 v42, v31, v31
	v_fmac_f32_e32 v42, v0, v0
	v_fmac_f32_e32 v42, v1, v1
	v_fmac_f32_e32 v42, v2, v2
	v_fmac_f32_e32 v42, v3, v3
	v_fmac_f32_e32 v42, v4, v4
	v_fmac_f32_e32 v42, v5, v5
	v_pk_mul_f32 v[40:41], v[6:7], v[6:7]
	v_pk_mul_f32 v[38:39], v[8:9], v[8:9]
	v_add_f32_e32 v40, v40, v42
	v_add_f32_e32 v40, v41, v40
	v_add_f32_e32 v38, v38, v40
	v_pk_mul_f32 v[36:37], v[10:11], v[10:11]
	v_add_f32_e32 v38, v39, v38
	v_add_f32_e32 v36, v36, v38
	v_pk_mul_f32 v[34:35], v[12:13], v[12:13]
	v_add_f32_e32 v36, v37, v36
	v_add_f32_e32 v34, v34, v36
	v_pk_mul_f32 v[32:33], v[14:15], v[14:15]
	v_add_f32_e32 v34, v35, v34
	v_add_f32_e32 v32, v32, v34
	v_add_f32_e32 v32, v33, v32
	v_xor_b32_e32 v33, 32, v190
	v_cmp_lt_i32_e32 vcc, v33, v191
	s_mov_b32 s0, 0x800000
	v_ashrrev_i32_e32 v75, 31, v74
	v_cndmask_b32_e32 v33, v190, v33, vcc
	v_lshlrev_b32_e32 v33, 2, v33
	ds_bpermute_b32 v33, v33, v32
	s_movk_i32 s2, 0x1800
	v_lshlrev_b32_e32 v112, 1, v128
	v_readlane_b32 s21, v255, 6
	v_readlane_b32 s28, v254, 47
	s_waitcnt lgkmcnt(0)
	v_add_f32_e32 v32, v32, v33
	v_fmamk_f32 v32, v32, 0x3c800000, v144
	v_cmp_gt_f32_e32 vcc, s0, v32
	v_readlane_b32 s0, v255, 3
	v_readlane_b32 s1, v255, 4
	v_mul_f32_e32 v33, 0x4b800000, v32
	v_cndmask_b32_e32 v32, v32, v33, vcc
	v_lshl_add_u64 v[34:35], s[0:1], 0, v[74:75]
	v_readlane_b32 s0, v253, 12
	v_readlane_b32 s1, v253, 13
	v_rsq_f32_e32 v32, v32
	s_movk_i32 s68, 0x1800
	v_mov_b64_e32 v[36:37], s[0:1]
	v_mad_u64_u32 v[36:37], s[0:1], v34, s2, v[36:37]
	v_mov_b32_e32 v38, v37
	v_mad_u64_u32 v[38:39], s[0:1], v35, s2, v[38:39]
	v_mov_b32_e32 v37, v38
	v_lshl_add_u64 v[36:37], v[36:37], 0, v[112:113]
	v_lshlrev_b32_e32 v38, 1, v73
	v_mov_b32_e32 v39, v113
	v_lshl_add_u64 v[36:37], v[36:37], 0, v[38:39]
	global_load_dwordx2 v[42:43], v[36:37], off offset:3072
	v_mul_f32_e32 v33, 0x45800000, v32
	v_readlane_b32 s2, v255, 1
	v_cndmask_b32_e32 v32, v32, v33, vcc
	v_lshlrev_b32_e32 v33, 2, v73
	v_readlane_b32 s3, v255, 2
	v_pk_mul_f32 v[16:17], v[16:17], v[32:33] op_sel_hi:[1,0]
	v_pk_mul_f32 v[18:19], v[18:19], v[32:33] op_sel_hi:[1,0]
	v_pk_mul_f32 v[20:21], v[20:21], v[32:33] op_sel_hi:[1,0]
	v_pk_mul_f32 v[22:23], v[22:23], v[32:33] op_sel_hi:[1,0]
	v_pk_mul_f32 v[24:25], v[24:25], v[32:33] op_sel_hi:[1,0]
	global_load_dwordx4 v[38:41], v33, s[2:3]
	global_load_dwordx2 v[156:157], v[36:37], off offset:3088
	global_load_dwordx4 v[204:207], v33, s[2:3] offset:32
	global_load_dwordx2 v[158:159], v[36:37], off offset:3104
	global_load_dwordx4 v[208:211], v33, s[2:3] offset:64
	global_load_dwordx2 v[160:161], v[36:37], off offset:3120
	global_load_dwordx4 v[212:215], v33, s[2:3] offset:96
	global_load_dwordx2 v[162:163], v[36:37], off offset:3136
	global_load_dwordx4 v[216:219], v33, s[2:3] offset:128
	global_load_dwordx2 v[164:165], v[36:37], off offset:3152
	global_load_dwordx4 v[220:223], v33, s[2:3] offset:160
	global_load_dwordx2 v[166:167], v[36:37], off offset:3168
	global_load_dwordx4 v[224:227], v33, s[2:3] offset:192
	global_load_dwordx2 v[168:169], v[36:37], off offset:3184
	global_load_dwordx4 v[228:231], v33, s[2:3] offset:224
	v_pk_mul_f32 v[26:27], v[26:27], v[32:33] op_sel_hi:[1,0]
	v_pk_mul_f32 v[28:29], v[28:29], v[32:33] op_sel_hi:[1,0]
	v_pk_mul_f32 v[0:1], v[0:1], v[32:33] op_sel_hi:[1,0]
	v_pk_mul_f32 v[2:3], v[2:3], v[32:33] op_sel_hi:[1,0]
	v_pk_mul_f32 v[4:5], v[4:5], v[32:33] op_sel_hi:[1,0]
	v_pk_mul_f32 v[6:7], v[6:7], v[32:33] op_sel_hi:[1,0]
	v_pk_mul_f32 v[8:9], v[8:9], v[32:33] op_sel_hi:[1,0]
	v_pk_mul_f32 v[10:11], v[10:11], v[32:33] op_sel_hi:[1,0]
	v_pk_mul_f32 v[12:13], v[12:13], v[32:33] op_sel_hi:[1,0]
	v_readlane_b32 s29, v254, 48
	s_movk_i32 s36, 0x44
	s_waitcnt vmcnt(15)
; DI unsigned pk2(float lo, float hi) { f32x2 v = {lo, hi}; bf2_t r = __builtin_convertvector(v, bf2_t); return __builtin_bit_cast(unsigned, r); }
; DI float bflo(unsigned u) { return __uint_as_float(u << 16); }
; DI float bfhi(unsigned u) { return __uint_as_float(u & 0xffff0000u); }
; DI void gla_out_item(const KP& P, int layer, int b, int tb, LAS unsigned char* lds) {
;     ...
;         for (int g4 = 0; g4 < 4; ++g4) { const int dv = 32 * nt + 8 * g4 + 4 * h;
;             const u32x2 rv = ldg8(Z + (R0 + t) * ZW + C_RC + hd * 64 + dv); const f32x4 gg = *(const f32x4*)(P.g_gla_out + layer * 64 + dv);
;             const float rr[4] = {bflo(rv.x), bfhi(rv.x), bflo(rv.y), bfhi(rv.y)}; float y[4];
; #pragma unroll
;             for (int e = 0; e < 4; ++e) { const float sl = rr[e] / (1.f + __expf(-rr[e])); y[e] = accO[nt][4 * g4 + e] * rstd * gg[e] * sl; }
;             og[4 * nt + g4].x = pk2(y[0], y[1]); og[4 * nt + g4].y = pk2(y[2], y[3]); }
	v_lshlrev_b32_e32 v46, 16, v42
	v_and_b32_e32 v42, 0xffff0000, v42
	v_mul_f32_e32 v44, 0xbfb8aa3b, v46
	v_mul_f32_e32 v45, 0xbfb8aa3b, v42
	v_exp_f32_e32 v44, v44
	v_exp_f32_e32 v45, v45
	s_waitcnt vmcnt(14)
	v_pk_mul_f32 v[16:17], v[38:39], v[16:17]
	v_pk_add_f32 v[44:45], v[44:45], 1.0 op_sel_hi:[1,0]
	v_pk_mul_f32 v[18:19], v[40:41], v[18:19]
	v_div_scale_f32 v47, s[0:1], v45, v45, v42
	v_rcp_f32_e32 v48, v47
	s_nop 0
	v_fma_f32 v49, -v47, v48, 1.0
	v_fmac_f32_e32 v48, v49, v48
	v_div_scale_f32 v49, vcc, v42, v45, v42
	v_mul_f32_e32 v50, v49, v48
	v_fma_f32 v51, -v47, v50, v49
	v_fmac_f32_e32 v50, v51, v48
	v_fma_f32 v47, -v47, v50, v49
	v_div_fmas_f32 v47, v47, v48, v50
	v_div_fixup_f32 v45, v47, v45, v42
	v_div_scale_f32 v42, s[0:1], v44, v44, v46
	v_rcp_f32_e32 v47, v42
	s_nop 0
	v_fma_f32 v48, -v42, v47, 1.0
	v_fmac_f32_e32 v47, v48, v47
	v_div_scale_f32 v48, vcc, v46, v44, v46
	v_mul_f32_e32 v49, v48, v47
	v_fma_f32 v50, -v42, v49, v48
	v_fmac_f32_e32 v49, v50, v47
	v_fma_f32 v42, -v42, v49, v48
	v_div_fmas_f32 v42, v42, v47, v49
	v_div_fixup_f32 v44, v42, v44, v46
	v_lshlrev_b32_e32 v42, 16, v43
	v_and_b32_e32 v43, 0xffff0000, v43
	v_mul_f32_e32 v38, 0xbfb8aa3b, v42
	v_mul_f32_e32 v39, 0xbfb8aa3b, v43
	v_exp_f32_e32 v38, v38
	v_exp_f32_e32 v39, v39
	v_pk_mul_f32 v[16:17], v[44:45], v[16:17]
	v_pk_add_f32 v[38:39], v[38:39], 1.0 op_sel_hi:[1,0]
	s_nop 0
	v_div_scale_f32 v44, s[0:1], v39, v39, v43
	v_rcp_f32_e32 v45, v44
	v_cvt_pk_bf16_f32 v16, v16, v17
	v_fma_f32 v46, -v44, v45, 1.0
	v_fmac_f32_e32 v45, v46, v45
	v_div_scale_f32 v46, vcc, v43, v39, v43
	v_mul_f32_e32 v47, v46, v45
	v_fma_f32 v48, -v44, v47, v46
	v_fmac_f32_e32 v47, v48, v45
	v_fma_f32 v44, -v44, v47, v46
	v_div_fmas_f32 v44, v44, v45, v47
	v_div_fixup_f32 v39, v44, v39, v43
	v_div_scale_f32 v43, s[0:1], v38, v38, v42
	v_rcp_f32_e32 v44, v43
	s_nop 0
	v_fma_f32 v45, -v43, v44, 1.0
	v_fmac_f32_e32 v44, v45, v44
	v_div_scale_f32 v45, vcc, v42, v38, v42
	v_mul_f32_e32 v46, v45, v44
	v_fma_f32 v47, -v43, v46, v45
	v_fmac_f32_e32 v46, v47, v44
	v_fma_f32 v43, -v43, v46, v45
	v_div_fmas_f32 v43, v43, v44, v46
	v_div_fixup_f32 v38, v43, v38, v42
	v_pk_mul_f32 v[18:19], v[38:39], v[18:19]
	s_nop 0
	v_cvt_pk_bf16_f32 v17, v18, v19
	s_waitcnt vmcnt(13)
	v_mov_b32_e32 v18, v156
	v_mov_b32_e32 v19, v157
	s_nop 0
	s_nop 0
	v_lshlrev_b32_e32 v44, 16, v18
	v_and_b32_e32 v18, 0xffff0000, v18
	v_mul_f32_e32 v42, 0xbfb8aa3b, v44
	v_mul_f32_e32 v43, 0xbfb8aa3b, v18
	v_exp_f32_e32 v42, v42
	v_exp_f32_e32 v43, v43
	s_waitcnt vmcnt(12)
	v_mov_b32_e32 v38, v204
	v_mov_b32_e32 v39, v205
	v_mov_b32_e32 v40, v206
	v_mov_b32_e32 v41, v207
	v_pk_mul_f32 v[20:21], v[38:39], v[20:21]
	v_lshlrev_b32_e32 v38, 16, v19
	v_and_b32_e32 v39, 0xffff0000, v19
	v_pk_add_f32 v[42:43], v[42:43], 1.0 op_sel_hi:[1,0]
	v_mul_f32_e32 v19, 0xbfb8aa3b, v39
	v_div_scale_f32 v45, s[0:1], v43, v43, v18
	v_rcp_f32_e32 v46, v45
	v_exp_f32_e32 v19, v19
	v_pk_mul_f32 v[22:23], v[40:41], v[22:23]
	v_fma_f32 v47, -v45, v46, 1.0
	v_fmac_f32_e32 v46, v47, v46
	v_div_scale_f32 v47, vcc, v18, v43, v18
	v_mul_f32_e32 v48, v47, v46
	v_fma_f32 v49, -v45, v48, v47
	v_fmac_f32_e32 v48, v49, v46
	v_fma_f32 v45, -v45, v48, v47
	v_div_fmas_f32 v45, v45, v46, v48
	v_div_fixup_f32 v43, v45, v43, v18
	v_div_scale_f32 v18, s[0:1], v42, v42, v44
	v_rcp_f32_e32 v45, v18
	s_nop 0
	v_fma_f32 v46, -v18, v45, 1.0
	v_fmac_f32_e32 v45, v46, v45
	v_div_scale_f32 v46, vcc, v44, v42, v44
	v_mul_f32_e32 v47, v46, v45
	v_fma_f32 v48, -v18, v47, v46
	v_fmac_f32_e32 v47, v48, v45
	v_fma_f32 v18, -v18, v47, v46
	v_div_fmas_f32 v18, v18, v45, v47
	v_div_fixup_f32 v42, v18, v42, v44
	v_mul_f32_e32 v18, 0xbfb8aa3b, v38
	v_exp_f32_e32 v18, v18
	v_pk_mul_f32 v[20:21], v[42:43], v[20:21]
	v_pk_add_f32 v[18:19], v[18:19], 1.0 op_sel_hi:[1,0]
	s_nop 0
	v_div_scale_f32 v42, s[0:1], v19, v19, v39
	v_rcp_f32_e32 v43, v42
	s_nop 0
	v_fma_f32 v44, -v42, v43, 1.0
	v_fmac_f32_e32 v43, v44, v43
	v_div_scale_f32 v44, vcc, v39, v19, v39
	v_mul_f32_e32 v45, v44, v43
	v_fma_f32 v46, -v42, v45, v44
	v_fmac_f32_e32 v45, v46, v43
	v_fma_f32 v42, -v42, v45, v44
	v_div_fmas_f32 v42, v42, v43, v45
	v_div_fixup_f32 v19, v42, v19, v39
	v_div_scale_f32 v39, s[0:1], v18, v18, v38
	v_rcp_f32_e32 v42, v39
	s_nop 0
	v_fma_f32 v43, -v39, v42, 1.0
	v_fmac_f32_e32 v42, v43, v42
	v_div_scale_f32 v43, vcc, v38, v18, v38
	v_mul_f32_e32 v44, v43, v42
	v_fma_f32 v45, -v39, v44, v43
	v_fmac_f32_e32 v44, v45, v42
	v_fma_f32 v39, -v39, v44, v43
	v_div_fmas_f32 v39, v39, v42, v44
	v_div_fixup_f32 v18, v39, v18, v38
	v_pk_mul_f32 v[22:23], v[18:19], v[22:23]
	v_cvt_pk_bf16_f32 v18, v20, v21
	v_cvt_pk_bf16_f32 v19, v22, v23
	s_waitcnt vmcnt(11)
	v_mov_b32_e32 v38, v158
	v_mov_b32_e32 v39, v159
	s_nop 0
	v_permlane32_swap_b32_e32 v16, v18
	v_permlane32_swap_b32_e32 v17, v19
	s_nop 0
	v_lshlrev_b32_e32 v42, 16, v38
	v_and_b32_e32 v38, 0xffff0000, v38
	v_mul_f32_e32 v40, 0xbfb8aa3b, v42
	v_mul_f32_e32 v41, 0xbfb8aa3b, v38
	v_exp_f32_e32 v40, v40
	v_exp_f32_e32 v41, v41
	s_waitcnt vmcnt(10)
; DI unsigned pk2(float lo, float hi) { f32x2 v = {lo, hi}; bf2_t r = __builtin_convertvector(v, bf2_t); return __builtin_bit_cast(unsigned, r); }
; DI float bflo(unsigned u) { return __uint_as_float(u << 16); }
; DI float bfhi(unsigned u) { return __uint_as_float(u & 0xffff0000u); }
; DI void gla_out_item(const KP& P, int layer, int b, int tb, LAS unsigned char* lds) {
;     ...
;         for (int g4 = 0; g4 < 4; ++g4) { const int dv = 32 * nt + 8 * g4 + 4 * h;
;             const u32x2 rv = ldg8(Z + (R0 + t) * ZW + C_RC + hd * 64 + dv); const f32x4 gg = *(const f32x4*)(P.g_gla_out + layer * 64 + dv);
;             const float rr[4] = {bflo(rv.x), bfhi(rv.x), bflo(rv.y), bfhi(rv.y)}; float y[4];
; #pragma unroll
;             for (int e = 0; e < 4; ++e) { const float sl = rr[e] / (1.f + __expf(-rr[e])); y[e] = accO[nt][4 * g4 + e] * rstd * gg[e] * sl; }
;             og[4 * nt + g4].x = pk2(y[0], y[1]); og[4 * nt + g4].y = pk2(y[2], y[3]); }
	v_mov_b32_e32 v20, v208
	v_mov_b32_e32 v21, v209
	v_mov_b32_e32 v22, v210
	v_mov_b32_e32 v23, v211
	v_pk_mul_f32 v[20:21], v[20:21], v[24:25]
	v_pk_mul_f32 v[22:23], v[22:23], v[26:27]
	v_pk_add_f32 v[40:41], v[40:41], 1.0 op_sel_hi:[1,0]
	s_nop 0
	v_div_scale_f32 v43, s[0:1], v41, v41, v38
	v_rcp_f32_e32 v44, v43
	s_nop 0
	v_fma_f32 v45, -v43, v44, 1.0
	v_fmac_f32_e32 v44, v45, v44
	v_div_scale_f32 v45, vcc, v38, v41, v38
	v_mul_f32_e32 v46, v45, v44
	v_fma_f32 v47, -v43, v46, v45
	v_fmac_f32_e32 v46, v47, v44
	v_fma_f32 v43, -v43, v46, v45
	v_div_fmas_f32 v43, v43, v44, v46
	v_div_fixup_f32 v41, v43, v41, v38
	v_div_scale_f32 v38, s[0:1], v40, v40, v42
	v_rcp_f32_e32 v43, v38
	s_nop 0
	v_fma_f32 v44, -v38, v43, 1.0
	v_fmac_f32_e32 v43, v44, v43
	v_div_scale_f32 v44, vcc, v42, v40, v42
	v_mul_f32_e32 v45, v44, v43
	v_fma_f32 v46, -v38, v45, v44
	v_fmac_f32_e32 v45, v46, v43
	v_fma_f32 v38, -v38, v45, v44
	v_div_fmas_f32 v38, v38, v43, v45
	v_div_fixup_f32 v40, v38, v40, v42
	v_lshlrev_b32_e32 v38, 16, v39
	v_and_b32_e32 v39, 0xffff0000, v39
	v_mul_f32_e32 v24, 0xbfb8aa3b, v38
	v_mul_f32_e32 v25, 0xbfb8aa3b, v39
	v_exp_f32_e32 v24, v24
	v_exp_f32_e32 v25, v25
	v_pk_mul_f32 v[20:21], v[20:21], v[40:41]
	v_pk_add_f32 v[24:25], v[24:25], 1.0 op_sel_hi:[1,0]
	s_nop 0
	v_div_scale_f32 v40, s[0:1], v25, v25, v39
	v_rcp_f32_e32 v41, v40
	v_cvt_pk_bf16_f32 v20, v20, v21
	v_fma_f32 v42, -v40, v41, 1.0
	v_fmac_f32_e32 v41, v42, v41
	v_div_scale_f32 v42, vcc, v39, v25, v39
	v_mul_f32_e32 v43, v42, v41
	v_fma_f32 v44, -v40, v43, v42
	v_fmac_f32_e32 v43, v44, v41
	v_fma_f32 v40, -v40, v43, v42
	v_div_fmas_f32 v40, v40, v41, v43
	v_div_fixup_f32 v25, v40, v25, v39
	v_div_scale_f32 v39, s[0:1], v24, v24, v38
	v_rcp_f32_e32 v40, v39
	s_nop 0
	v_fma_f32 v41, -v39, v40, 1.0
	v_fmac_f32_e32 v40, v41, v40
	v_div_scale_f32 v41, vcc, v38, v24, v38
	v_mul_f32_e32 v42, v41, v40
	v_fma_f32 v43, -v39, v42, v41
	v_fmac_f32_e32 v42, v43, v40
	v_fma_f32 v39, -v39, v42, v41
	v_div_fmas_f32 v39, v39, v40, v42
	v_div_fixup_f32 v24, v39, v24, v38
	v_pk_mul_f32 v[22:23], v[22:23], v[24:25]
	s_nop 0
	v_cvt_pk_bf16_f32 v21, v22, v23
	s_waitcnt vmcnt(9)
	v_mov_b32_e32 v22, v160
	v_mov_b32_e32 v23, v161
	s_nop 0
	s_nop 0
	v_lshlrev_b32_e32 v40, 16, v22
	v_and_b32_e32 v22, 0xffff0000, v22
	v_mul_f32_e32 v38, 0xbfb8aa3b, v40
	v_mul_f32_e32 v39, 0xbfb8aa3b, v22
	v_exp_f32_e32 v38, v38
	v_exp_f32_e32 v39, v39
	s_waitcnt vmcnt(8)
	v_mov_b32_e32 v24, v212
	v_mov_b32_e32 v25, v213
	v_mov_b32_e32 v26, v214
	v_mov_b32_e32 v27, v215
	v_pk_mul_f32 v[24:25], v[24:25], v[28:29]
	v_lshlrev_b32_e32 v28, 16, v23
	v_and_b32_e32 v29, 0xffff0000, v23
	v_pk_add_f32 v[38:39], v[38:39], 1.0 op_sel_hi:[1,0]
	v_mul_f32_e32 v23, 0xbfb8aa3b, v29
	v_div_scale_f32 v41, s[0:1], v39, v39, v22
	v_rcp_f32_e32 v42, v41
	v_exp_f32_e32 v23, v23
	v_fma_f32 v43, -v41, v42, 1.0
	v_fmac_f32_e32 v42, v43, v42
	v_div_scale_f32 v43, vcc, v22, v39, v22
	v_mul_f32_e32 v44, v43, v42
	v_fma_f32 v45, -v41, v44, v43
	v_fmac_f32_e32 v44, v45, v42
	v_fma_f32 v41, -v41, v44, v43
	v_div_fmas_f32 v41, v41, v42, v44
	v_div_fixup_f32 v39, v41, v39, v22
	v_div_scale_f32 v22, s[0:1], v38, v38, v40
	v_rcp_f32_e32 v41, v22
	s_nop 0
	v_fma_f32 v42, -v22, v41, 1.0
	v_fmac_f32_e32 v41, v42, v41
	v_div_scale_f32 v42, vcc, v40, v38, v40
	v_mul_f32_e32 v43, v42, v41
	v_fma_f32 v44, -v22, v43, v42
	v_fmac_f32_e32 v43, v44, v41
	v_fma_f32 v22, -v22, v43, v42
	v_div_fmas_f32 v22, v22, v41, v43
	v_div_fixup_f32 v38, v22, v38, v40
	v_mul_f32_e32 v22, 0xbfb8aa3b, v28
	v_exp_f32_e32 v22, v22
	v_pk_mul_f32 v[24:25], v[24:25], v[38:39]
	v_pk_add_f32 v[22:23], v[22:23], 1.0 op_sel_hi:[1,0]
	s_nop 0
	v_div_scale_f32 v38, s[0:1], v23, v23, v29
	v_rcp_f32_e32 v39, v38
	s_nop 0
	v_fma_f32 v40, -v38, v39, 1.0
	v_fmac_f32_e32 v39, v40, v39
	v_div_scale_f32 v40, vcc, v29, v23, v29
	v_mul_f32_e32 v41, v40, v39
	v_fma_f32 v42, -v38, v41, v40
	v_fmac_f32_e32 v41, v42, v39
	v_fma_f32 v38, -v38, v41, v40
	v_div_fmas_f32 v38, v38, v39, v41
	v_div_fixup_f32 v23, v38, v23, v29
	v_div_scale_f32 v29, s[0:1], v22, v22, v28
	v_rcp_f32_e32 v38, v29
	s_nop 0
	v_fma_f32 v39, -v29, v38, 1.0
	v_fmac_f32_e32 v38, v39, v38
	v_div_scale_f32 v39, vcc, v28, v22, v28
	v_mul_f32_e32 v40, v39, v38
	v_fma_f32 v41, -v29, v40, v39
	v_fmac_f32_e32 v40, v41, v38
	v_fma_f32 v29, -v29, v40, v39
	v_div_fmas_f32 v29, v29, v38, v40
	v_div_fixup_f32 v22, v29, v22, v28
	v_pk_mul_f32 v[28:29], v[30:31], v[32:33] op_sel_hi:[1,0]
	s_nop 0
	v_pk_mul_f32 v[26:27], v[26:27], v[28:29]
	s_nop 0
	v_pk_mul_f32 v[26:27], v[26:27], v[22:23]
	v_cvt_pk_bf16_f32 v22, v24, v25
	v_cvt_pk_bf16_f32 v23, v26, v27
	s_waitcnt vmcnt(7)
	v_mov_b32_e32 v28, v162
	v_mov_b32_e32 v29, v163
	s_nop 0
	v_permlane32_swap_b32_e32 v20, v22
	v_permlane32_swap_b32_e32 v21, v23
	s_nop 0
	v_lshlrev_b32_e32 v38, 16, v28
	v_and_b32_e32 v28, 0xffff0000, v28
	v_mul_f32_e32 v30, 0xbfb8aa3b, v38
	v_mul_f32_e32 v31, 0xbfb8aa3b, v28
	v_exp_f32_e32 v30, v30
	v_exp_f32_e32 v31, v31
	s_waitcnt vmcnt(6)
; DI unsigned pk2(float lo, float hi) { f32x2 v = {lo, hi}; bf2_t r = __builtin_convertvector(v, bf2_t); return __builtin_bit_cast(unsigned, r); }
; DI float bflo(unsigned u) { return __uint_as_float(u << 16); }
; DI float bfhi(unsigned u) { return __uint_as_float(u & 0xffff0000u); }
; DI void gla_out_item(const KP& P, int layer, int b, int tb, LAS unsigned char* lds) {
;     ...
;         for (int g4 = 0; g4 < 4; ++g4) { const int dv = 32 * nt + 8 * g4 + 4 * h;
;             const u32x2 rv = ldg8(Z + (R0 + t) * ZW + C_RC + hd * 64 + dv); const f32x4 gg = *(const f32x4*)(P.g_gla_out + layer * 64 + dv);
;             const float rr[4] = {bflo(rv.x), bfhi(rv.x), bflo(rv.y), bfhi(rv.y)}; float y[4];
; #pragma unroll
;             for (int e = 0; e < 4; ++e) { const float sl = rr[e] / (1.f + __expf(-rr[e])); y[e] = accO[nt][4 * g4 + e] * rstd * gg[e] * sl; }
;             og[4 * nt + g4].x = pk2(y[0], y[1]); og[4 * nt + g4].y = pk2(y[2], y[3]); }
	v_mov_b32_e32 v24, v216
	v_mov_b32_e32 v25, v217
	v_mov_b32_e32 v26, v218
	v_mov_b32_e32 v27, v219
	v_pk_mul_f32 v[0:1], v[0:1], v[24:25]
	v_pk_mul_f32 v[2:3], v[2:3], v[26:27]
	v_pk_add_f32 v[30:31], v[30:31], 1.0 op_sel_hi:[1,0]
	s_nop 0
	v_div_scale_f32 v39, s[0:1], v31, v31, v28
	v_rcp_f32_e32 v40, v39
	s_nop 0
	v_fma_f32 v41, -v39, v40, 1.0
	v_fmac_f32_e32 v40, v41, v40
	v_div_scale_f32 v41, vcc, v28, v31, v28
	v_mul_f32_e32 v42, v41, v40
	v_fma_f32 v43, -v39, v42, v41
	v_fmac_f32_e32 v42, v43, v40
	v_fma_f32 v39, -v39, v42, v41
	v_div_fmas_f32 v39, v39, v40, v42
	v_div_fixup_f32 v31, v39, v31, v28
	v_div_scale_f32 v28, s[0:1], v30, v30, v38
	v_rcp_f32_e32 v39, v28
	s_nop 0
	v_fma_f32 v40, -v28, v39, 1.0
	v_fmac_f32_e32 v39, v40, v39
	v_div_scale_f32 v40, vcc, v38, v30, v38
	v_mul_f32_e32 v41, v40, v39
	v_fma_f32 v42, -v28, v41, v40
	v_fmac_f32_e32 v41, v42, v39
	v_fma_f32 v28, -v28, v41, v40
	v_div_fmas_f32 v28, v28, v39, v41
	v_div_fixup_f32 v30, v28, v30, v38
	v_lshlrev_b32_e32 v28, 16, v29
	v_and_b32_e32 v29, 0xffff0000, v29
	v_mul_f32_e32 v24, 0xbfb8aa3b, v28
	v_mul_f32_e32 v25, 0xbfb8aa3b, v29
	v_exp_f32_e32 v24, v24
	v_exp_f32_e32 v25, v25
	v_pk_mul_f32 v[0:1], v[0:1], v[30:31]
	v_pk_add_f32 v[24:25], v[24:25], 1.0 op_sel_hi:[1,0]
	s_nop 0
	v_div_scale_f32 v30, s[0:1], v25, v25, v29
	v_rcp_f32_e32 v31, v30
	v_cvt_pk_bf16_f32 v0, v0, v1
	v_fma_f32 v38, -v30, v31, 1.0
	v_fmac_f32_e32 v31, v38, v31
	v_div_scale_f32 v38, vcc, v29, v25, v29
	v_mul_f32_e32 v39, v38, v31
	v_fma_f32 v40, -v30, v39, v38
	v_fmac_f32_e32 v39, v40, v31
	v_fma_f32 v30, -v30, v39, v38
	v_div_fmas_f32 v30, v30, v31, v39
	v_div_fixup_f32 v25, v30, v25, v29
	v_div_scale_f32 v29, s[0:1], v24, v24, v28
	v_rcp_f32_e32 v30, v29
	s_nop 0
	v_fma_f32 v31, -v29, v30, 1.0
	v_fmac_f32_e32 v30, v31, v30
	v_div_scale_f32 v31, vcc, v28, v24, v28
	v_mul_f32_e32 v38, v31, v30
	v_fma_f32 v39, -v29, v38, v31
	v_fmac_f32_e32 v38, v39, v30
	v_fma_f32 v29, -v29, v38, v31
	v_div_fmas_f32 v29, v29, v30, v38
	v_div_fixup_f32 v24, v29, v24, v28
	v_pk_mul_f32 v[2:3], v[2:3], v[24:25]
	s_nop 0
	v_cvt_pk_bf16_f32 v1, v2, v3
	s_waitcnt vmcnt(5)
	v_mov_b32_e32 v2, v164
	v_mov_b32_e32 v3, v165
	s_nop 0
	s_nop 0
	v_lshlrev_b32_e32 v30, 16, v2
	v_and_b32_e32 v2, 0xffff0000, v2
	v_mul_f32_e32 v28, 0xbfb8aa3b, v30
	v_mul_f32_e32 v29, 0xbfb8aa3b, v2
	v_exp_f32_e32 v28, v28
	v_exp_f32_e32 v29, v29
	s_waitcnt vmcnt(4)
	v_mov_b32_e32 v24, v220
	v_mov_b32_e32 v25, v221
	v_mov_b32_e32 v26, v222
	v_mov_b32_e32 v27, v223
	v_pk_mul_f32 v[4:5], v[4:5], v[24:25]
	v_lshlrev_b32_e32 v24, 16, v3
	v_and_b32_e32 v25, 0xffff0000, v3
	v_pk_add_f32 v[28:29], v[28:29], 1.0 op_sel_hi:[1,0]
	v_mul_f32_e32 v3, 0xbfb8aa3b, v25
	v_div_scale_f32 v31, s[0:1], v29, v29, v2
	v_rcp_f32_e32 v38, v31
	v_exp_f32_e32 v3, v3
	v_pk_mul_f32 v[6:7], v[6:7], v[26:27]
	v_fma_f32 v39, -v31, v38, 1.0
	v_fmac_f32_e32 v38, v39, v38
	v_div_scale_f32 v39, vcc, v2, v29, v2
	v_mul_f32_e32 v40, v39, v38
	v_fma_f32 v41, -v31, v40, v39
	v_fmac_f32_e32 v40, v41, v38
	v_fma_f32 v31, -v31, v40, v39
	v_div_fmas_f32 v31, v31, v38, v40
	v_div_fixup_f32 v29, v31, v29, v2
	v_div_scale_f32 v2, s[0:1], v28, v28, v30
	v_rcp_f32_e32 v31, v2
	s_nop 0
	v_fma_f32 v38, -v2, v31, 1.0
	v_fmac_f32_e32 v31, v38, v31
	v_div_scale_f32 v38, vcc, v30, v28, v30
	v_mul_f32_e32 v39, v38, v31
	v_fma_f32 v40, -v2, v39, v38
	v_fmac_f32_e32 v39, v40, v31
	v_fma_f32 v2, -v2, v39, v38
	v_div_fmas_f32 v2, v2, v31, v39
	v_div_fixup_f32 v28, v2, v28, v30
	v_mul_f32_e32 v2, 0xbfb8aa3b, v24
	v_exp_f32_e32 v2, v2
	v_pk_mul_f32 v[4:5], v[4:5], v[28:29]
	v_pk_add_f32 v[2:3], v[2:3], 1.0 op_sel_hi:[1,0]
	s_nop 0
	v_div_scale_f32 v28, s[0:1], v3, v3, v25
	v_rcp_f32_e32 v29, v28
	s_nop 0
	v_fma_f32 v30, -v28, v29, 1.0
	v_fmac_f32_e32 v29, v30, v29
	v_div_scale_f32 v30, vcc, v25, v3, v25
	v_mul_f32_e32 v31, v30, v29
	v_fma_f32 v38, -v28, v31, v30
	v_fmac_f32_e32 v31, v38, v29
	v_fma_f32 v28, -v28, v31, v30
	v_div_fmas_f32 v28, v28, v29, v31
	v_div_fixup_f32 v3, v28, v3, v25
	v_div_scale_f32 v25, s[0:1], v2, v2, v24
	v_rcp_f32_e32 v28, v25
	s_nop 0
	v_fma_f32 v29, -v25, v28, 1.0
	v_fmac_f32_e32 v28, v29, v28
	v_div_scale_f32 v29, vcc, v24, v2, v24
	v_mul_f32_e32 v30, v29, v28
	v_fma_f32 v31, -v25, v30, v29
	v_fmac_f32_e32 v30, v31, v28
	v_fma_f32 v25, -v25, v30, v29
	v_div_fmas_f32 v25, v25, v28, v30
	v_div_fixup_f32 v2, v25, v2, v24
	v_pk_mul_f32 v[6:7], v[6:7], v[2:3]
	v_cvt_pk_bf16_f32 v2, v4, v5
	v_cvt_pk_bf16_f32 v3, v6, v7
	s_waitcnt vmcnt(3)
	v_mov_b32_e32 v24, v166
	v_mov_b32_e32 v25, v167
	s_nop 0
	v_permlane32_swap_b32_e32 v0, v2
	v_permlane32_swap_b32_e32 v1, v3
	s_nop 0
	v_lshlrev_b32_e32 v28, 16, v24
	v_and_b32_e32 v24, 0xffff0000, v24
	v_mul_f32_e32 v26, 0xbfb8aa3b, v28
	v_mul_f32_e32 v27, 0xbfb8aa3b, v24
	v_exp_f32_e32 v26, v26
	v_exp_f32_e32 v27, v27
	s_waitcnt vmcnt(2)
; DI unsigned pk2(float lo, float hi) { f32x2 v = {lo, hi}; bf2_t r = __builtin_convertvector(v, bf2_t); return __builtin_bit_cast(unsigned, r); }
; DI float bflo(unsigned u) { return __uint_as_float(u << 16); }
; DI float bfhi(unsigned u) { return __uint_as_float(u & 0xffff0000u); }
; DI void gla_out_item(const KP& P, int layer, int b, int tb, LAS unsigned char* lds) {
;     ...
;         for (int g4 = 0; g4 < 4; ++g4) { const int dv = 32 * nt + 8 * g4 + 4 * h;
;             const u32x2 rv = ldg8(Z + (R0 + t) * ZW + C_RC + hd * 64 + dv); const f32x4 gg = *(const f32x4*)(P.g_gla_out + layer * 64 + dv);
;             const float rr[4] = {bflo(rv.x), bfhi(rv.x), bflo(rv.y), bfhi(rv.y)}; float y[4];
; #pragma unroll
;             for (int e = 0; e < 4; ++e) { const float sl = rr[e] / (1.f + __expf(-rr[e])); y[e] = accO[nt][4 * g4 + e] * rstd * gg[e] * sl; }
;             og[4 * nt + g4].x = pk2(y[0], y[1]); og[4 * nt + g4].y = pk2(y[2], y[3]); }
;     store_row8(O + (R0 + t) * D + 512 + hd * 64, og, h);
;     __syncthreads();
	v_mov_b32_e32 v4, v224
	v_mov_b32_e32 v5, v225
	v_mov_b32_e32 v6, v226
	v_mov_b32_e32 v7, v227
	v_pk_mul_f32 v[4:5], v[8:9], v[4:5]
	v_pk_mul_f32 v[6:7], v[10:11], v[6:7]
	v_pk_add_f32 v[26:27], v[26:27], 1.0 op_sel_hi:[1,0]
	s_nop 0
	v_div_scale_f32 v29, s[0:1], v27, v27, v24
	v_rcp_f32_e32 v30, v29
	s_nop 0
	v_fma_f32 v31, -v29, v30, 1.0
	v_fmac_f32_e32 v30, v31, v30
	v_div_scale_f32 v31, vcc, v24, v27, v24
	v_mul_f32_e32 v38, v31, v30
	v_fma_f32 v39, -v29, v38, v31
	v_fmac_f32_e32 v38, v39, v30
	v_fma_f32 v29, -v29, v38, v31
	v_div_fmas_f32 v29, v29, v30, v38
	v_div_fixup_f32 v27, v29, v27, v24
	v_div_scale_f32 v24, s[0:1], v26, v26, v28
	v_rcp_f32_e32 v29, v24
	s_nop 0
	v_fma_f32 v30, -v24, v29, 1.0
	v_fmac_f32_e32 v29, v30, v29
	v_div_scale_f32 v30, vcc, v28, v26, v28
	v_mul_f32_e32 v31, v30, v29
	v_fma_f32 v38, -v24, v31, v30
	v_fmac_f32_e32 v31, v38, v29
	v_fma_f32 v24, -v24, v31, v30
	v_div_fmas_f32 v24, v24, v29, v31
	v_div_fixup_f32 v26, v24, v26, v28
	v_lshlrev_b32_e32 v24, 16, v25
	v_and_b32_e32 v25, 0xffff0000, v25
	v_mul_f32_e32 v8, 0xbfb8aa3b, v24
	v_mul_f32_e32 v9, 0xbfb8aa3b, v25
	v_exp_f32_e32 v8, v8
	v_exp_f32_e32 v9, v9
	v_pk_mul_f32 v[4:5], v[4:5], v[26:27]
	v_pk_add_f32 v[8:9], v[8:9], 1.0 op_sel_hi:[1,0]
	s_nop 0
	v_div_scale_f32 v26, s[0:1], v9, v9, v25
	v_rcp_f32_e32 v27, v26
	v_cvt_pk_bf16_f32 v4, v4, v5
	v_fma_f32 v28, -v26, v27, 1.0
	v_fmac_f32_e32 v27, v28, v27
	v_div_scale_f32 v28, vcc, v25, v9, v25
	v_mul_f32_e32 v29, v28, v27
	v_fma_f32 v30, -v26, v29, v28
	v_fmac_f32_e32 v29, v30, v27
	v_fma_f32 v26, -v26, v29, v28
	v_div_fmas_f32 v26, v26, v27, v29
	v_div_fixup_f32 v9, v26, v9, v25
	v_div_scale_f32 v25, s[0:1], v8, v8, v24
	v_rcp_f32_e32 v26, v25
	s_nop 0
	v_fma_f32 v27, -v25, v26, 1.0
	v_fmac_f32_e32 v26, v27, v26
	v_div_scale_f32 v27, vcc, v24, v8, v24
	v_mul_f32_e32 v28, v27, v26
	v_fma_f32 v29, -v25, v28, v27
	v_fmac_f32_e32 v28, v29, v26
	v_fma_f32 v25, -v25, v28, v27
	v_div_fmas_f32 v25, v25, v26, v28
	v_div_fixup_f32 v8, v25, v8, v24
	v_pk_mul_f32 v[6:7], v[6:7], v[8:9]
	s_nop 0
	v_cvt_pk_bf16_f32 v5, v6, v7
	s_waitcnt vmcnt(1)
	v_mov_b32_e32 v10, v168
	v_mov_b32_e32 v11, v169
	s_nop 0
	s_nop 0
	v_lshlrev_b32_e32 v26, 16, v10
	v_and_b32_e32 v10, 0xffff0000, v10
	v_mul_f32_e32 v24, 0xbfb8aa3b, v26
	v_mul_f32_e32 v25, 0xbfb8aa3b, v10
	v_exp_f32_e32 v24, v24
	v_exp_f32_e32 v25, v25
	s_waitcnt vmcnt(0)
	v_mov_b32_e32 v6, v228
	v_mov_b32_e32 v7, v229
	v_mov_b32_e32 v8, v230
	v_mov_b32_e32 v9, v231
	v_pk_mul_f32 v[6:7], v[12:13], v[6:7]
	v_lshlrev_b32_e32 v12, 16, v11
	v_and_b32_e32 v13, 0xffff0000, v11
	v_pk_add_f32 v[24:25], v[24:25], 1.0 op_sel_hi:[1,0]
	v_mul_f32_e32 v11, 0xbfb8aa3b, v13
	v_div_scale_f32 v27, s[0:1], v25, v25, v10
	v_rcp_f32_e32 v28, v27
	v_exp_f32_e32 v11, v11
	v_fma_f32 v29, -v27, v28, 1.0
	v_fmac_f32_e32 v28, v29, v28
	v_div_scale_f32 v29, vcc, v10, v25, v10
	v_mul_f32_e32 v30, v29, v28
	v_fma_f32 v31, -v27, v30, v29
	v_fmac_f32_e32 v30, v31, v28
	v_fma_f32 v27, -v27, v30, v29
	v_div_fmas_f32 v27, v27, v28, v30
	v_div_fixup_f32 v25, v27, v25, v10
	v_div_scale_f32 v10, s[0:1], v24, v24, v26
	v_rcp_f32_e32 v27, v10
	s_nop 0
	v_fma_f32 v28, -v10, v27, 1.0
	v_fmac_f32_e32 v27, v28, v27
	v_div_scale_f32 v28, vcc, v26, v24, v26
	v_mul_f32_e32 v29, v28, v27
	v_fma_f32 v30, -v10, v29, v28
	v_fmac_f32_e32 v29, v30, v27
	v_fma_f32 v10, -v10, v29, v28
	v_div_fmas_f32 v10, v10, v27, v29
	v_div_fixup_f32 v24, v10, v24, v26
	v_mul_f32_e32 v10, 0xbfb8aa3b, v12
	v_exp_f32_e32 v10, v10
	v_pk_mul_f32 v[6:7], v[6:7], v[24:25]
	v_pk_add_f32 v[10:11], v[10:11], 1.0 op_sel_hi:[1,0]
	s_nop 0
	v_div_scale_f32 v24, s[0:1], v11, v11, v13
	v_rcp_f32_e32 v25, v24
	v_cvt_pk_bf16_f32 v6, v6, v7
	s_nop 1
	v_permlane32_swap_b32_e32 v4, v6
	v_fma_f32 v26, -v24, v25, 1.0
	v_fmac_f32_e32 v25, v26, v25
	v_div_scale_f32 v26, vcc, v13, v11, v13
	v_mul_f32_e32 v27, v26, v25
	v_fma_f32 v28, -v24, v27, v26
	v_fmac_f32_e32 v27, v28, v25
	v_fma_f32 v24, -v24, v27, v26
	v_div_fmas_f32 v24, v24, v25, v27
	v_div_fixup_f32 v11, v24, v11, v13
	v_div_scale_f32 v13, s[0:1], v10, v10, v12
	v_rcp_f32_e32 v24, v13
	v_readlane_b32 s0, v251, 1
	v_readlane_b32 s1, v251, 2
	v_fma_f32 v25, -v13, v24, 1.0
	v_fmac_f32_e32 v24, v25, v24
	v_div_scale_f32 v25, vcc, v12, v10, v12
	v_mul_f32_e32 v26, v25, v24
	v_fma_f32 v27, -v13, v26, v25
	v_fmac_f32_e32 v26, v27, v24
	v_fma_f32 v13, -v13, v26, v25
	v_div_fmas_f32 v13, v13, v24, v26
	v_div_fixup_f32 v10, v13, v10, v12
	v_pk_mul_f32 v[12:13], v[14:15], v[32:33] op_sel_hi:[1,0]
	s_nop 0
	v_pk_mul_f32 v[8:9], v[12:13], v[8:9]
	s_nop 0
	v_pk_mul_f32 v[8:9], v[8:9], v[10:11]
	s_nop 0
	v_cvt_pk_bf16_f32 v7, v8, v9
	v_lshlrev_b64 v[8:9], 11, v[34:35]
	v_lshl_add_u64 v[8:9], s[0:1], 0, v[8:9]
	v_lshl_add_u64 v[8:9], v[8:9], 0, v[112:113]
	v_lshlrev_b32_e32 v112, 1, v72
	v_lshl_add_u64 v[8:9], v[8:9], 0, v[112:113]
	s_mov_b64 s[0:1], 0x1046c400
	v_lshl_add_u64 v[10:11], v[8:9], 0, s[0:1]
	s_mov_b32 s0, 0x1046c000
	v_add_co_u32_e32 v8, vcc, s0, v8
	v_readlane_b32 s0, v251, 3
	s_add_i32 s21, s21, s0
	v_readlane_b32 s0, v255, 0
	v_addc_co_u32_e32 v9, vcc, 0, v9, vcc
	v_permlane32_swap_b32_e32 v5, v7
	s_cmp_lt_i32 s21, s0
	global_store_dwordx4 v[8:9], v[16:19], off offset:1024
	global_store_dwordx4 v[10:11], v[20:23], off offset:32
	global_store_dwordx4 v[10:11], v[0:3], off offset:64
	global_store_dwordx4 v[10:11], v[4:7], off offset:96
	s_barrier
	s_cbranch_scc1 .LBB0_613

; DI void norm_phase(const KP& P, int layer, int which  , int skip_ctx) {
;     const int tid = otid(P.wv), lane = tid & 63, wave = tid >> 6;
;     const int gw = blockIdx.x * 8 + wave, NGW = gridDim.x * 8;
;     const float* MOD = (const float*)(P.ws + WS_MOD);
;     bf16_t* H = (bf16_t*)(P.ws + WS_H);
;     const float* g = (which == 1 ? P.g_norm1 : P.g_norm2) + layer * D;
;     const int nslab = (layer == 0 && which == 2) ? 4 : (layer == 1 && which == 1) ? 8 : 0;
;     for (int R = gw; R < MROWS; R += NGW) {
;         const int b = R / TT, t = R % TT;
;         if (skip_ctx && t < CTX) continue;
;         const int tl = t < CTX ? 0 : 1 + ((t - CTX) >> 8), rin = t < CTX ? t : ((t - CTX) & 255);
;         const float* src = ((which == 1 && layer == 0) ? xin_tile(P, b, tl) : xst_tile(P, b, tl)) + (size_t)rin * D;
;         const float* mrow = MOD + ((size_t)layer * 9 + (t < CTX ? 8 : b)) * 6144 + (which == 1 ? 0 : 3072);
;         f32x4 v[4]; float ss = 0.f;
; #pragma unroll
;         for (int j = 0; j < 4; ++j) v[j] = *(const f32x4*)(src + 8 * lane + 512 * (j >> 1) + 4 * (j & 1));
;         if (nslab && t < CTX) { const float* sl = (const float*)(P.ws + WS_SLAB) + ((size_t)b * CTX + t) * D + 8 * lane;
;             for (int s = 0; s < nslab; ++s)
; #pragma unroll
;                 for (int j = 0; j < 4; ++j) v[j] = v[j] + *(const f32x4*)(sl + (size_t)s * (NB * CTX) * D + 512 * (j >> 1) + 4 * (j & 1));
;             if (which == 2) { float* dst = xst_tile(P, b, 0) + (size_t)rin * D + 8 * lane;
; #pragma unroll
;                 for (int j = 0; j < 4; ++j) *(f32x4*)(dst + 512 * (j >> 1) + 4 * (j & 1)) = v[j]; } }
; #pragma unroll
;         for (int j = 0; j < 4; ++j) { ss += v[j][0] * v[j][0] + v[j][1] * v[j][1] + v[j][2] * v[j][2] + v[j][3] * v[j][3]; }
; #pragma unroll
;         for (int o = 1; o < 64; o <<= 1) ss += __shfl_xor(ss, o);
;         const float rstd = rsqrtf(ss * (1.f / D) + EPS);
; #pragma unroll
;         for (int jj = 0; jj < 2; ++jj) { u32x4 o;
; #pragma unroll
;             for (int hh = 0; hh < 2; ++hh) { const int j = 2 * jj + hh, col = 8 * lane + 512 * jj + 4 * hh;
;                 const f32x4 gg = *(const f32x4*)(g + col), sh = *(const f32x4*)(mrow + col), sc = *(const f32x4*)(mrow + 1024 + col);
.LBB0_837:
	s_or_b64 exec, exec, s[0:1]
	v_readlane_b32 s0, v251, 4
	s_waitcnt lgkmcnt(0)
	s_barrier
	v_readlane_b32 s78, v251, 61
	v_readlane_b32 s86, v251, 4
	v_readlane_b32 s76, v254, 14
	v_readlane_b32 s77, v254, 15
	v_readlane_b32 s90, v251, 21
	v_readlane_b32 s91, v251, 22
	v_readlane_b32 s74, v251, 56
	v_readlane_b32 s75, v251, 57
	v_readlane_b32 s94, v251, 19
	v_readlane_b32 s95, v251, 20
	v_mbcnt_lo_u32_b32 v114, -1, 0
	v_mbcnt_hi_u32_b32 v114, -1, v114
	s_nop 3
	s_lshr_b32 s87, s86, 6
	s_add_i32 s78, s78, s87
	s_lshr_b32 s81, s78, 8
	s_lshl_b32 s81, s81, 1
	s_lshl_b32 s80, s87, 13
	s_add_i32 s80, s80, 0x12000
	s_lshl_b32 s87, s70, 12
	s_add_u32 s94, s94, s87
	s_addc_u32 s95, s95, 0
	s_mul_i32 s87, s70, 0x36000
	s_add_i32 s87, s87, 0x3000
	s_add_u32 s90, s90, s87
	s_addc_u32 s91, s91, 0
	v_lshlrev_b32_e32 v115, 5, v114
	v_add_u32_e32 v116, 16, v115
	v_add_u32_e32 v117, 0x800, v115
	v_add_u32_e32 v118, 0x810, v115
	v_lshlrev_b32_e32 v121, 4, v114
	v_add_u32_e32 v119, s80, v121
	v_mov_b32_e32 v120, v115
	v_add_u32_e32 v122, s86, v114
	v_and_b32_e32 v122, 0xff, v122
	v_lshlrev_b32_e32 v122, 4, v122
	s_cmpk_ge_u32 s86, 0x100
	s_cbranch_scc1 .Lstage_hi_n2
	global_load_dwordx4 v[152:155], v122, s[94:95]
	s_add_u32 s82, s90, 0x0
	s_addc_u32 s83, s91, 0
	global_load_dwordx4 v[156:159], v122, s[82:83]
	s_add_u32 s82, s90, 0x6000
	s_addc_u32 s83, s91, 0
	global_load_dwordx4 v[160:163], v122, s[82:83]
	s_add_u32 s82, s90, 0xc000
	s_addc_u32 s83, s91, 0
	global_load_dwordx4 v[164:167], v122, s[82:83]
	s_add_u32 s82, s90, 0x12000
	s_addc_u32 s83, s91, 0
	global_load_dwordx4 v[168:171], v122, s[82:83]
	s_add_u32 s82, s90, 0x18000
	s_addc_u32 s83, s91, 0
	global_load_dwordx4 v[172:175], v122, s[82:83]
	s_add_u32 s82, s90, 0x1e000
	s_addc_u32 s83, s91, 0
	global_load_dwordx4 v[176:179], v122, s[82:83]
	s_add_u32 s82, s90, 0x24000
	s_addc_u32 s83, s91, 0
	global_load_dwordx4 v[180:183], v122, s[82:83]
	s_add_u32 s82, s90, 0x2a000
	s_addc_u32 s83, s91, 0
	global_load_dwordx4 v[184:187], v122, s[82:83]
	v_add_u32_e32 v123, 0x8000, v122
	s_waitcnt vmcnt(8)
	ds_write_b128 v122, v[152:155]
	s_waitcnt vmcnt(7)
	ds_write_b128 v122, v[156:159] offset:8192
	s_waitcnt vmcnt(6)
	ds_write_b128 v122, v[160:163] offset:16384
	s_waitcnt vmcnt(5)
	ds_write_b128 v122, v[164:167] offset:24576
	s_waitcnt vmcnt(4)
	ds_write_b128 v123, v[168:171]
	s_waitcnt vmcnt(3)
	ds_write_b128 v123, v[172:175] offset:8192
	s_waitcnt vmcnt(2)
	ds_write_b128 v123, v[176:179] offset:16384
	s_waitcnt vmcnt(1)
	ds_write_b128 v123, v[180:183] offset:24576
	s_waitcnt vmcnt(0)
	ds_write_b128 v123, v[184:187] offset:32768
	s_branch .Lstage_done_n2

; DI void norm_phase(const KP& P, int layer, int which  , int skip_ctx) {
;     ...
;     for (int R = gw; R < MROWS; R += NGW) {
;         const int b = R / TT, t = R % TT;
;         if (skip_ctx && t < CTX) continue;
;         const int tl = t < CTX ? 0 : 1 + ((t - CTX) >> 8), rin = t < CTX ? t : ((t - CTX) & 255);
;         const float* src = ((which == 1 && layer == 0) ? xin_tile(P, b, tl) : xst_tile(P, b, tl)) + (size_t)rin * D;
;         const float* mrow = MOD + ((size_t)layer * 9 + (t < CTX ? 8 : b)) * 6144 + (which == 1 ? 0 : 3072);
;         f32x4 v[4]; float ss = 0.f;
; #pragma unroll
;         for (int j = 0; j < 4; ++j) v[j] = *(const f32x4*)(src + 8 * lane + 512 * (j >> 1) + 4 * (j & 1));
.Lstage_done_n2:
	s_movk_i32 s79, 0
	s_cmp_ge_u32 s79, s81
	s_cselect_b32 s86, 1, 0
	s_add_i32 s86, s86, s79
	s_lshl_b32 s86, s86, 11
	s_add_i32 s89, s78, s86
	s_lshr_b32 s88, s89, 8
	s_mul_i32 s88, s88, 0xf10
	s_lshr_b32 s88, s88, 16
	s_mul_i32 s87, s88, 0x1100
	s_sub_i32 s87, s89, s87
	s_lshl_b32 s86, s88, 12
	s_add_i32 s87, s87, s86
	s_add_i32 s87, s87, 0xffffff00
	s_lshl_b32 s87, s87, 12
	s_add_u32 s82, s74, s87
	s_addc_u32 s83, s75, 0
	s_mov_b32 m0, s80
	s_nop 0
	global_load_lds_dwordx4 v115, s[82:83]
	s_add_i32 m0, s80, 0x400
	s_nop 0
	global_load_lds_dwordx4 v116, s[82:83]
	s_add_i32 m0, s80, 0x800
	s_nop 0
	global_load_lds_dwordx4 v117, s[82:83]
	s_add_i32 m0, s80, 0xc00
	s_nop 0
	global_load_lds_dwordx4 v118, s[82:83]
	s_movk_i32 s79, 1
	s_cmp_ge_u32 s79, s81
	s_cselect_b32 s86, 1, 0
	s_add_i32 s86, s86, s79
	s_lshl_b32 s86, s86, 11
	s_add_i32 s89, s78, s86
	s_lshr_b32 s88, s89, 8
	s_mul_i32 s88, s88, 0xf10
	s_lshr_b32 s88, s88, 16
	s_mul_i32 s87, s88, 0x1100
	s_sub_i32 s87, s89, s87
	s_lshl_b32 s86, s88, 12
	s_add_i32 s87, s87, s86
	s_add_i32 s87, s87, 0xffffff00
	s_lshl_b32 s87, s87, 12
	s_add_u32 s82, s74, s87
	s_addc_u32 s83, s75, 0
	s_add_i32 m0, s80, 0x1000
	s_nop 0
	global_load_lds_dwordx4 v115, s[82:83]
	s_add_i32 m0, s80, 0x1400
	s_nop 0
	global_load_lds_dwordx4 v116, s[82:83]
	s_add_i32 m0, s80, 0x1800
	s_nop 0
	global_load_lds_dwordx4 v117, s[82:83]
	s_add_i32 m0, s80, 0x1c00
	s_nop 0
	global_load_lds_dwordx4 v118, s[82:83]
	v_mbcnt_lo_u32_b32 v0, -1, 0
	v_mbcnt_hi_u32_b32 v0, -1, v0
	s_nop 0
	v_add_u32_e32 v1, s0, v0
	v_ashrrev_i32_e32 v1, 6, v1
	v_readlane_b32 s0, v251, 61
	s_nop 1
	v_add_u32_e32 v36, s0, v1
	v_lshrrev_b32_e32 v1, 8, v36
	v_lshl_add_u32 v36, v1, 12, v36
	s_mov_b32 s0, 0x8800
	v_cmp_gt_i32_e32 vcc, s0, v36
	s_and_saveexec_b64 s[2:3], vcc
	s_cbranch_execz .LBB0_844
	v_readlane_b32 s0, v251, 59
	v_readlane_b32 s1, v251, 60
	s_mov_b32 s5, s1
	v_writelane_b32 v251, s0, 59
	s_lshl_b32 s4, s70, 10
	v_lshlrev_b32_e32 v0, 3, v0
	v_writelane_b32 v251, s1, 60
	s_lshl_b64 s[0:1], s[4:5], 2
	v_readlane_b32 s4, v251, 5
	v_readlane_b32 s5, v251, 6
	v_readlane_b32 s18, v251, 19
	v_and_b32_e32 v38, 0x1f8, v0
	v_readlane_b32 s4, v254, 14
	v_readlane_b32 s19, v251, 20
	s_add_u32 s0, s18, s0
	v_lshlrev_b32_e32 v112, 1, v38
	v_readlane_b32 s5, v254, 15
	s_addc_u32 s1, s19, s1
	v_or_b32_e32 v0, 0x200, v38
	v_lshl_add_u64 v[40:41], s[4:5], 0, v[112:113]
	v_lshlrev_b32_e32 v112, 2, v38
	v_lshl_add_u64 v[42:43], s[0:1], 0, v[112:113]
	s_mov_b64 s[4:5], 0
	v_lshlrev_b32_e32 v44, 2, v0
	v_readlane_b32 s6, v251, 7
	v_readlane_b32 s7, v251, 8
	v_readlane_b32 s8, v251, 9
	v_readlane_b32 s9, v251, 10
	v_readlane_b32 s10, v251, 11
	v_readlane_b32 s11, v251, 12
	v_readlane_b32 s12, v251, 13
	v_readlane_b32 s13, v251, 14
	v_readlane_b32 s14, v251, 15
	v_readlane_b32 s15, v251, 16
	v_readlane_b32 s16, v251, 17
	v_readlane_b32 s17, v251, 18
	s_branch .LBB0_841

; DI void norm_phase(const KP& P, int layer, int which  , int skip_ctx) {
;     ...
;     for (int R = gw; R < MROWS; R += NGW) {
.LBB0_840:
	s_or_b64 exec, exec, s[6:7]
	s_mov_b32 s0, 0x8800
	s_nop 1
	v_add_u32_e32 v36, s0, v36
	s_mov_b32 s0, 0x87ff
	v_cmp_lt_i32_e32 vcc, s0, v36
	s_or_b64 s[4:5], vcc, s[4:5]
	s_andn2_b64 exec, exec, s[4:5]
	s_cbranch_execz .LBB0_844

; DI unsigned pk2(float lo, float hi) { f32x2 v = {lo, hi}; bf2_t r = __builtin_convertvector(v, bf2_t); return __builtin_bit_cast(unsigned, r); }
; DI int otid(int wv) { int l; asm volatile("v_mbcnt_lo_u32_b32 %0, -1, 0\n\tv_mbcnt_hi_u32_b32 %0, -1, %0" : "=v"(l)); return wv * 64 + l; }
; DI void norm_phase(const KP& P, int layer, int which  , int skip_ctx) {
;     ...
;         for (int j = 0; j < 4; ++j) { ss += v[j][0] * v[j][0] + v[j][1] * v[j][1] + v[j][2] * v[j][2] + v[j][3] * v[j][3]; }
; #pragma unroll
;         for (int o = 1; o < 64; o <<= 1) ss += __shfl_xor(ss, o);
;         const float rstd = rsqrtf(ss * (1.f / D) + EPS);
; #pragma unroll
;         for (int jj = 0; jj < 2; ++jj) { u32x4 o;
; #pragma unroll
;             for (int hh = 0; hh < 2; ++hh) { const int j = 2 * jj + hh, col = 8 * lane + 512 * jj + 4 * hh;
;                 const f32x4 gg = *(const f32x4*)(g + col), sh = *(const f32x4*)(mrow + col), sc = *(const f32x4*)(mrow + 1024 + col);
;                 f32x4 y;
; #pragma unroll
;                 for (int e = 0; e < 4; ++e) y[e] = v[j][e] * rstd * gg[e] * (1.f + sc[e]) + sh[e];
;                 if (hh == 0) { o.x = pk2(y[0], y[1]); o.y = pk2(y[2], y[3]); } else { o.z = pk2(y[0], y[1]); o.w = pk2(y[2], y[3]); } }
;             *(u32x4*)(H + (size_t)R * D + 8 * lane + 512 * jj) = o; }
; DI void xcd_barrier(const XcdBarrier& b, int wv) {
;     asm volatile("s_waitcnt vmcnt(0)" ::: "memory");
;     __syncthreads();
;     if (otid(wv) == 0) {
;         unsigned* bar = b.bar;
;         __builtin_amdgcn_s_waitcnt(0);
;         unsigned nloc = b.st[0], nx = b.st[1];
;         if (nloc == 0u) { xcd_barrier_complete(bar, b.x, nloc, nx); b.st[0] = nloc; b.st[1] = nx; }
.Lnodma_n2:
	v_mul_f32_e32 v140, v124, v124
	v_mul_f32_e32 v141, v125, v125
	v_add_f32_e32 v140, v140, v141
	v_mul_f32_e32 v141, v126, v126
	v_add_f32_e32 v140, v141, v140
	v_mul_f32_e32 v141, v127, v127
	v_add_f32_e32 v140, v141, v140
	v_mul_f32_e32 v228, v128, v128
	v_mul_f32_e32 v141, v129, v129
	v_add_f32_e32 v228, v228, v141
	v_mul_f32_e32 v141, v130, v130
	v_add_f32_e32 v228, v141, v228
	v_mul_f32_e32 v141, v131, v131
	v_add_f32_e32 v228, v141, v228
	v_mul_f32_e32 v229, v132, v132
	v_mul_f32_e32 v141, v133, v133
	v_add_f32_e32 v229, v229, v141
	v_mul_f32_e32 v141, v134, v134
	v_add_f32_e32 v229, v141, v229
	v_mul_f32_e32 v141, v135, v135
	v_add_f32_e32 v229, v141, v229
	v_mul_f32_e32 v230, v136, v136
	v_mul_f32_e32 v141, v137, v137
	v_add_f32_e32 v230, v230, v141
	v_mul_f32_e32 v141, v138, v138
	v_add_f32_e32 v230, v141, v230
	v_mul_f32_e32 v141, v139, v139
	v_add_f32_e32 v230, v141, v230
	v_add_f32_e32 v140, v140, v228
	v_add_f32_e32 v140, v229, v140
	v_add_f32_e32 v140, v230, v140
	s_nop 1
	v_add_f32_dpp v141, v140, v140 quad_perm:[1,0,3,2] row_mask:0xf bank_mask:0xf
	s_nop 1
	v_add_f32_dpp v140, v141, v141 quad_perm:[2,3,0,1] row_mask:0xf bank_mask:0xf
	s_nop 1
	v_add_f32_dpp v141, v140, v140 row_half_mirror row_mask:0xf bank_mask:0xf
	s_nop 1
	v_add_f32_dpp v140, v141, v141 row_mirror row_mask:0xf bank_mask:0xf
	s_nop 1
	v_readlane_b32 s92, v140, 0
	v_readlane_b32 s93, v140, 16
	v_readlane_b32 s94, v140, 32
	v_readlane_b32 s95, v140, 48
	s_nop 1
	v_mov_b32_e32 v141, s93
	v_mov_b32_e32 v140, s95
	v_add_f32_e32 v141, s92, v141
	v_add_f32_e32 v140, s94, v140
	v_add_f32_e32 v140, v141, v140
	v_fmamk_f32 v140, v140, 0x3a800000, v143
	s_mov_b32 s86, 0x800000
	v_mul_f32_e32 v141, 0x4b800000, v140
	v_cmp_gt_f32_e32 vcc, s86, v140
	s_nop 1
	v_cndmask_b32_e32 v140, v140, v141, vcc
	v_rsq_f32_e32 v142, v140
	s_nop 0
	v_mul_f32_e32 v141, 0x45800000, v142
	v_cndmask_b32_e32 v142, v142, v141, vcc
	s_waitcnt lgkmcnt(0)
	v_pk_mul_f32 v[124:125], v[124:125], v[142:143] op_sel_hi:[1,0]
	v_pk_mul_f32 v[126:127], v[126:127], v[142:143] op_sel_hi:[1,0]
	v_pk_mul_f32 v[124:125], v[152:153], v[124:125]
	v_pk_mul_f32 v[126:127], v[154:155], v[126:127]
	v_pk_fma_f32 v[124:125], v[168:169], v[124:125], v[204:205]
	v_pk_fma_f32 v[126:127], v[170:171], v[126:127], v[206:207]
	v_pk_mul_f32 v[128:129], v[128:129], v[142:143] op_sel_hi:[1,0]
	v_pk_mul_f32 v[130:131], v[130:131], v[142:143] op_sel_hi:[1,0]
	v_pk_mul_f32 v[128:129], v[156:157], v[128:129]
	v_pk_mul_f32 v[130:131], v[158:159], v[130:131]
	v_pk_fma_f32 v[128:129], v[172:173], v[128:129], v[208:209]
	v_pk_fma_f32 v[130:131], v[174:175], v[130:131], v[210:211]
	v_pk_mul_f32 v[132:133], v[132:133], v[142:143] op_sel_hi:[1,0]
	v_pk_mul_f32 v[134:135], v[134:135], v[142:143] op_sel_hi:[1,0]
	v_pk_mul_f32 v[132:133], v[160:161], v[132:133]
	v_pk_mul_f32 v[134:135], v[162:163], v[134:135]
	v_pk_fma_f32 v[132:133], v[176:177], v[132:133], v[212:213]
	v_pk_fma_f32 v[134:135], v[178:179], v[134:135], v[214:215]
	v_pk_mul_f32 v[136:137], v[136:137], v[142:143] op_sel_hi:[1,0]
	v_pk_mul_f32 v[138:139], v[138:139], v[142:143] op_sel_hi:[1,0]
	v_pk_mul_f32 v[136:137], v[164:165], v[136:137]
	v_pk_mul_f32 v[138:139], v[166:167], v[138:139]
	v_pk_fma_f32 v[136:137], v[180:181], v[136:137], v[216:217]
	v_pk_fma_f32 v[138:139], v[182:183], v[138:139], v[218:219]
	v_cvt_pk_bf16_f32 v220, v124, v125
	v_cvt_pk_bf16_f32 v221, v126, v127
	v_cvt_pk_bf16_f32 v222, v128, v129
	v_cvt_pk_bf16_f32 v223, v130, v131
	v_cvt_pk_bf16_f32 v224, v132, v133
	v_cvt_pk_bf16_f32 v225, v134, v135
	v_cvt_pk_bf16_f32 v226, v136, v137
	v_cvt_pk_bf16_f32 v227, v138, v139
	global_store_dwordx4 v121, v[220:223], s[84:85]
	global_store_dwordx4 v121, v[224:227], s[84:85] offset:1024
	v_xor_b32_e32 v119, 0x1000, v119
	s_xor_b32 s80, s80, 0x1000
	s_add_i32 s79, s79, 1
	s_cmp_lt_u32 s79, 16
	s_cbranch_scc1 .Lrow_n2
	s_waitcnt vmcnt(0)
	v_readlane_b32 s0, v252, 1
	s_barrier
	v_mbcnt_lo_u32_b32 v0, -1, 0
	v_mbcnt_hi_u32_b32 v0, -1, v0
	s_nop 0
	v_cmp_eq_u32_e32 vcc, s0, v0
	s_and_saveexec_b64 s[0:1], vcc
	s_cbranch_execz .LBB0_896
	v_readlane_b32 s2, v254, 38
	s_waitcnt vmcnt(0) expcnt(0) lgkmcnt(0)
	s_nop 0
	v_mov_b32_e32 v0, s2
	ds_read_b32 v2, v0
	v_readlane_b32 s2, v254, 39
	s_waitcnt lgkmcnt(0)
	v_cmp_ne_u32_e32 vcc, 0, v2
	v_mov_b32_e32 v0, s2
	ds_read_b32 v0, v0
	s_cbranch_vccnz .LBB0_860
	s_mov_b32 s8, 1
	s_branch .LBB0_848
